# scan: v of 4 steps in one LDS b128 (loader writes compact v via b32), on top of hand-scheduled scan
# speedup vs baseline: 1.0194x; 1.0194x over previous
; #define LAS __attribute__((address_space(3)))
; __device__ __forceinline__ void rwkv_scan(Frame& F, int wg, unsigned* shw, unsigned wait_target, int wait_blk) {
;     ...
;     auto lstore = [&](const LdRegs& L, int b) {
;         LAS float* rec = buf + (b * RW_TB + lstep) * RW_REC;
;         const u32x4 av = L.a, bv = L.b, kv = L.k, rv = L.r;
;         f32x4 a_0 = {bflo(av.x), bfhi(av.x), bflo(av.y), bfhi(av.y)}, a_1 = {bflo(av.z), bfhi(av.z), bflo(av.w), bfhi(av.w)};
;         f32x4 b_0 = {bflo(bv.x), bfhi(bv.x), bflo(bv.y), bfhi(bv.y)}, b_1 = {bflo(bv.z), bfhi(bv.z), bflo(bv.w), bfhi(bv.w)};
;         f32x4 k_0 = {bflo(kv.x), bfhi(kv.x), bflo(kv.y), bfhi(kv.y)}, k_1 = {bflo(kv.z), bfhi(kv.z), bflo(kv.w), bfhi(kv.w)};
;         f32x4 r_0 = {bflo(rv.x), bfhi(rv.x), bflo(rv.y), bfhi(rv.y)}, r_1 = {bflo(rv.z), bfhi(rv.z), bflo(rv.w), bfhi(rv.w)};
;         *(LAS f32x4*)(rec + 8 * part) = L.w0; *(LAS f32x4*)(rec + 8 * part + 4) = L.w1;
;         *(LAS f32x4*)(rec + 64 + 8 * part) = a_0; *(LAS f32x4*)(rec + 64 + 8 * part + 4) = a_1;
;         *(LAS f32x4*)(rec + 128 + 8 * part) = b_0; *(LAS f32x4*)(rec + 128 + 8 * part + 4) = b_1;
;         *(LAS f32x4*)(rec + 192 + 8 * part) = k_0; *(LAS f32x4*)(rec + 192 + 8 * part + 4) = k_1;
;         *(LAS f32x4*)(rec + 256 + 8 * part) = L.w0 * r_0; *(LAS f32x4*)(rec + 256 + 8 * part + 4) = L.w1 * r_1;
;         if (part < 2) { const u32x4 vv = L.v;
;             const float v8[8] = {bflo(vv.x), bfhi(vv.x), bflo(vv.y), bfhi(vv.y), bflo(vv.z), bfhi(vv.z), bflo(vv.w), bfhi(vv.w)};
; #pragma unroll
;             for (int e = 0; e < 8; ++e) *(LAS f32x4*)(rec + 320 + (8 * part + e) * 4) = (f32x4){v8[e], v8[e] * L.kr, L.br, 0.f}; }
.LBB0_838:
	s_or_b64 exec, exec, s[6:7]
	s_movk_i32 s6, 0x600
	v_mad_i32_i24 v7, v60, s6, 0
	s_waitcnt vmcnt(0)
	v_lshlrev_b32_e32 v4, 16, v16
	v_and_b32_e32 v5, 0xffff0000, v16
	v_lshlrev_b32_e32 v16, 16, v17
	v_and_b32_e32 v17, 0xffff0000, v17
	v_lshlrev_b32_e32 v44, 16, v18
	v_and_b32_e32 v45, 0xffff0000, v18
	v_lshlrev_b32_e32 v18, 16, v19
	v_and_b32_e32 v19, 0xffff0000, v19
	v_add_u32_e32 v46, v7, v195
	v_lshlrev_b32_e32 v32, 16, v28
	v_and_b32_e32 v33, 0xffff0000, v28
	v_lshlrev_b32_e32 v34, 16, v29
	v_and_b32_e32 v35, 0xffff0000, v29
	v_lshlrev_b32_e32 v28, 16, v30
	v_and_b32_e32 v29, 0xffff0000, v30
	v_lshlrev_b32_e32 v30, 16, v31
	v_and_b32_e32 v31, 0xffff0000, v31
	v_lshlrev_b32_e32 v36, 16, v24
	v_and_b32_e32 v37, 0xffff0000, v24
	v_lshlrev_b32_e32 v38, 16, v25
	v_and_b32_e32 v39, 0xffff0000, v25
	v_lshlrev_b32_e32 v24, 16, v26
	v_and_b32_e32 v25, 0xffff0000, v26
	v_lshlrev_b32_e32 v26, 16, v27
	v_and_b32_e32 v27, 0xffff0000, v27
	v_lshlrev_b32_e32 v40, 16, v20
	v_and_b32_e32 v41, 0xffff0000, v20
	v_lshlrev_b32_e32 v42, 16, v21
	v_and_b32_e32 v43, 0xffff0000, v21
	v_lshlrev_b32_e32 v20, 16, v22
	v_and_b32_e32 v21, 0xffff0000, v22
	v_lshlrev_b32_e32 v22, 16, v23
	v_and_b32_e32 v23, 0xffff0000, v23
	ds_write_b128 v46, v[12:15]
	ds_write_b128 v46, v[8:11] offset:16
	ds_write_b128 v46, v[32:35] offset:256
	ds_write_b128 v46, v[28:31] offset:272
	ds_write_b128 v46, v[36:39] offset:512
	ds_write_b128 v46, v[24:27] offset:528
	ds_write_b128 v46, v[40:43] offset:768
	ds_write_b128 v46, v[20:23] offset:784
	v_mov_b64_e32 v[14:15], v[16:17]
	v_mov_b64_e32 v[12:13], v[4:5]
	v_mov_b64_e32 v[10:11], v[18:19]
	v_mov_b64_e32 v[8:9], v[44:45]
	ds_write_b128 v46, v[12:15] offset:1024
	ds_write_b128 v46, v[8:11] offset:1040
	s_and_saveexec_b64 s[6:7], s[4:5]
	s_cbranch_execz .LBB0_840
	v_and_b32_e32 v100, 3, v60
	v_mul_u32_u24_e32 v100, 0x5fc, v100
	v_lshl_add_u32 v101, v63, 7, v7
	v_sub_u32_e32 v101, v101, v100
	v_lshlrev_b32_e32 v104, 16, v0
	v_and_b32_e32 v105, 0xffff0000, v0
	v_lshlrev_b32_e32 v106, 16, v1
	v_and_b32_e32 v107, 0xffff0000, v1
	v_lshlrev_b32_e32 v108, 16, v2
	v_and_b32_e32 v109, 0xffff0000, v2
	v_lshlrev_b32_e32 v110, 16, v3
	v_and_b32_e32 v111, 0xffff0000, v3
	ds_write_b32 v101, v104 offset:1280
	ds_write_b32 v101, v105 offset:1296
	ds_write_b32 v101, v106 offset:1312
	ds_write_b32 v101, v107 offset:1328
	ds_write_b32 v101, v108 offset:1344
	ds_write_b32 v101, v109 offset:1360
	ds_write_b32 v101, v110 offset:1376
	ds_write_b32 v101, v111 offset:1392

; #define LAS __attribute__((address_space(3)))
; __device__ __forceinline__ void rwkv_scan(Frame& F, int wg, unsigned* shw, unsigned wait_target, int wait_blk) {
;     ...
;     auto lstore = [&](const LdRegs& L, int b) {
;         LAS float* rec = buf + (b * RW_TB + lstep) * RW_REC;
;         const u32x4 av = L.a, bv = L.b, kv = L.k, rv = L.r;
;         f32x4 a_0 = {bflo(av.x), bfhi(av.x), bflo(av.y), bfhi(av.y)}, a_1 = {bflo(av.z), bfhi(av.z), bflo(av.w), bfhi(av.w)};
;         f32x4 b_0 = {bflo(bv.x), bfhi(bv.x), bflo(bv.y), bfhi(bv.y)}, b_1 = {bflo(bv.z), bfhi(bv.z), bflo(bv.w), bfhi(bv.w)};
;         f32x4 k_0 = {bflo(kv.x), bfhi(kv.x), bflo(kv.y), bfhi(kv.y)}, k_1 = {bflo(kv.z), bfhi(kv.z), bflo(kv.w), bfhi(kv.w)};
;         f32x4 r_0 = {bflo(rv.x), bfhi(rv.x), bflo(rv.y), bfhi(rv.y)}, r_1 = {bflo(rv.z), bfhi(rv.z), bflo(rv.w), bfhi(rv.w)};
;         *(LAS f32x4*)(rec + 8 * part) = L.w0; *(LAS f32x4*)(rec + 8 * part + 4) = L.w1;
;         *(LAS f32x4*)(rec + 64 + 8 * part) = a_0; *(LAS f32x4*)(rec + 64 + 8 * part + 4) = a_1;
;         *(LAS f32x4*)(rec + 128 + 8 * part) = b_0; *(LAS f32x4*)(rec + 128 + 8 * part + 4) = b_1;
;         *(LAS f32x4*)(rec + 192 + 8 * part) = k_0; *(LAS f32x4*)(rec + 192 + 8 * part + 4) = k_1;
;         *(LAS f32x4*)(rec + 256 + 8 * part) = L.w0 * r_0; *(LAS f32x4*)(rec + 256 + 8 * part + 4) = L.w1 * r_1;
;         if (part < 2) { const u32x4 vv = L.v;
;             const float v8[8] = {bflo(vv.x), bfhi(vv.x), bflo(vv.y), bfhi(vv.y), bflo(vv.z), bfhi(vv.z), bflo(vv.w), bfhi(vv.w)};
; #pragma unroll
;             for (int e = 0; e < 8; ++e) *(LAS f32x4*)(rec + 320 + (8 * part + e) * 4) = (f32x4){v8[e], v8[e] * L.kr, L.br, 0.f}; }
.LBB0_850:
	s_and_b64 vcc, exec, s[50:51]
	s_cbranch_vccz .LBB0_890
	s_waitcnt vmcnt(3)
	v_lshlrev_b32_e32 v72, 16, v16
	v_and_b32_e32 v73, 0xffff0000, v16
	v_lshlrev_b32_e32 v74, 16, v17
	v_and_b32_e32 v75, 0xffff0000, v17
	s_waitcnt vmcnt(0)
	v_lshlrev_b32_e32 v4, 16, v28
	v_and_b32_e32 v5, 0xffff0000, v28
	v_lshlrev_b32_e32 v60, 16, v29
	v_and_b32_e32 v61, 0xffff0000, v29
	v_add_u32_e32 v7, v199, v195
	v_lshlrev_b32_e32 v76, 16, v18
	v_and_b32_e32 v77, 0xffff0000, v18
	v_lshlrev_b32_e32 v78, 16, v19
	v_and_b32_e32 v79, 0xffff0000, v19
	v_lshlrev_b32_e32 v80, 16, v20
	v_and_b32_e32 v81, 0xffff0000, v20
	v_lshlrev_b32_e32 v82, 16, v21
	v_and_b32_e32 v83, 0xffff0000, v21
	v_lshlrev_b32_e32 v84, 16, v22
	v_and_b32_e32 v85, 0xffff0000, v22
	v_lshlrev_b32_e32 v86, 16, v23
	v_and_b32_e32 v87, 0xffff0000, v23
	v_lshlrev_b32_e32 v88, 16, v24
	v_and_b32_e32 v89, 0xffff0000, v24
	v_lshlrev_b32_e32 v90, 16, v25
	v_and_b32_e32 v91, 0xffff0000, v25
	v_lshlrev_b32_e32 v92, 16, v26
	v_and_b32_e32 v93, 0xffff0000, v26
	v_lshlrev_b32_e32 v94, 16, v27
	v_and_b32_e32 v95, 0xffff0000, v27
	v_lshlrev_b32_e32 v64, 16, v30
	v_and_b32_e32 v65, 0xffff0000, v30
	v_lshlrev_b32_e32 v96, 16, v31
	v_and_b32_e32 v97, 0xffff0000, v31
	ds_write_b128 v7, v[12:15] offset:49152
	ds_write_b128 v7, v[8:11] offset:49168
	ds_write_b128 v7, v[72:75] offset:49408
	ds_write_b128 v7, v[76:79] offset:49424
	ds_write_b128 v7, v[80:83] offset:49664
	ds_write_b128 v7, v[84:87] offset:49680
	ds_write_b128 v7, v[88:91] offset:49920
	ds_write_b128 v7, v[92:95] offset:49936
	v_mov_b64_e32 v[74:75], v[60:61]
	v_mov_b64_e32 v[72:73], v[4:5]
	ds_write_b128 v7, v[72:75] offset:50176
	v_mov_b64_e32 v[74:75], v[96:97]
	v_mov_b64_e32 v[72:73], v[64:65]
	ds_write_b128 v7, v[72:75] offset:50192
	s_and_saveexec_b64 s[50:51], s[10:11]
	s_cbranch_execz .LBB0_853
	v_and_b32_e32 v100, 3, v201
	v_mul_u32_u24_e32 v100, 0x5fc, v100
	v_add_u32_e32 v101, v199, v200
	v_sub_u32_e32 v101, v101, v100
	v_lshlrev_b32_e32 v104, 16, v0
	v_and_b32_e32 v105, 0xffff0000, v0
	v_lshlrev_b32_e32 v106, 16, v1
	v_and_b32_e32 v107, 0xffff0000, v1
	v_lshlrev_b32_e32 v108, 16, v2
	v_and_b32_e32 v109, 0xffff0000, v2
	v_lshlrev_b32_e32 v110, 16, v3
	v_and_b32_e32 v111, 0xffff0000, v3
	ds_write_b32 v101, v104 offset:50432
	ds_write_b32 v101, v105 offset:50448
	ds_write_b32 v101, v106 offset:50464
	ds_write_b32 v101, v107 offset:50480
	ds_write_b32 v101, v108 offset:50496
	ds_write_b32 v101, v109 offset:50512
	ds_write_b32 v101, v110 offset:50528
	ds_write_b32 v101, v111 offset:50544

; __device__ __forceinline__ void rwkv_scan(Frame& F, int wg, unsigned* shw, unsigned wait_target, int wait_blk) {
;     ...
;             RwOps R[4];
;             RW_LD(R[0], 0); RW_LD(R[1], 1); RW_LD(R[2], 2);
;             for (int s4 = 0; s4 < RW_TB; s4 += 4) {
;                 float pz[4], u[4];
; #pragma unroll
;                 for (int q = 0; q < 4; ++q) {
;                     RW_LD(R[(q + 3) & 3], s4 + q + 3);
;                     const RwOps& cur = R[q];
;                     const f32x2 slo = {st.x, st.y}, shi = {st.z, st.w};
;                     f32x2 ma = slo * (f32x2){cur.a.x, cur.a.y}; ma = __builtin_elementwise_fma(shi, (f32x2){cur.a.z, cur.a.w}, ma);
;                     f32x2 mz = slo * (f32x2){cur.wr.x, cur.wr.y}; mz = __builtin_elementwise_fma(shi, (f32x2){cur.wr.z, cur.wr.w}, mz);
;                     float psa = ma.x + ma.y; pz[q] = mz.x + mz.y;
;                     const f32x2 vb = {cur.vs.x, cur.vs.x};
;                     f32x2 tlo = (f32x2){cur.k.x, cur.k.y} * vb, thi = (f32x2){cur.k.z, cur.k.w} * vb;
;                     tlo = __builtin_elementwise_fma(slo, (f32x2){cur.w.x, cur.w.y}, tlo); thi = __builtin_elementwise_fma(shi, (f32x2){cur.w.z, cur.w.w}, thi);
;                     psa = red16(psa);
;                     const f32x2 pb = {psa, psa};
;                     tlo = __builtin_elementwise_fma((f32x2){cur.b.x, cur.b.y}, pb, tlo); thi = __builtin_elementwise_fma((f32x2){cur.b.z, cur.b.w}, pb, thi);
;                     st = (f32x4){tlo.x, tlo.y, thi.x, thi.y};
;                     u[q] = psa * cur.vs.z + cur.vs.y;
;                 }
;                 const float qa = (odd1 ? pz[1] : pz[0]) + dppf<0xB1>(odd1 ? pz[0] : pz[1]);
;                 const float qb = (odd1 ? pz[3] : pz[2]) + dppf<0xB1>(odd1 ? pz[2] : pz[3]);
;                 float r = (odd2 ? qb : qa) + dppf<0x4E>(odd2 ? qa : qb);
;                 r += dppf<0x124>(r); r += dppf<0x128>(r);
;                 const float us = odd2 ? (odd1 ? u[3] : u[2]) : (odd1 ? u[1] : u[0]);
;                 if (j < 4) { const int t = blk * RW_TB + s4 + j; ((float*)(Ub + (size_t)t * (PWP * 2) + URR * 2))[h * 64 + row] = r + us; }
.LBB0_873:
	s_mul_i32 s50, s59, 0x58000
	ds_read_b128 v[80:83], v198 offset:256
	ds_read_b128 v[88:91], v198 offset:768
	ds_read_b128 v[124:127], v204 offset:1280
	ds_read_b128 v[76:79], v198 offset:0
	ds_read_b128 v[84:87], v198 offset:512
	ds_read_b128 v[132:135], v198 offset:1024
	ds_read_b128 v[96:99], v198 offset:1792
	ds_read_b128 v[104:107], v198 offset:2304
	ds_read_b128 v[92:95], v198 offset:1536
	ds_read_b128 v[100:103], v198 offset:2048
	ds_read_b128 v[136:139], v198 offset:2560
	v_lshrrev_b32_e32 v165, 2, v194
	v_mul_u32_u24_e32 v165, 0x2c00, v165
	v_lshl_add_u32 v165, v186, 2, v165
	v_add_u32_e32 v165, s50, v165
	s_waitcnt lgkmcnt(5)
	v_pk_mul_f32 v[148:149], v[68:69], v[80:81]
	v_pk_fma_f32 v[148:149], v[70:71], v[82:83], v[148:149]
	v_add_f32_e32 v150, v148, v149
	v_pk_mul_f32 v[152:153], v[88:89], v[124:125] op_sel_hi:[1,0]
	v_pk_mul_f32 v[154:155], v[90:91], v[124:125] op_sel_hi:[1,0]
	v_add_f32_dpp v150, v150, v150 quad_perm:[1,0,3,2] row_mask:0xf bank_mask:0xf bound_ctrl:1
	v_pk_fma_f32 v[152:153], v[68:69], v[76:77], v[152:153]
	v_pk_fma_f32 v[154:155], v[70:71], v[78:79], v[154:155]
	v_add_f32_dpp v150, v150, v150 quad_perm:[2,3,0,1] row_mask:0xf bank_mask:0xf bound_ctrl:1
	ds_read_b128 v[112:115], v198 offset:3328
	ds_read_b128 v[120:123], v198 offset:3840
	v_add_f32_dpp v150, v150, v150 row_half_mirror row_mask:0xf bank_mask:0xf bound_ctrl:1
	ds_read_b128 v[108:111], v198 offset:3072
	ds_read_b128 v[116:119], v198 offset:3584
	v_add_f32_dpp v150, v150, v150 row_mirror row_mask:0xf bank_mask:0xf bound_ctrl:1
	v_pk_fma_f32 v[72:73], v[84:85], v[150:151], v[152:153] op_sel_hi:[1,0,1]
	v_pk_fma_f32 v[74:75], v[86:87], v[150:151], v[154:155] op_sel_hi:[1,0,1]
	ds_read_b128 v[140:143], v198 offset:4096
	s_waitcnt lgkmcnt(5)
	v_pk_mul_f32 v[148:149], v[72:73], v[96:97]
	v_pk_fma_f32 v[148:149], v[74:75], v[98:99], v[148:149]
	v_add_f32_e32 v150, v148, v149
	v_pk_mul_f32 v[152:153], v[104:105], v[124:125] op_sel:[0,1] op_sel_hi:[1,1]
	v_pk_mul_f32 v[154:155], v[106:107], v[124:125] op_sel:[0,1] op_sel_hi:[1,1]
	v_add_f32_dpp v150, v150, v150 quad_perm:[1,0,3,2] row_mask:0xf bank_mask:0xf bound_ctrl:1
	v_pk_fma_f32 v[152:153], v[72:73], v[92:93], v[152:153]
	v_pk_fma_f32 v[154:155], v[74:75], v[94:95], v[154:155]
	v_add_f32_dpp v150, v150, v150 quad_perm:[2,3,0,1] row_mask:0xf bank_mask:0xf bound_ctrl:1
	v_pk_mul_f32 v[156:157], v[72:73], v[132:133]
	v_pk_fma_f32 v[156:157], v[74:75], v[134:135], v[156:157]
	v_add_f32_dpp v150, v150, v150 row_half_mirror row_mask:0xf bank_mask:0xf bound_ctrl:1
	v_add_f32_e32 v158, v156, v157
	ds_read_b128 v[80:83], v198 offset:4864
	v_add_f32_dpp v150, v150, v150 row_mirror row_mask:0xf bank_mask:0xf bound_ctrl:1
	v_pk_fma_f32 v[68:69], v[100:101], v[150:151], v[152:153] op_sel_hi:[1,0,1]
	v_pk_fma_f32 v[70:71], v[102:103], v[150:151], v[154:155] op_sel_hi:[1,0,1]
	ds_read_b128 v[88:91], v198 offset:5376
	ds_read_b128 v[76:79], v198 offset:4608
	ds_read_b128 v[84:87], v198 offset:5120
	ds_read_b128 v[144:147], v198 offset:5632
	s_waitcnt lgkmcnt(5)
	v_pk_mul_f32 v[148:149], v[68:69], v[112:113]
	v_pk_fma_f32 v[148:149], v[70:71], v[114:115], v[148:149]
	v_add_f32_e32 v150, v148, v149
	v_pk_mul_f32 v[152:153], v[120:121], v[126:127] op_sel_hi:[1,0]
	v_pk_mul_f32 v[154:155], v[122:123], v[126:127] op_sel_hi:[1,0]
	v_add_f32_dpp v150, v150, v150 quad_perm:[1,0,3,2] row_mask:0xf bank_mask:0xf bound_ctrl:1
	v_pk_fma_f32 v[152:153], v[68:69], v[108:109], v[152:153]
	v_pk_fma_f32 v[154:155], v[70:71], v[110:111], v[154:155]
	v_add_f32_dpp v150, v150, v150 quad_perm:[2,3,0,1] row_mask:0xf bank_mask:0xf bound_ctrl:1
	v_pk_mul_f32 v[156:157], v[68:69], v[136:137]
	v_pk_fma_f32 v[156:157], v[70:71], v[138:139], v[156:157]
	v_add_f32_dpp v150, v150, v150 row_half_mirror row_mask:0xf bank_mask:0xf bound_ctrl:1
	v_add_f32_e32 v159, v156, v157
	ds_read_b128 v[96:99], v198 offset:6400
	v_add_f32_dpp v150, v150, v150 row_mirror row_mask:0xf bank_mask:0xf bound_ctrl:1
	v_pk_fma_f32 v[72:73], v[116:117], v[150:151], v[152:153] op_sel_hi:[1,0,1]
	v_pk_fma_f32 v[74:75], v[118:119], v[150:151], v[154:155] op_sel_hi:[1,0,1]
	ds_read_b128 v[104:107], v198 offset:6912
	ds_read_b128 v[128:131], v204 offset:7424
	ds_read_b128 v[92:95], v198 offset:6144
	ds_read_b128 v[100:103], v198 offset:6656
	ds_read_b128 v[132:135], v198 offset:7168
	s_waitcnt lgkmcnt(6)
	v_pk_mul_f32 v[148:149], v[72:73], v[80:81]
	v_pk_fma_f32 v[148:149], v[74:75], v[82:83], v[148:149]
	v_add_f32_e32 v150, v148, v149
	v_pk_mul_f32 v[152:153], v[88:89], v[126:127] op_sel:[0,1] op_sel_hi:[1,1]
	v_pk_mul_f32 v[154:155], v[90:91], v[126:127] op_sel:[0,1] op_sel_hi:[1,1]
	v_add_f32_dpp v150, v150, v150 quad_perm:[1,0,3,2] row_mask:0xf bank_mask:0xf bound_ctrl:1
	v_pk_fma_f32 v[152:153], v[72:73], v[76:77], v[152:153]
	v_pk_fma_f32 v[154:155], v[74:75], v[78:79], v[154:155]
	v_add_f32_dpp v150, v150, v150 quad_perm:[2,3,0,1] row_mask:0xf bank_mask:0xf bound_ctrl:1
	v_pk_mul_f32 v[156:157], v[72:73], v[140:141]
	v_pk_fma_f32 v[156:157], v[74:75], v[142:143], v[156:157]
	v_add_f32_dpp v150, v150, v150 row_half_mirror row_mask:0xf bank_mask:0xf bound_ctrl:1
	v_add_f32_e32 v160, v156, v157
	ds_read_b128 v[112:115], v198 offset:7936
	v_add_f32_dpp v150, v150, v150 row_mirror row_mask:0xf bank_mask:0xf bound_ctrl:1
	v_pk_fma_f32 v[68:69], v[84:85], v[150:151], v[152:153] op_sel_hi:[1,0,1]
	v_pk_fma_f32 v[70:71], v[86:87], v[150:151], v[154:155] op_sel_hi:[1,0,1]
	ds_read_b128 v[120:123], v198 offset:8448
	ds_read_b128 v[108:111], v198 offset:7680
	ds_read_b128 v[116:119], v198 offset:8192
	ds_read_b128 v[136:139], v198 offset:8704
	s_waitcnt lgkmcnt(5)
; __device__ __forceinline__ void rwkv_scan(Frame& F, int wg, unsigned* shw, unsigned wait_target, int wait_blk) {
;     ...
;             RwOps R[4];
;             RW_LD(R[0], 0); RW_LD(R[1], 1); RW_LD(R[2], 2);
;             for (int s4 = 0; s4 < RW_TB; s4 += 4) {
;                 float pz[4], u[4];
; #pragma unroll
;                 for (int q = 0; q < 4; ++q) {
;                     RW_LD(R[(q + 3) & 3], s4 + q + 3);
;                     const RwOps& cur = R[q];
;                     const f32x2 slo = {st.x, st.y}, shi = {st.z, st.w};
;                     f32x2 ma = slo * (f32x2){cur.a.x, cur.a.y}; ma = __builtin_elementwise_fma(shi, (f32x2){cur.a.z, cur.a.w}, ma);
;                     f32x2 mz = slo * (f32x2){cur.wr.x, cur.wr.y}; mz = __builtin_elementwise_fma(shi, (f32x2){cur.wr.z, cur.wr.w}, mz);
;                     float psa = ma.x + ma.y; pz[q] = mz.x + mz.y;
;                     const f32x2 vb = {cur.vs.x, cur.vs.x};
;                     f32x2 tlo = (f32x2){cur.k.x, cur.k.y} * vb, thi = (f32x2){cur.k.z, cur.k.w} * vb;
;                     tlo = __builtin_elementwise_fma(slo, (f32x2){cur.w.x, cur.w.y}, tlo); thi = __builtin_elementwise_fma(shi, (f32x2){cur.w.z, cur.w.w}, thi);
;                     psa = red16(psa);
;                     const f32x2 pb = {psa, psa};
;                     tlo = __builtin_elementwise_fma((f32x2){cur.b.x, cur.b.y}, pb, tlo); thi = __builtin_elementwise_fma((f32x2){cur.b.z, cur.b.w}, pb, thi);
;                     st = (f32x4){tlo.x, tlo.y, thi.x, thi.y};
;                     u[q] = psa * cur.vs.z + cur.vs.y;
;                 }
;                 const float qa = (odd1 ? pz[1] : pz[0]) + dppf<0xB1>(odd1 ? pz[0] : pz[1]);
;                 const float qb = (odd1 ? pz[3] : pz[2]) + dppf<0xB1>(odd1 ? pz[2] : pz[3]);
;                 float r = (odd2 ? qb : qa) + dppf<0x4E>(odd2 ? qa : qb);
;                 r += dppf<0x124>(r); r += dppf<0x128>(r);
;                 const float us = odd2 ? (odd1 ? u[3] : u[2]) : (odd1 ? u[1] : u[0]);
;                 if (j < 4) { const int t = blk * RW_TB + s4 + j; ((float*)(Ub + (size_t)t * (PWP * 2) + URR * 2))[h * 64 + row] = r + us; }
	v_pk_mul_f32 v[148:149], v[68:69], v[96:97]
	v_pk_fma_f32 v[148:149], v[70:71], v[98:99], v[148:149]
	v_add_f32_e32 v150, v148, v149
	v_pk_mul_f32 v[152:153], v[104:105], v[128:129] op_sel_hi:[1,0]
	v_pk_mul_f32 v[154:155], v[106:107], v[128:129] op_sel_hi:[1,0]
	v_add_f32_dpp v150, v150, v150 quad_perm:[1,0,3,2] row_mask:0xf bank_mask:0xf bound_ctrl:1
	v_pk_fma_f32 v[152:153], v[68:69], v[92:93], v[152:153]
	v_pk_fma_f32 v[154:155], v[70:71], v[94:95], v[154:155]
	v_add_f32_dpp v150, v150, v150 quad_perm:[2,3,0,1] row_mask:0xf bank_mask:0xf bound_ctrl:1
	v_pk_mul_f32 v[156:157], v[68:69], v[144:145]
	v_pk_fma_f32 v[156:157], v[70:71], v[146:147], v[156:157]
	v_add_f32_dpp v150, v150, v150 row_half_mirror row_mask:0xf bank_mask:0xf bound_ctrl:1
	v_add_f32_e32 v161, v156, v157
	v_add_f32_dpp v162, v158, v158 row_ror:8 row_mask:0xf bank_mask:0xf
	v_add_f32_dpp v150, v150, v150 row_mirror row_mask:0xf bank_mask:0xf bound_ctrl:1
	v_pk_fma_f32 v[72:73], v[100:101], v[150:151], v[152:153] op_sel_hi:[1,0,1]
	v_pk_fma_f32 v[74:75], v[102:103], v[150:151], v[154:155] op_sel_hi:[1,0,1]
	v_add_f32_dpp v163, v159, v159 row_ror:8 row_mask:0xf bank_mask:0xf
	v_add_f32_dpp v162, v160, v160 row_ror:8 row_mask:0xf bank_mask:0xc
	v_add_f32_dpp v163, v161, v161 row_ror:8 row_mask:0xf bank_mask:0xc
	ds_read_b128 v[80:83], v198 offset:9472
	ds_read_b128 v[88:91], v198 offset:9984
	v_add_f32_dpp v164, v162, v162 row_half_mirror row_mask:0xf bank_mask:0xf
	v_add_f32_dpp v164, v163, v163 row_half_mirror row_mask:0xf bank_mask:0xa
	ds_read_b128 v[76:79], v198 offset:9216
	ds_read_b128 v[84:87], v198 offset:9728
	v_add_f32_dpp v164, v164, v164 quad_perm:[1,0,3,2] row_mask:0xf bank_mask:0xf bound_ctrl:1
	ds_read_b128 v[140:143], v198 offset:10240
	s_nop 0
	v_add_f32_dpp v164, v164, v164 quad_perm:[2,3,0,1] row_mask:0xf bank_mask:0xf bound_ctrl:1
	global_store_dword v165, v164, s[34:35]
	v_add_u32_e32 v165, 0xb000, v165
	s_waitcnt lgkmcnt(5)
	v_pk_mul_f32 v[148:149], v[72:73], v[112:113]
	v_pk_fma_f32 v[148:149], v[74:75], v[114:115], v[148:149]
	v_add_f32_e32 v150, v148, v149
	v_pk_mul_f32 v[152:153], v[120:121], v[128:129] op_sel:[0,1] op_sel_hi:[1,1]
	v_pk_mul_f32 v[154:155], v[122:123], v[128:129] op_sel:[0,1] op_sel_hi:[1,1]
	v_add_f32_dpp v150, v150, v150 quad_perm:[1,0,3,2] row_mask:0xf bank_mask:0xf bound_ctrl:1
	v_pk_fma_f32 v[152:153], v[72:73], v[108:109], v[152:153]
	v_pk_fma_f32 v[154:155], v[74:75], v[110:111], v[154:155]
	v_add_f32_dpp v150, v150, v150 quad_perm:[2,3,0,1] row_mask:0xf bank_mask:0xf bound_ctrl:1
	v_pk_mul_f32 v[156:157], v[72:73], v[132:133]
	v_pk_fma_f32 v[156:157], v[74:75], v[134:135], v[156:157]
	v_add_f32_dpp v150, v150, v150 row_half_mirror row_mask:0xf bank_mask:0xf bound_ctrl:1
	v_add_f32_e32 v158, v156, v157
	ds_read_b128 v[96:99], v198 offset:11008
	v_add_f32_dpp v150, v150, v150 row_mirror row_mask:0xf bank_mask:0xf bound_ctrl:1
	v_pk_fma_f32 v[68:69], v[116:117], v[150:151], v[152:153] op_sel_hi:[1,0,1]
	v_pk_fma_f32 v[70:71], v[118:119], v[150:151], v[154:155] op_sel_hi:[1,0,1]
	ds_read_b128 v[104:107], v198 offset:11520
	ds_read_b128 v[92:95], v198 offset:10752
	ds_read_b128 v[100:103], v198 offset:11264
	ds_read_b128 v[144:147], v198 offset:11776
	s_waitcnt lgkmcnt(5)
	v_pk_mul_f32 v[148:149], v[68:69], v[80:81]
	v_pk_fma_f32 v[148:149], v[70:71], v[82:83], v[148:149]
	v_add_f32_e32 v150, v148, v149
	v_pk_mul_f32 v[152:153], v[88:89], v[130:131] op_sel_hi:[1,0]
	v_pk_mul_f32 v[154:155], v[90:91], v[130:131] op_sel_hi:[1,0]
	v_add_f32_dpp v150, v150, v150 quad_perm:[1,0,3,2] row_mask:0xf bank_mask:0xf bound_ctrl:1
	v_pk_fma_f32 v[152:153], v[68:69], v[76:77], v[152:153]
	v_pk_fma_f32 v[154:155], v[70:71], v[78:79], v[154:155]
	v_add_f32_dpp v150, v150, v150 quad_perm:[2,3,0,1] row_mask:0xf bank_mask:0xf bound_ctrl:1
	v_pk_mul_f32 v[156:157], v[68:69], v[136:137]
	v_pk_fma_f32 v[156:157], v[70:71], v[138:139], v[156:157]
	v_add_f32_dpp v150, v150, v150 row_half_mirror row_mask:0xf bank_mask:0xf bound_ctrl:1
	v_add_f32_e32 v159, v156, v157
	ds_read_b128 v[112:115], v198 offset:12544
	v_add_f32_dpp v150, v150, v150 row_mirror row_mask:0xf bank_mask:0xf bound_ctrl:1
	v_pk_fma_f32 v[72:73], v[84:85], v[150:151], v[152:153] op_sel_hi:[1,0,1]
	v_pk_fma_f32 v[74:75], v[86:87], v[150:151], v[154:155] op_sel_hi:[1,0,1]
	ds_read_b128 v[120:123], v198 offset:13056
	ds_read_b128 v[124:127], v204 offset:13568
	ds_read_b128 v[108:111], v198 offset:12288
	ds_read_b128 v[116:119], v198 offset:12800
	ds_read_b128 v[132:135], v198 offset:13312
	s_waitcnt lgkmcnt(6)
	v_pk_mul_f32 v[148:149], v[72:73], v[96:97]
	v_pk_fma_f32 v[148:149], v[74:75], v[98:99], v[148:149]
	v_add_f32_e32 v150, v148, v149
	v_pk_mul_f32 v[152:153], v[104:105], v[130:131] op_sel:[0,1] op_sel_hi:[1,1]
	v_pk_mul_f32 v[154:155], v[106:107], v[130:131] op_sel:[0,1] op_sel_hi:[1,1]
	v_add_f32_dpp v150, v150, v150 quad_perm:[1,0,3,2] row_mask:0xf bank_mask:0xf bound_ctrl:1
	v_pk_fma_f32 v[152:153], v[72:73], v[92:93], v[152:153]
	v_pk_fma_f32 v[154:155], v[74:75], v[94:95], v[154:155]
	v_add_f32_dpp v150, v150, v150 quad_perm:[2,3,0,1] row_mask:0xf bank_mask:0xf bound_ctrl:1
	v_pk_mul_f32 v[156:157], v[72:73], v[140:141]
	v_pk_fma_f32 v[156:157], v[74:75], v[142:143], v[156:157]
	v_add_f32_dpp v150, v150, v150 row_half_mirror row_mask:0xf bank_mask:0xf bound_ctrl:1
	v_add_f32_e32 v160, v156, v157
	ds_read_b128 v[80:83], v198 offset:14080
	v_add_f32_dpp v150, v150, v150 row_mirror row_mask:0xf bank_mask:0xf bound_ctrl:1
	v_pk_fma_f32 v[68:69], v[100:101], v[150:151], v[152:153] op_sel_hi:[1,0,1]
	v_pk_fma_f32 v[70:71], v[102:103], v[150:151], v[154:155] op_sel_hi:[1,0,1]
	ds_read_b128 v[88:91], v198 offset:14592
	ds_read_b128 v[76:79], v198 offset:13824
	ds_read_b128 v[84:87], v198 offset:14336
	ds_read_b128 v[136:139], v198 offset:14848
	s_waitcnt lgkmcnt(5)
; __device__ __forceinline__ void rwkv_scan(Frame& F, int wg, unsigned* shw, unsigned wait_target, int wait_blk) {
;     ...
;             RwOps R[4];
;             RW_LD(R[0], 0); RW_LD(R[1], 1); RW_LD(R[2], 2);
;             for (int s4 = 0; s4 < RW_TB; s4 += 4) {
;                 float pz[4], u[4];
; #pragma unroll
;                 for (int q = 0; q < 4; ++q) {
;                     RW_LD(R[(q + 3) & 3], s4 + q + 3);
;                     const RwOps& cur = R[q];
;                     const f32x2 slo = {st.x, st.y}, shi = {st.z, st.w};
;                     f32x2 ma = slo * (f32x2){cur.a.x, cur.a.y}; ma = __builtin_elementwise_fma(shi, (f32x2){cur.a.z, cur.a.w}, ma);
;                     f32x2 mz = slo * (f32x2){cur.wr.x, cur.wr.y}; mz = __builtin_elementwise_fma(shi, (f32x2){cur.wr.z, cur.wr.w}, mz);
;                     float psa = ma.x + ma.y; pz[q] = mz.x + mz.y;
;                     const f32x2 vb = {cur.vs.x, cur.vs.x};
;                     f32x2 tlo = (f32x2){cur.k.x, cur.k.y} * vb, thi = (f32x2){cur.k.z, cur.k.w} * vb;
;                     tlo = __builtin_elementwise_fma(slo, (f32x2){cur.w.x, cur.w.y}, tlo); thi = __builtin_elementwise_fma(shi, (f32x2){cur.w.z, cur.w.w}, thi);
;                     psa = red16(psa);
;                     const f32x2 pb = {psa, psa};
;                     tlo = __builtin_elementwise_fma((f32x2){cur.b.x, cur.b.y}, pb, tlo); thi = __builtin_elementwise_fma((f32x2){cur.b.z, cur.b.w}, pb, thi);
;                     st = (f32x4){tlo.x, tlo.y, thi.x, thi.y};
;                     u[q] = psa * cur.vs.z + cur.vs.y;
;                 }
;                 const float qa = (odd1 ? pz[1] : pz[0]) + dppf<0xB1>(odd1 ? pz[0] : pz[1]);
;                 const float qb = (odd1 ? pz[3] : pz[2]) + dppf<0xB1>(odd1 ? pz[2] : pz[3]);
;                 float r = (odd2 ? qb : qa) + dppf<0x4E>(odd2 ? qa : qb);
;                 r += dppf<0x124>(r); r += dppf<0x128>(r);
;                 const float us = odd2 ? (odd1 ? u[3] : u[2]) : (odd1 ? u[1] : u[0]);
;                 if (j < 4) { const int t = blk * RW_TB + s4 + j; ((float*)(Ub + (size_t)t * (PWP * 2) + URR * 2))[h * 64 + row] = r + us; }
	v_pk_mul_f32 v[148:149], v[68:69], v[112:113]
	v_pk_fma_f32 v[148:149], v[70:71], v[114:115], v[148:149]
	v_add_f32_e32 v150, v148, v149
	v_pk_mul_f32 v[152:153], v[120:121], v[124:125] op_sel_hi:[1,0]
	v_pk_mul_f32 v[154:155], v[122:123], v[124:125] op_sel_hi:[1,0]
	v_add_f32_dpp v150, v150, v150 quad_perm:[1,0,3,2] row_mask:0xf bank_mask:0xf bound_ctrl:1
	v_pk_fma_f32 v[152:153], v[68:69], v[108:109], v[152:153]
	v_pk_fma_f32 v[154:155], v[70:71], v[110:111], v[154:155]
	v_add_f32_dpp v150, v150, v150 quad_perm:[2,3,0,1] row_mask:0xf bank_mask:0xf bound_ctrl:1
	v_pk_mul_f32 v[156:157], v[68:69], v[144:145]
	v_pk_fma_f32 v[156:157], v[70:71], v[146:147], v[156:157]
	v_add_f32_dpp v150, v150, v150 row_half_mirror row_mask:0xf bank_mask:0xf bound_ctrl:1
	v_add_f32_e32 v161, v156, v157
	v_add_f32_dpp v162, v158, v158 row_ror:8 row_mask:0xf bank_mask:0xf
	v_add_f32_dpp v150, v150, v150 row_mirror row_mask:0xf bank_mask:0xf bound_ctrl:1
	v_pk_fma_f32 v[72:73], v[116:117], v[150:151], v[152:153] op_sel_hi:[1,0,1]
	v_pk_fma_f32 v[74:75], v[118:119], v[150:151], v[154:155] op_sel_hi:[1,0,1]
	v_add_f32_dpp v163, v159, v159 row_ror:8 row_mask:0xf bank_mask:0xf
	v_add_f32_dpp v162, v160, v160 row_ror:8 row_mask:0xf bank_mask:0xc
	v_add_f32_dpp v163, v161, v161 row_ror:8 row_mask:0xf bank_mask:0xc
	ds_read_b128 v[96:99], v198 offset:15616
	ds_read_b128 v[104:107], v198 offset:16128
	v_add_f32_dpp v164, v162, v162 row_half_mirror row_mask:0xf bank_mask:0xf
	v_add_f32_dpp v164, v163, v163 row_half_mirror row_mask:0xf bank_mask:0xa
	ds_read_b128 v[92:95], v198 offset:15360
	ds_read_b128 v[100:103], v198 offset:15872
	v_add_f32_dpp v164, v164, v164 quad_perm:[1,0,3,2] row_mask:0xf bank_mask:0xf bound_ctrl:1
	ds_read_b128 v[140:143], v198 offset:16384
	s_nop 0
	v_add_f32_dpp v164, v164, v164 quad_perm:[2,3,0,1] row_mask:0xf bank_mask:0xf bound_ctrl:1
	global_store_dword v165, v164, s[34:35]
	v_add_u32_e32 v165, 0xb000, v165
	s_waitcnt lgkmcnt(5)
	v_pk_mul_f32 v[148:149], v[72:73], v[80:81]
	v_pk_fma_f32 v[148:149], v[74:75], v[82:83], v[148:149]
	v_add_f32_e32 v150, v148, v149
	v_pk_mul_f32 v[152:153], v[88:89], v[124:125] op_sel:[0,1] op_sel_hi:[1,1]
	v_pk_mul_f32 v[154:155], v[90:91], v[124:125] op_sel:[0,1] op_sel_hi:[1,1]
	v_add_f32_dpp v150, v150, v150 quad_perm:[1,0,3,2] row_mask:0xf bank_mask:0xf bound_ctrl:1
	v_pk_fma_f32 v[152:153], v[72:73], v[76:77], v[152:153]
	v_pk_fma_f32 v[154:155], v[74:75], v[78:79], v[154:155]
	v_add_f32_dpp v150, v150, v150 quad_perm:[2,3,0,1] row_mask:0xf bank_mask:0xf bound_ctrl:1
	v_pk_mul_f32 v[156:157], v[72:73], v[132:133]
	v_pk_fma_f32 v[156:157], v[74:75], v[134:135], v[156:157]
	v_add_f32_dpp v150, v150, v150 row_half_mirror row_mask:0xf bank_mask:0xf bound_ctrl:1
	v_add_f32_e32 v158, v156, v157
	ds_read_b128 v[112:115], v198 offset:17152
	v_add_f32_dpp v150, v150, v150 row_mirror row_mask:0xf bank_mask:0xf bound_ctrl:1
	v_pk_fma_f32 v[68:69], v[84:85], v[150:151], v[152:153] op_sel_hi:[1,0,1]
	v_pk_fma_f32 v[70:71], v[86:87], v[150:151], v[154:155] op_sel_hi:[1,0,1]
	ds_read_b128 v[120:123], v198 offset:17664
	ds_read_b128 v[108:111], v198 offset:16896
	ds_read_b128 v[116:119], v198 offset:17408
	ds_read_b128 v[144:147], v198 offset:17920
	s_waitcnt lgkmcnt(5)
	v_pk_mul_f32 v[148:149], v[68:69], v[96:97]
	v_pk_fma_f32 v[148:149], v[70:71], v[98:99], v[148:149]
	v_add_f32_e32 v150, v148, v149
	v_pk_mul_f32 v[152:153], v[104:105], v[126:127] op_sel_hi:[1,0]
	v_pk_mul_f32 v[154:155], v[106:107], v[126:127] op_sel_hi:[1,0]
	v_add_f32_dpp v150, v150, v150 quad_perm:[1,0,3,2] row_mask:0xf bank_mask:0xf bound_ctrl:1
	v_pk_fma_f32 v[152:153], v[68:69], v[92:93], v[152:153]
	v_pk_fma_f32 v[154:155], v[70:71], v[94:95], v[154:155]
	v_add_f32_dpp v150, v150, v150 quad_perm:[2,3,0,1] row_mask:0xf bank_mask:0xf bound_ctrl:1
	v_pk_mul_f32 v[156:157], v[68:69], v[136:137]
	v_pk_fma_f32 v[156:157], v[70:71], v[138:139], v[156:157]
	v_add_f32_dpp v150, v150, v150 row_half_mirror row_mask:0xf bank_mask:0xf bound_ctrl:1
	v_add_f32_e32 v159, v156, v157
	ds_read_b128 v[80:83], v198 offset:18688
	v_add_f32_dpp v150, v150, v150 row_mirror row_mask:0xf bank_mask:0xf bound_ctrl:1
	v_pk_fma_f32 v[72:73], v[100:101], v[150:151], v[152:153] op_sel_hi:[1,0,1]
	v_pk_fma_f32 v[74:75], v[102:103], v[150:151], v[154:155] op_sel_hi:[1,0,1]
	ds_read_b128 v[88:91], v198 offset:19200
	ds_read_b128 v[128:131], v204 offset:19712
	ds_read_b128 v[76:79], v198 offset:18432
	ds_read_b128 v[84:87], v198 offset:18944
	ds_read_b128 v[132:135], v198 offset:19456
	s_waitcnt lgkmcnt(6)
	v_pk_mul_f32 v[148:149], v[72:73], v[112:113]
	v_pk_fma_f32 v[148:149], v[74:75], v[114:115], v[148:149]
	v_add_f32_e32 v150, v148, v149
	v_pk_mul_f32 v[152:153], v[120:121], v[126:127] op_sel:[0,1] op_sel_hi:[1,1]
	v_pk_mul_f32 v[154:155], v[122:123], v[126:127] op_sel:[0,1] op_sel_hi:[1,1]
	v_add_f32_dpp v150, v150, v150 quad_perm:[1,0,3,2] row_mask:0xf bank_mask:0xf bound_ctrl:1
	v_pk_fma_f32 v[152:153], v[72:73], v[108:109], v[152:153]
	v_pk_fma_f32 v[154:155], v[74:75], v[110:111], v[154:155]
	v_add_f32_dpp v150, v150, v150 quad_perm:[2,3,0,1] row_mask:0xf bank_mask:0xf bound_ctrl:1
	v_pk_mul_f32 v[156:157], v[72:73], v[140:141]
	v_pk_fma_f32 v[156:157], v[74:75], v[142:143], v[156:157]
	v_add_f32_dpp v150, v150, v150 row_half_mirror row_mask:0xf bank_mask:0xf bound_ctrl:1
	v_add_f32_e32 v160, v156, v157
	ds_read_b128 v[96:99], v198 offset:20224
	v_add_f32_dpp v150, v150, v150 row_mirror row_mask:0xf bank_mask:0xf bound_ctrl:1
	v_pk_fma_f32 v[68:69], v[116:117], v[150:151], v[152:153] op_sel_hi:[1,0,1]
	v_pk_fma_f32 v[70:71], v[118:119], v[150:151], v[154:155] op_sel_hi:[1,0,1]
	ds_read_b128 v[104:107], v198 offset:20736
	ds_read_b128 v[92:95], v198 offset:19968
	ds_read_b128 v[100:103], v198 offset:20480
	ds_read_b128 v[136:139], v198 offset:20992
	s_waitcnt lgkmcnt(5)
; __device__ __forceinline__ void rwkv_scan(Frame& F, int wg, unsigned* shw, unsigned wait_target, int wait_blk) {
;     ...
;             RwOps R[4];
;             RW_LD(R[0], 0); RW_LD(R[1], 1); RW_LD(R[2], 2);
;             for (int s4 = 0; s4 < RW_TB; s4 += 4) {
;                 float pz[4], u[4];
; #pragma unroll
;                 for (int q = 0; q < 4; ++q) {
;                     RW_LD(R[(q + 3) & 3], s4 + q + 3);
;                     const RwOps& cur = R[q];
;                     const f32x2 slo = {st.x, st.y}, shi = {st.z, st.w};
;                     f32x2 ma = slo * (f32x2){cur.a.x, cur.a.y}; ma = __builtin_elementwise_fma(shi, (f32x2){cur.a.z, cur.a.w}, ma);
;                     f32x2 mz = slo * (f32x2){cur.wr.x, cur.wr.y}; mz = __builtin_elementwise_fma(shi, (f32x2){cur.wr.z, cur.wr.w}, mz);
;                     float psa = ma.x + ma.y; pz[q] = mz.x + mz.y;
;                     const f32x2 vb = {cur.vs.x, cur.vs.x};
;                     f32x2 tlo = (f32x2){cur.k.x, cur.k.y} * vb, thi = (f32x2){cur.k.z, cur.k.w} * vb;
;                     tlo = __builtin_elementwise_fma(slo, (f32x2){cur.w.x, cur.w.y}, tlo); thi = __builtin_elementwise_fma(shi, (f32x2){cur.w.z, cur.w.w}, thi);
;                     psa = red16(psa);
;                     const f32x2 pb = {psa, psa};
;                     tlo = __builtin_elementwise_fma((f32x2){cur.b.x, cur.b.y}, pb, tlo); thi = __builtin_elementwise_fma((f32x2){cur.b.z, cur.b.w}, pb, thi);
;                     st = (f32x4){tlo.x, tlo.y, thi.x, thi.y};
;                     u[q] = psa * cur.vs.z + cur.vs.y;
;                 }
;                 const float qa = (odd1 ? pz[1] : pz[0]) + dppf<0xB1>(odd1 ? pz[0] : pz[1]);
;                 const float qb = (odd1 ? pz[3] : pz[2]) + dppf<0xB1>(odd1 ? pz[2] : pz[3]);
;                 float r = (odd2 ? qb : qa) + dppf<0x4E>(odd2 ? qa : qb);
;                 r += dppf<0x124>(r); r += dppf<0x128>(r);
;                 const float us = odd2 ? (odd1 ? u[3] : u[2]) : (odd1 ? u[1] : u[0]);
;                 if (j < 4) { const int t = blk * RW_TB + s4 + j; ((float*)(Ub + (size_t)t * (PWP * 2) + URR * 2))[h * 64 + row] = r + us; }
	v_pk_mul_f32 v[148:149], v[68:69], v[80:81]
	v_pk_fma_f32 v[148:149], v[70:71], v[82:83], v[148:149]
	v_add_f32_e32 v150, v148, v149
	v_pk_mul_f32 v[152:153], v[88:89], v[128:129] op_sel_hi:[1,0]
	v_pk_mul_f32 v[154:155], v[90:91], v[128:129] op_sel_hi:[1,0]
	v_add_f32_dpp v150, v150, v150 quad_perm:[1,0,3,2] row_mask:0xf bank_mask:0xf bound_ctrl:1
	v_pk_fma_f32 v[152:153], v[68:69], v[76:77], v[152:153]
	v_pk_fma_f32 v[154:155], v[70:71], v[78:79], v[154:155]
	v_add_f32_dpp v150, v150, v150 quad_perm:[2,3,0,1] row_mask:0xf bank_mask:0xf bound_ctrl:1
	v_pk_mul_f32 v[156:157], v[68:69], v[144:145]
	v_pk_fma_f32 v[156:157], v[70:71], v[146:147], v[156:157]
	v_add_f32_dpp v150, v150, v150 row_half_mirror row_mask:0xf bank_mask:0xf bound_ctrl:1
	v_add_f32_e32 v161, v156, v157
	v_add_f32_dpp v162, v158, v158 row_ror:8 row_mask:0xf bank_mask:0xf
	v_add_f32_dpp v150, v150, v150 row_mirror row_mask:0xf bank_mask:0xf bound_ctrl:1
	v_pk_fma_f32 v[72:73], v[84:85], v[150:151], v[152:153] op_sel_hi:[1,0,1]
	v_pk_fma_f32 v[74:75], v[86:87], v[150:151], v[154:155] op_sel_hi:[1,0,1]
	v_add_f32_dpp v163, v159, v159 row_ror:8 row_mask:0xf bank_mask:0xf
	v_add_f32_dpp v162, v160, v160 row_ror:8 row_mask:0xf bank_mask:0xc
	v_add_f32_dpp v163, v161, v161 row_ror:8 row_mask:0xf bank_mask:0xc
	ds_read_b128 v[112:115], v198 offset:21760
	ds_read_b128 v[120:123], v198 offset:22272
	v_add_f32_dpp v164, v162, v162 row_half_mirror row_mask:0xf bank_mask:0xf
	v_add_f32_dpp v164, v163, v163 row_half_mirror row_mask:0xf bank_mask:0xa
	ds_read_b128 v[108:111], v198 offset:21504
	ds_read_b128 v[116:119], v198 offset:22016
	v_add_f32_dpp v164, v164, v164 quad_perm:[1,0,3,2] row_mask:0xf bank_mask:0xf bound_ctrl:1
	ds_read_b128 v[140:143], v198 offset:22528
	s_nop 0
	v_add_f32_dpp v164, v164, v164 quad_perm:[2,3,0,1] row_mask:0xf bank_mask:0xf bound_ctrl:1
	global_store_dword v165, v164, s[34:35]
	v_add_u32_e32 v165, 0xb000, v165
	s_waitcnt lgkmcnt(5)
	v_pk_mul_f32 v[148:149], v[72:73], v[96:97]
	v_pk_fma_f32 v[148:149], v[74:75], v[98:99], v[148:149]
	v_add_f32_e32 v150, v148, v149
	v_pk_mul_f32 v[152:153], v[104:105], v[128:129] op_sel:[0,1] op_sel_hi:[1,1]
	v_pk_mul_f32 v[154:155], v[106:107], v[128:129] op_sel:[0,1] op_sel_hi:[1,1]
	v_add_f32_dpp v150, v150, v150 quad_perm:[1,0,3,2] row_mask:0xf bank_mask:0xf bound_ctrl:1
	v_pk_fma_f32 v[152:153], v[72:73], v[92:93], v[152:153]
	v_pk_fma_f32 v[154:155], v[74:75], v[94:95], v[154:155]
	v_add_f32_dpp v150, v150, v150 quad_perm:[2,3,0,1] row_mask:0xf bank_mask:0xf bound_ctrl:1
	v_pk_mul_f32 v[156:157], v[72:73], v[132:133]
	v_pk_fma_f32 v[156:157], v[74:75], v[134:135], v[156:157]
	v_add_f32_dpp v150, v150, v150 row_half_mirror row_mask:0xf bank_mask:0xf bound_ctrl:1
	v_add_f32_e32 v158, v156, v157
	ds_read_b128 v[80:83], v198 offset:23296
	v_add_f32_dpp v150, v150, v150 row_mirror row_mask:0xf bank_mask:0xf bound_ctrl:1
	v_pk_fma_f32 v[68:69], v[100:101], v[150:151], v[152:153] op_sel_hi:[1,0,1]
	v_pk_fma_f32 v[70:71], v[102:103], v[150:151], v[154:155] op_sel_hi:[1,0,1]
	ds_read_b128 v[88:91], v198 offset:23808
	ds_read_b128 v[76:79], v198 offset:23040
	ds_read_b128 v[84:87], v198 offset:23552
	ds_read_b128 v[144:147], v198 offset:24064
	s_waitcnt lgkmcnt(5)
	v_pk_mul_f32 v[148:149], v[68:69], v[112:113]
	v_pk_fma_f32 v[148:149], v[70:71], v[114:115], v[148:149]
	v_add_f32_e32 v150, v148, v149
	v_pk_mul_f32 v[152:153], v[120:121], v[130:131] op_sel_hi:[1,0]
	v_pk_mul_f32 v[154:155], v[122:123], v[130:131] op_sel_hi:[1,0]
	v_add_f32_dpp v150, v150, v150 quad_perm:[1,0,3,2] row_mask:0xf bank_mask:0xf bound_ctrl:1
	v_pk_fma_f32 v[152:153], v[68:69], v[108:109], v[152:153]
	v_pk_fma_f32 v[154:155], v[70:71], v[110:111], v[154:155]
	v_add_f32_dpp v150, v150, v150 quad_perm:[2,3,0,1] row_mask:0xf bank_mask:0xf bound_ctrl:1
	v_pk_mul_f32 v[156:157], v[68:69], v[136:137]
	v_pk_fma_f32 v[156:157], v[70:71], v[138:139], v[156:157]
	v_add_f32_dpp v150, v150, v150 row_half_mirror row_mask:0xf bank_mask:0xf bound_ctrl:1
	v_add_f32_e32 v159, v156, v157
	ds_read_b128 v[96:99], v198 offset:24832
	v_add_f32_dpp v150, v150, v150 row_mirror row_mask:0xf bank_mask:0xf bound_ctrl:1
	v_pk_fma_f32 v[72:73], v[116:117], v[150:151], v[152:153] op_sel_hi:[1,0,1]
	v_pk_fma_f32 v[74:75], v[118:119], v[150:151], v[154:155] op_sel_hi:[1,0,1]
	ds_read_b128 v[104:107], v198 offset:25344
	ds_read_b128 v[124:127], v204 offset:25856
	ds_read_b128 v[92:95], v198 offset:24576
	ds_read_b128 v[100:103], v198 offset:25088
	ds_read_b128 v[132:135], v198 offset:25600
	s_waitcnt lgkmcnt(6)
	v_pk_mul_f32 v[148:149], v[72:73], v[80:81]
	v_pk_fma_f32 v[148:149], v[74:75], v[82:83], v[148:149]
	v_add_f32_e32 v150, v148, v149
	v_pk_mul_f32 v[152:153], v[88:89], v[130:131] op_sel:[0,1] op_sel_hi:[1,1]
	v_pk_mul_f32 v[154:155], v[90:91], v[130:131] op_sel:[0,1] op_sel_hi:[1,1]
	v_add_f32_dpp v150, v150, v150 quad_perm:[1,0,3,2] row_mask:0xf bank_mask:0xf bound_ctrl:1
	v_pk_fma_f32 v[152:153], v[72:73], v[76:77], v[152:153]
	v_pk_fma_f32 v[154:155], v[74:75], v[78:79], v[154:155]
	v_add_f32_dpp v150, v150, v150 quad_perm:[2,3,0,1] row_mask:0xf bank_mask:0xf bound_ctrl:1
	v_pk_mul_f32 v[156:157], v[72:73], v[140:141]
	v_pk_fma_f32 v[156:157], v[74:75], v[142:143], v[156:157]
	v_add_f32_dpp v150, v150, v150 row_half_mirror row_mask:0xf bank_mask:0xf bound_ctrl:1
	v_add_f32_e32 v160, v156, v157
	ds_read_b128 v[112:115], v198 offset:26368
	v_add_f32_dpp v150, v150, v150 row_mirror row_mask:0xf bank_mask:0xf bound_ctrl:1
	v_pk_fma_f32 v[68:69], v[84:85], v[150:151], v[152:153] op_sel_hi:[1,0,1]
	v_pk_fma_f32 v[70:71], v[86:87], v[150:151], v[154:155] op_sel_hi:[1,0,1]
	ds_read_b128 v[120:123], v198 offset:26880
	ds_read_b128 v[108:111], v198 offset:26112
	ds_read_b128 v[116:119], v198 offset:26624
	ds_read_b128 v[136:139], v198 offset:27136
	s_waitcnt lgkmcnt(5)
; __device__ __forceinline__ void rwkv_scan(Frame& F, int wg, unsigned* shw, unsigned wait_target, int wait_blk) {
;     ...
;             RwOps R[4];
;             RW_LD(R[0], 0); RW_LD(R[1], 1); RW_LD(R[2], 2);
;             for (int s4 = 0; s4 < RW_TB; s4 += 4) {
;                 float pz[4], u[4];
; #pragma unroll
;                 for (int q = 0; q < 4; ++q) {
;                     RW_LD(R[(q + 3) & 3], s4 + q + 3);
;                     const RwOps& cur = R[q];
;                     const f32x2 slo = {st.x, st.y}, shi = {st.z, st.w};
;                     f32x2 ma = slo * (f32x2){cur.a.x, cur.a.y}; ma = __builtin_elementwise_fma(shi, (f32x2){cur.a.z, cur.a.w}, ma);
;                     f32x2 mz = slo * (f32x2){cur.wr.x, cur.wr.y}; mz = __builtin_elementwise_fma(shi, (f32x2){cur.wr.z, cur.wr.w}, mz);
;                     float psa = ma.x + ma.y; pz[q] = mz.x + mz.y;
;                     const f32x2 vb = {cur.vs.x, cur.vs.x};
;                     f32x2 tlo = (f32x2){cur.k.x, cur.k.y} * vb, thi = (f32x2){cur.k.z, cur.k.w} * vb;
;                     tlo = __builtin_elementwise_fma(slo, (f32x2){cur.w.x, cur.w.y}, tlo); thi = __builtin_elementwise_fma(shi, (f32x2){cur.w.z, cur.w.w}, thi);
;                     psa = red16(psa);
;                     const f32x2 pb = {psa, psa};
;                     tlo = __builtin_elementwise_fma((f32x2){cur.b.x, cur.b.y}, pb, tlo); thi = __builtin_elementwise_fma((f32x2){cur.b.z, cur.b.w}, pb, thi);
;                     st = (f32x4){tlo.x, tlo.y, thi.x, thi.y};
;                     u[q] = psa * cur.vs.z + cur.vs.y;
;                 }
;                 const float qa = (odd1 ? pz[1] : pz[0]) + dppf<0xB1>(odd1 ? pz[0] : pz[1]);
;                 const float qb = (odd1 ? pz[3] : pz[2]) + dppf<0xB1>(odd1 ? pz[2] : pz[3]);
;                 float r = (odd2 ? qb : qa) + dppf<0x4E>(odd2 ? qa : qb);
;                 r += dppf<0x124>(r); r += dppf<0x128>(r);
;                 const float us = odd2 ? (odd1 ? u[3] : u[2]) : (odd1 ? u[1] : u[0]);
;                 if (j < 4) { const int t = blk * RW_TB + s4 + j; ((float*)(Ub + (size_t)t * (PWP * 2) + URR * 2))[h * 64 + row] = r + us; }
	v_pk_mul_f32 v[148:149], v[68:69], v[96:97]
	v_pk_fma_f32 v[148:149], v[70:71], v[98:99], v[148:149]
	v_add_f32_e32 v150, v148, v149
	v_pk_mul_f32 v[152:153], v[104:105], v[124:125] op_sel_hi:[1,0]
	v_pk_mul_f32 v[154:155], v[106:107], v[124:125] op_sel_hi:[1,0]
	v_add_f32_dpp v150, v150, v150 quad_perm:[1,0,3,2] row_mask:0xf bank_mask:0xf bound_ctrl:1
	v_pk_fma_f32 v[152:153], v[68:69], v[92:93], v[152:153]
	v_pk_fma_f32 v[154:155], v[70:71], v[94:95], v[154:155]
	v_add_f32_dpp v150, v150, v150 quad_perm:[2,3,0,1] row_mask:0xf bank_mask:0xf bound_ctrl:1
	v_pk_mul_f32 v[156:157], v[68:69], v[144:145]
	v_pk_fma_f32 v[156:157], v[70:71], v[146:147], v[156:157]
	v_add_f32_dpp v150, v150, v150 row_half_mirror row_mask:0xf bank_mask:0xf bound_ctrl:1
	v_add_f32_e32 v161, v156, v157
	v_add_f32_dpp v162, v158, v158 row_ror:8 row_mask:0xf bank_mask:0xf
	v_add_f32_dpp v150, v150, v150 row_mirror row_mask:0xf bank_mask:0xf bound_ctrl:1
	v_pk_fma_f32 v[72:73], v[100:101], v[150:151], v[152:153] op_sel_hi:[1,0,1]
	v_pk_fma_f32 v[74:75], v[102:103], v[150:151], v[154:155] op_sel_hi:[1,0,1]
	v_add_f32_dpp v163, v159, v159 row_ror:8 row_mask:0xf bank_mask:0xf
	v_add_f32_dpp v162, v160, v160 row_ror:8 row_mask:0xf bank_mask:0xc
	v_add_f32_dpp v163, v161, v161 row_ror:8 row_mask:0xf bank_mask:0xc
	ds_read_b128 v[80:83], v198 offset:27904
	ds_read_b128 v[88:91], v198 offset:28416
	v_add_f32_dpp v164, v162, v162 row_half_mirror row_mask:0xf bank_mask:0xf
	v_add_f32_dpp v164, v163, v163 row_half_mirror row_mask:0xf bank_mask:0xa
	ds_read_b128 v[76:79], v198 offset:27648
	ds_read_b128 v[84:87], v198 offset:28160
	v_add_f32_dpp v164, v164, v164 quad_perm:[1,0,3,2] row_mask:0xf bank_mask:0xf bound_ctrl:1
	ds_read_b128 v[140:143], v198 offset:28672
	s_nop 0
	v_add_f32_dpp v164, v164, v164 quad_perm:[2,3,0,1] row_mask:0xf bank_mask:0xf bound_ctrl:1
	global_store_dword v165, v164, s[34:35]
	v_add_u32_e32 v165, 0xb000, v165
	s_waitcnt lgkmcnt(5)
	v_pk_mul_f32 v[148:149], v[72:73], v[112:113]
	v_pk_fma_f32 v[148:149], v[74:75], v[114:115], v[148:149]
	v_add_f32_e32 v150, v148, v149
	v_pk_mul_f32 v[152:153], v[120:121], v[124:125] op_sel:[0,1] op_sel_hi:[1,1]
	v_pk_mul_f32 v[154:155], v[122:123], v[124:125] op_sel:[0,1] op_sel_hi:[1,1]
	v_add_f32_dpp v150, v150, v150 quad_perm:[1,0,3,2] row_mask:0xf bank_mask:0xf bound_ctrl:1
	v_pk_fma_f32 v[152:153], v[72:73], v[108:109], v[152:153]
	v_pk_fma_f32 v[154:155], v[74:75], v[110:111], v[154:155]
	v_add_f32_dpp v150, v150, v150 quad_perm:[2,3,0,1] row_mask:0xf bank_mask:0xf bound_ctrl:1
	v_pk_mul_f32 v[156:157], v[72:73], v[132:133]
	v_pk_fma_f32 v[156:157], v[74:75], v[134:135], v[156:157]
	v_add_f32_dpp v150, v150, v150 row_half_mirror row_mask:0xf bank_mask:0xf bound_ctrl:1
	v_add_f32_e32 v158, v156, v157
	ds_read_b128 v[96:99], v198 offset:29440
	v_add_f32_dpp v150, v150, v150 row_mirror row_mask:0xf bank_mask:0xf bound_ctrl:1
	v_pk_fma_f32 v[68:69], v[116:117], v[150:151], v[152:153] op_sel_hi:[1,0,1]
	v_pk_fma_f32 v[70:71], v[118:119], v[150:151], v[154:155] op_sel_hi:[1,0,1]
	ds_read_b128 v[104:107], v198 offset:29952
	ds_read_b128 v[92:95], v198 offset:29184
	ds_read_b128 v[100:103], v198 offset:29696
	ds_read_b128 v[144:147], v198 offset:30208
	s_waitcnt lgkmcnt(5)
	v_pk_mul_f32 v[148:149], v[68:69], v[80:81]
	v_pk_fma_f32 v[148:149], v[70:71], v[82:83], v[148:149]
	v_add_f32_e32 v150, v148, v149
	v_pk_mul_f32 v[152:153], v[88:89], v[126:127] op_sel_hi:[1,0]
	v_pk_mul_f32 v[154:155], v[90:91], v[126:127] op_sel_hi:[1,0]
	v_add_f32_dpp v150, v150, v150 quad_perm:[1,0,3,2] row_mask:0xf bank_mask:0xf bound_ctrl:1
	v_pk_fma_f32 v[152:153], v[68:69], v[76:77], v[152:153]
	v_pk_fma_f32 v[154:155], v[70:71], v[78:79], v[154:155]
	v_add_f32_dpp v150, v150, v150 quad_perm:[2,3,0,1] row_mask:0xf bank_mask:0xf bound_ctrl:1
	v_pk_mul_f32 v[156:157], v[68:69], v[136:137]
	v_pk_fma_f32 v[156:157], v[70:71], v[138:139], v[156:157]
	v_add_f32_dpp v150, v150, v150 row_half_mirror row_mask:0xf bank_mask:0xf bound_ctrl:1
	v_add_f32_e32 v159, v156, v157
	ds_read_b128 v[112:115], v198 offset:30976
	v_add_f32_dpp v150, v150, v150 row_mirror row_mask:0xf bank_mask:0xf bound_ctrl:1
	v_pk_fma_f32 v[72:73], v[84:85], v[150:151], v[152:153] op_sel_hi:[1,0,1]
	v_pk_fma_f32 v[74:75], v[86:87], v[150:151], v[154:155] op_sel_hi:[1,0,1]
	ds_read_b128 v[120:123], v198 offset:31488
	ds_read_b128 v[128:131], v204 offset:32000
	ds_read_b128 v[108:111], v198 offset:30720
	ds_read_b128 v[116:119], v198 offset:31232
	ds_read_b128 v[132:135], v198 offset:31744
	s_waitcnt lgkmcnt(6)
	v_pk_mul_f32 v[148:149], v[72:73], v[96:97]
	v_pk_fma_f32 v[148:149], v[74:75], v[98:99], v[148:149]
	v_add_f32_e32 v150, v148, v149
	v_pk_mul_f32 v[152:153], v[104:105], v[126:127] op_sel:[0,1] op_sel_hi:[1,1]
	v_pk_mul_f32 v[154:155], v[106:107], v[126:127] op_sel:[0,1] op_sel_hi:[1,1]
	v_add_f32_dpp v150, v150, v150 quad_perm:[1,0,3,2] row_mask:0xf bank_mask:0xf bound_ctrl:1
	v_pk_fma_f32 v[152:153], v[72:73], v[92:93], v[152:153]
	v_pk_fma_f32 v[154:155], v[74:75], v[94:95], v[154:155]
	v_add_f32_dpp v150, v150, v150 quad_perm:[2,3,0,1] row_mask:0xf bank_mask:0xf bound_ctrl:1
	v_pk_mul_f32 v[156:157], v[72:73], v[140:141]
	v_pk_fma_f32 v[156:157], v[74:75], v[142:143], v[156:157]
	v_add_f32_dpp v150, v150, v150 row_half_mirror row_mask:0xf bank_mask:0xf bound_ctrl:1
	v_add_f32_e32 v160, v156, v157
	ds_read_b128 v[80:83], v198 offset:32512
	v_add_f32_dpp v150, v150, v150 row_mirror row_mask:0xf bank_mask:0xf bound_ctrl:1
	v_pk_fma_f32 v[68:69], v[100:101], v[150:151], v[152:153] op_sel_hi:[1,0,1]
	v_pk_fma_f32 v[70:71], v[102:103], v[150:151], v[154:155] op_sel_hi:[1,0,1]
	ds_read_b128 v[88:91], v198 offset:33024
	ds_read_b128 v[76:79], v198 offset:32256
	ds_read_b128 v[84:87], v198 offset:32768
	ds_read_b128 v[136:139], v198 offset:33280
	s_waitcnt lgkmcnt(5)
; __device__ __forceinline__ void rwkv_scan(Frame& F, int wg, unsigned* shw, unsigned wait_target, int wait_blk) {
;     ...
;             RwOps R[4];
;             RW_LD(R[0], 0); RW_LD(R[1], 1); RW_LD(R[2], 2);
;             for (int s4 = 0; s4 < RW_TB; s4 += 4) {
;                 float pz[4], u[4];
; #pragma unroll
;                 for (int q = 0; q < 4; ++q) {
;                     RW_LD(R[(q + 3) & 3], s4 + q + 3);
;                     const RwOps& cur = R[q];
;                     const f32x2 slo = {st.x, st.y}, shi = {st.z, st.w};
;                     f32x2 ma = slo * (f32x2){cur.a.x, cur.a.y}; ma = __builtin_elementwise_fma(shi, (f32x2){cur.a.z, cur.a.w}, ma);
;                     f32x2 mz = slo * (f32x2){cur.wr.x, cur.wr.y}; mz = __builtin_elementwise_fma(shi, (f32x2){cur.wr.z, cur.wr.w}, mz);
;                     float psa = ma.x + ma.y; pz[q] = mz.x + mz.y;
;                     const f32x2 vb = {cur.vs.x, cur.vs.x};
;                     f32x2 tlo = (f32x2){cur.k.x, cur.k.y} * vb, thi = (f32x2){cur.k.z, cur.k.w} * vb;
;                     tlo = __builtin_elementwise_fma(slo, (f32x2){cur.w.x, cur.w.y}, tlo); thi = __builtin_elementwise_fma(shi, (f32x2){cur.w.z, cur.w.w}, thi);
;                     psa = red16(psa);
;                     const f32x2 pb = {psa, psa};
;                     tlo = __builtin_elementwise_fma((f32x2){cur.b.x, cur.b.y}, pb, tlo); thi = __builtin_elementwise_fma((f32x2){cur.b.z, cur.b.w}, pb, thi);
;                     st = (f32x4){tlo.x, tlo.y, thi.x, thi.y};
;                     u[q] = psa * cur.vs.z + cur.vs.y;
;                 }
;                 const float qa = (odd1 ? pz[1] : pz[0]) + dppf<0xB1>(odd1 ? pz[0] : pz[1]);
;                 const float qb = (odd1 ? pz[3] : pz[2]) + dppf<0xB1>(odd1 ? pz[2] : pz[3]);
;                 float r = (odd2 ? qb : qa) + dppf<0x4E>(odd2 ? qa : qb);
;                 r += dppf<0x124>(r); r += dppf<0x128>(r);
;                 const float us = odd2 ? (odd1 ? u[3] : u[2]) : (odd1 ? u[1] : u[0]);
;                 if (j < 4) { const int t = blk * RW_TB + s4 + j; ((float*)(Ub + (size_t)t * (PWP * 2) + URR * 2))[h * 64 + row] = r + us; }
	v_pk_mul_f32 v[148:149], v[68:69], v[112:113]
	v_pk_fma_f32 v[148:149], v[70:71], v[114:115], v[148:149]
	v_add_f32_e32 v150, v148, v149
	v_pk_mul_f32 v[152:153], v[120:121], v[128:129] op_sel_hi:[1,0]
	v_pk_mul_f32 v[154:155], v[122:123], v[128:129] op_sel_hi:[1,0]
	v_add_f32_dpp v150, v150, v150 quad_perm:[1,0,3,2] row_mask:0xf bank_mask:0xf bound_ctrl:1
	v_pk_fma_f32 v[152:153], v[68:69], v[108:109], v[152:153]
	v_pk_fma_f32 v[154:155], v[70:71], v[110:111], v[154:155]
	v_add_f32_dpp v150, v150, v150 quad_perm:[2,3,0,1] row_mask:0xf bank_mask:0xf bound_ctrl:1
	v_pk_mul_f32 v[156:157], v[68:69], v[144:145]
	v_pk_fma_f32 v[156:157], v[70:71], v[146:147], v[156:157]
	v_add_f32_dpp v150, v150, v150 row_half_mirror row_mask:0xf bank_mask:0xf bound_ctrl:1
	v_add_f32_e32 v161, v156, v157
	v_add_f32_dpp v162, v158, v158 row_ror:8 row_mask:0xf bank_mask:0xf
	v_add_f32_dpp v150, v150, v150 row_mirror row_mask:0xf bank_mask:0xf bound_ctrl:1
	v_pk_fma_f32 v[72:73], v[116:117], v[150:151], v[152:153] op_sel_hi:[1,0,1]
	v_pk_fma_f32 v[74:75], v[118:119], v[150:151], v[154:155] op_sel_hi:[1,0,1]
	v_add_f32_dpp v163, v159, v159 row_ror:8 row_mask:0xf bank_mask:0xf
	v_add_f32_dpp v162, v160, v160 row_ror:8 row_mask:0xf bank_mask:0xc
	v_add_f32_dpp v163, v161, v161 row_ror:8 row_mask:0xf bank_mask:0xc
	ds_read_b128 v[96:99], v198 offset:34048
	ds_read_b128 v[104:107], v198 offset:34560
	v_add_f32_dpp v164, v162, v162 row_half_mirror row_mask:0xf bank_mask:0xf
	v_add_f32_dpp v164, v163, v163 row_half_mirror row_mask:0xf bank_mask:0xa
	ds_read_b128 v[92:95], v198 offset:33792
	ds_read_b128 v[100:103], v198 offset:34304
	v_add_f32_dpp v164, v164, v164 quad_perm:[1,0,3,2] row_mask:0xf bank_mask:0xf bound_ctrl:1
	ds_read_b128 v[140:143], v198 offset:34816
	s_nop 0
	v_add_f32_dpp v164, v164, v164 quad_perm:[2,3,0,1] row_mask:0xf bank_mask:0xf bound_ctrl:1
	global_store_dword v165, v164, s[34:35]
	v_add_u32_e32 v165, 0xb000, v165
	s_waitcnt lgkmcnt(5)
	v_pk_mul_f32 v[148:149], v[72:73], v[80:81]
	v_pk_fma_f32 v[148:149], v[74:75], v[82:83], v[148:149]
	v_add_f32_e32 v150, v148, v149
	v_pk_mul_f32 v[152:153], v[88:89], v[128:129] op_sel:[0,1] op_sel_hi:[1,1]
	v_pk_mul_f32 v[154:155], v[90:91], v[128:129] op_sel:[0,1] op_sel_hi:[1,1]
	v_add_f32_dpp v150, v150, v150 quad_perm:[1,0,3,2] row_mask:0xf bank_mask:0xf bound_ctrl:1
	v_pk_fma_f32 v[152:153], v[72:73], v[76:77], v[152:153]
	v_pk_fma_f32 v[154:155], v[74:75], v[78:79], v[154:155]
	v_add_f32_dpp v150, v150, v150 quad_perm:[2,3,0,1] row_mask:0xf bank_mask:0xf bound_ctrl:1
	v_pk_mul_f32 v[156:157], v[72:73], v[132:133]
	v_pk_fma_f32 v[156:157], v[74:75], v[134:135], v[156:157]
	v_add_f32_dpp v150, v150, v150 row_half_mirror row_mask:0xf bank_mask:0xf bound_ctrl:1
	v_add_f32_e32 v158, v156, v157
	ds_read_b128 v[112:115], v198 offset:35584
	v_add_f32_dpp v150, v150, v150 row_mirror row_mask:0xf bank_mask:0xf bound_ctrl:1
	v_pk_fma_f32 v[68:69], v[84:85], v[150:151], v[152:153] op_sel_hi:[1,0,1]
	v_pk_fma_f32 v[70:71], v[86:87], v[150:151], v[154:155] op_sel_hi:[1,0,1]
	ds_read_b128 v[120:123], v198 offset:36096
	ds_read_b128 v[108:111], v198 offset:35328
	ds_read_b128 v[116:119], v198 offset:35840
	ds_read_b128 v[144:147], v198 offset:36352
	s_waitcnt lgkmcnt(5)
	v_pk_mul_f32 v[148:149], v[68:69], v[96:97]
	v_pk_fma_f32 v[148:149], v[70:71], v[98:99], v[148:149]
	v_add_f32_e32 v150, v148, v149
	v_pk_mul_f32 v[152:153], v[104:105], v[130:131] op_sel_hi:[1,0]
	v_pk_mul_f32 v[154:155], v[106:107], v[130:131] op_sel_hi:[1,0]
	v_add_f32_dpp v150, v150, v150 quad_perm:[1,0,3,2] row_mask:0xf bank_mask:0xf bound_ctrl:1
	v_pk_fma_f32 v[152:153], v[68:69], v[92:93], v[152:153]
	v_pk_fma_f32 v[154:155], v[70:71], v[94:95], v[154:155]
	v_add_f32_dpp v150, v150, v150 quad_perm:[2,3,0,1] row_mask:0xf bank_mask:0xf bound_ctrl:1
	v_pk_mul_f32 v[156:157], v[68:69], v[136:137]
	v_pk_fma_f32 v[156:157], v[70:71], v[138:139], v[156:157]
	v_add_f32_dpp v150, v150, v150 row_half_mirror row_mask:0xf bank_mask:0xf bound_ctrl:1
	v_add_f32_e32 v159, v156, v157
	ds_read_b128 v[80:83], v198 offset:37120
	v_add_f32_dpp v150, v150, v150 row_mirror row_mask:0xf bank_mask:0xf bound_ctrl:1
	v_pk_fma_f32 v[72:73], v[100:101], v[150:151], v[152:153] op_sel_hi:[1,0,1]
	v_pk_fma_f32 v[74:75], v[102:103], v[150:151], v[154:155] op_sel_hi:[1,0,1]
	ds_read_b128 v[88:91], v198 offset:37632
	ds_read_b128 v[124:127], v204 offset:38144
	ds_read_b128 v[76:79], v198 offset:36864
	ds_read_b128 v[84:87], v198 offset:37376
	ds_read_b128 v[132:135], v198 offset:37888
	s_waitcnt lgkmcnt(6)
	v_pk_mul_f32 v[148:149], v[72:73], v[112:113]
	v_pk_fma_f32 v[148:149], v[74:75], v[114:115], v[148:149]
	v_add_f32_e32 v150, v148, v149
	v_pk_mul_f32 v[152:153], v[120:121], v[130:131] op_sel:[0,1] op_sel_hi:[1,1]
	v_pk_mul_f32 v[154:155], v[122:123], v[130:131] op_sel:[0,1] op_sel_hi:[1,1]
	v_add_f32_dpp v150, v150, v150 quad_perm:[1,0,3,2] row_mask:0xf bank_mask:0xf bound_ctrl:1
	v_pk_fma_f32 v[152:153], v[72:73], v[108:109], v[152:153]
	v_pk_fma_f32 v[154:155], v[74:75], v[110:111], v[154:155]
	v_add_f32_dpp v150, v150, v150 quad_perm:[2,3,0,1] row_mask:0xf bank_mask:0xf bound_ctrl:1
	v_pk_mul_f32 v[156:157], v[72:73], v[140:141]
	v_pk_fma_f32 v[156:157], v[74:75], v[142:143], v[156:157]
	v_add_f32_dpp v150, v150, v150 row_half_mirror row_mask:0xf bank_mask:0xf bound_ctrl:1
	v_add_f32_e32 v160, v156, v157
	ds_read_b128 v[96:99], v198 offset:38656
	v_add_f32_dpp v150, v150, v150 row_mirror row_mask:0xf bank_mask:0xf bound_ctrl:1
	v_pk_fma_f32 v[68:69], v[116:117], v[150:151], v[152:153] op_sel_hi:[1,0,1]
	v_pk_fma_f32 v[70:71], v[118:119], v[150:151], v[154:155] op_sel_hi:[1,0,1]
	ds_read_b128 v[104:107], v198 offset:39168
	ds_read_b128 v[92:95], v198 offset:38400
	ds_read_b128 v[100:103], v198 offset:38912
	ds_read_b128 v[136:139], v198 offset:39424
	s_waitcnt lgkmcnt(5)
; __device__ __forceinline__ void rwkv_scan(Frame& F, int wg, unsigned* shw, unsigned wait_target, int wait_blk) {
;     ...
;             RwOps R[4];
;             RW_LD(R[0], 0); RW_LD(R[1], 1); RW_LD(R[2], 2);
;             for (int s4 = 0; s4 < RW_TB; s4 += 4) {
;                 float pz[4], u[4];
; #pragma unroll
;                 for (int q = 0; q < 4; ++q) {
;                     RW_LD(R[(q + 3) & 3], s4 + q + 3);
;                     const RwOps& cur = R[q];
;                     const f32x2 slo = {st.x, st.y}, shi = {st.z, st.w};
;                     f32x2 ma = slo * (f32x2){cur.a.x, cur.a.y}; ma = __builtin_elementwise_fma(shi, (f32x2){cur.a.z, cur.a.w}, ma);
;                     f32x2 mz = slo * (f32x2){cur.wr.x, cur.wr.y}; mz = __builtin_elementwise_fma(shi, (f32x2){cur.wr.z, cur.wr.w}, mz);
;                     float psa = ma.x + ma.y; pz[q] = mz.x + mz.y;
;                     const f32x2 vb = {cur.vs.x, cur.vs.x};
;                     f32x2 tlo = (f32x2){cur.k.x, cur.k.y} * vb, thi = (f32x2){cur.k.z, cur.k.w} * vb;
;                     tlo = __builtin_elementwise_fma(slo, (f32x2){cur.w.x, cur.w.y}, tlo); thi = __builtin_elementwise_fma(shi, (f32x2){cur.w.z, cur.w.w}, thi);
;                     psa = red16(psa);
;                     const f32x2 pb = {psa, psa};
;                     tlo = __builtin_elementwise_fma((f32x2){cur.b.x, cur.b.y}, pb, tlo); thi = __builtin_elementwise_fma((f32x2){cur.b.z, cur.b.w}, pb, thi);
;                     st = (f32x4){tlo.x, tlo.y, thi.x, thi.y};
;                     u[q] = psa * cur.vs.z + cur.vs.y;
;                 }
;                 const float qa = (odd1 ? pz[1] : pz[0]) + dppf<0xB1>(odd1 ? pz[0] : pz[1]);
;                 const float qb = (odd1 ? pz[3] : pz[2]) + dppf<0xB1>(odd1 ? pz[2] : pz[3]);
;                 float r = (odd2 ? qb : qa) + dppf<0x4E>(odd2 ? qa : qb);
;                 r += dppf<0x124>(r); r += dppf<0x128>(r);
;                 const float us = odd2 ? (odd1 ? u[3] : u[2]) : (odd1 ? u[1] : u[0]);
;                 if (j < 4) { const int t = blk * RW_TB + s4 + j; ((float*)(Ub + (size_t)t * (PWP * 2) + URR * 2))[h * 64 + row] = r + us; }
	v_pk_mul_f32 v[148:149], v[68:69], v[80:81]
	v_pk_fma_f32 v[148:149], v[70:71], v[82:83], v[148:149]
	v_add_f32_e32 v150, v148, v149
	v_pk_mul_f32 v[152:153], v[88:89], v[124:125] op_sel_hi:[1,0]
	v_pk_mul_f32 v[154:155], v[90:91], v[124:125] op_sel_hi:[1,0]
	v_add_f32_dpp v150, v150, v150 quad_perm:[1,0,3,2] row_mask:0xf bank_mask:0xf bound_ctrl:1
	v_pk_fma_f32 v[152:153], v[68:69], v[76:77], v[152:153]
	v_pk_fma_f32 v[154:155], v[70:71], v[78:79], v[154:155]
	v_add_f32_dpp v150, v150, v150 quad_perm:[2,3,0,1] row_mask:0xf bank_mask:0xf bound_ctrl:1
	v_pk_mul_f32 v[156:157], v[68:69], v[144:145]
	v_pk_fma_f32 v[156:157], v[70:71], v[146:147], v[156:157]
	v_add_f32_dpp v150, v150, v150 row_half_mirror row_mask:0xf bank_mask:0xf bound_ctrl:1
	v_add_f32_e32 v161, v156, v157
	v_add_f32_dpp v162, v158, v158 row_ror:8 row_mask:0xf bank_mask:0xf
	v_add_f32_dpp v150, v150, v150 row_mirror row_mask:0xf bank_mask:0xf bound_ctrl:1
	v_pk_fma_f32 v[72:73], v[84:85], v[150:151], v[152:153] op_sel_hi:[1,0,1]
	v_pk_fma_f32 v[74:75], v[86:87], v[150:151], v[154:155] op_sel_hi:[1,0,1]
	v_add_f32_dpp v163, v159, v159 row_ror:8 row_mask:0xf bank_mask:0xf
	v_add_f32_dpp v162, v160, v160 row_ror:8 row_mask:0xf bank_mask:0xc
	v_add_f32_dpp v163, v161, v161 row_ror:8 row_mask:0xf bank_mask:0xc
	ds_read_b128 v[112:115], v198 offset:40192
	ds_read_b128 v[120:123], v198 offset:40704
	v_add_f32_dpp v164, v162, v162 row_half_mirror row_mask:0xf bank_mask:0xf
	v_add_f32_dpp v164, v163, v163 row_half_mirror row_mask:0xf bank_mask:0xa
	ds_read_b128 v[108:111], v198 offset:39936
	ds_read_b128 v[116:119], v198 offset:40448
	v_add_f32_dpp v164, v164, v164 quad_perm:[1,0,3,2] row_mask:0xf bank_mask:0xf bound_ctrl:1
	ds_read_b128 v[140:143], v198 offset:40960
	s_nop 0
	v_add_f32_dpp v164, v164, v164 quad_perm:[2,3,0,1] row_mask:0xf bank_mask:0xf bound_ctrl:1
	global_store_dword v165, v164, s[34:35]
	v_add_u32_e32 v165, 0xb000, v165
	s_waitcnt lgkmcnt(5)
	v_pk_mul_f32 v[148:149], v[72:73], v[96:97]
	v_pk_fma_f32 v[148:149], v[74:75], v[98:99], v[148:149]
	v_add_f32_e32 v150, v148, v149
	v_pk_mul_f32 v[152:153], v[104:105], v[124:125] op_sel:[0,1] op_sel_hi:[1,1]
	v_pk_mul_f32 v[154:155], v[106:107], v[124:125] op_sel:[0,1] op_sel_hi:[1,1]
	v_add_f32_dpp v150, v150, v150 quad_perm:[1,0,3,2] row_mask:0xf bank_mask:0xf bound_ctrl:1
	v_pk_fma_f32 v[152:153], v[72:73], v[92:93], v[152:153]
	v_pk_fma_f32 v[154:155], v[74:75], v[94:95], v[154:155]
	v_add_f32_dpp v150, v150, v150 quad_perm:[2,3,0,1] row_mask:0xf bank_mask:0xf bound_ctrl:1
	v_pk_mul_f32 v[156:157], v[72:73], v[132:133]
	v_pk_fma_f32 v[156:157], v[74:75], v[134:135], v[156:157]
	v_add_f32_dpp v150, v150, v150 row_half_mirror row_mask:0xf bank_mask:0xf bound_ctrl:1
	v_add_f32_e32 v158, v156, v157
	ds_read_b128 v[80:83], v198 offset:41728
	v_add_f32_dpp v150, v150, v150 row_mirror row_mask:0xf bank_mask:0xf bound_ctrl:1
	v_pk_fma_f32 v[68:69], v[100:101], v[150:151], v[152:153] op_sel_hi:[1,0,1]
	v_pk_fma_f32 v[70:71], v[102:103], v[150:151], v[154:155] op_sel_hi:[1,0,1]
	ds_read_b128 v[88:91], v198 offset:42240
	ds_read_b128 v[76:79], v198 offset:41472
	ds_read_b128 v[84:87], v198 offset:41984
	ds_read_b128 v[144:147], v198 offset:42496
	s_waitcnt lgkmcnt(5)
	v_pk_mul_f32 v[148:149], v[68:69], v[112:113]
	v_pk_fma_f32 v[148:149], v[70:71], v[114:115], v[148:149]
	v_add_f32_e32 v150, v148, v149
	v_pk_mul_f32 v[152:153], v[120:121], v[126:127] op_sel_hi:[1,0]
	v_pk_mul_f32 v[154:155], v[122:123], v[126:127] op_sel_hi:[1,0]
	v_add_f32_dpp v150, v150, v150 quad_perm:[1,0,3,2] row_mask:0xf bank_mask:0xf bound_ctrl:1
	v_pk_fma_f32 v[152:153], v[68:69], v[108:109], v[152:153]
	v_pk_fma_f32 v[154:155], v[70:71], v[110:111], v[154:155]
	v_add_f32_dpp v150, v150, v150 quad_perm:[2,3,0,1] row_mask:0xf bank_mask:0xf bound_ctrl:1
	v_pk_mul_f32 v[156:157], v[68:69], v[136:137]
	v_pk_fma_f32 v[156:157], v[70:71], v[138:139], v[156:157]
	v_add_f32_dpp v150, v150, v150 row_half_mirror row_mask:0xf bank_mask:0xf bound_ctrl:1
	v_add_f32_e32 v159, v156, v157
	ds_read_b128 v[96:99], v198 offset:43264
	v_add_f32_dpp v150, v150, v150 row_mirror row_mask:0xf bank_mask:0xf bound_ctrl:1
	v_pk_fma_f32 v[72:73], v[116:117], v[150:151], v[152:153] op_sel_hi:[1,0,1]
	v_pk_fma_f32 v[74:75], v[118:119], v[150:151], v[154:155] op_sel_hi:[1,0,1]
	ds_read_b128 v[104:107], v198 offset:43776
	ds_read_b128 v[128:131], v204 offset:44288
	ds_read_b128 v[92:95], v198 offset:43008
	ds_read_b128 v[100:103], v198 offset:43520
	ds_read_b128 v[132:135], v198 offset:44032
	s_waitcnt lgkmcnt(6)
	v_pk_mul_f32 v[148:149], v[72:73], v[80:81]
	v_pk_fma_f32 v[148:149], v[74:75], v[82:83], v[148:149]
	v_add_f32_e32 v150, v148, v149
	v_pk_mul_f32 v[152:153], v[88:89], v[126:127] op_sel:[0,1] op_sel_hi:[1,1]
	v_pk_mul_f32 v[154:155], v[90:91], v[126:127] op_sel:[0,1] op_sel_hi:[1,1]
	v_add_f32_dpp v150, v150, v150 quad_perm:[1,0,3,2] row_mask:0xf bank_mask:0xf bound_ctrl:1
	v_pk_fma_f32 v[152:153], v[72:73], v[76:77], v[152:153]
	v_pk_fma_f32 v[154:155], v[74:75], v[78:79], v[154:155]
	v_add_f32_dpp v150, v150, v150 quad_perm:[2,3,0,1] row_mask:0xf bank_mask:0xf bound_ctrl:1
	v_pk_mul_f32 v[156:157], v[72:73], v[140:141]
	v_pk_fma_f32 v[156:157], v[74:75], v[142:143], v[156:157]
	v_add_f32_dpp v150, v150, v150 row_half_mirror row_mask:0xf bank_mask:0xf bound_ctrl:1
	v_add_f32_e32 v160, v156, v157
	ds_read_b128 v[112:115], v198 offset:44800
	v_add_f32_dpp v150, v150, v150 row_mirror row_mask:0xf bank_mask:0xf bound_ctrl:1
	v_pk_fma_f32 v[68:69], v[84:85], v[150:151], v[152:153] op_sel_hi:[1,0,1]
	v_pk_fma_f32 v[70:71], v[86:87], v[150:151], v[154:155] op_sel_hi:[1,0,1]
	ds_read_b128 v[120:123], v198 offset:45312
	ds_read_b128 v[108:111], v198 offset:44544
	ds_read_b128 v[116:119], v198 offset:45056
	ds_read_b128 v[136:139], v198 offset:45568
	s_waitcnt lgkmcnt(5)
; __device__ __forceinline__ void rwkv_scan(Frame& F, int wg, unsigned* shw, unsigned wait_target, int wait_blk) {
;     ...
;             RwOps R[4];
;             RW_LD(R[0], 0); RW_LD(R[1], 1); RW_LD(R[2], 2);
;             for (int s4 = 0; s4 < RW_TB; s4 += 4) {
;                 float pz[4], u[4];
; #pragma unroll
;                 for (int q = 0; q < 4; ++q) {
;                     RW_LD(R[(q + 3) & 3], s4 + q + 3);
;                     const RwOps& cur = R[q];
;                     const f32x2 slo = {st.x, st.y}, shi = {st.z, st.w};
;                     f32x2 ma = slo * (f32x2){cur.a.x, cur.a.y}; ma = __builtin_elementwise_fma(shi, (f32x2){cur.a.z, cur.a.w}, ma);
;                     f32x2 mz = slo * (f32x2){cur.wr.x, cur.wr.y}; mz = __builtin_elementwise_fma(shi, (f32x2){cur.wr.z, cur.wr.w}, mz);
;                     float psa = ma.x + ma.y; pz[q] = mz.x + mz.y;
;                     const f32x2 vb = {cur.vs.x, cur.vs.x};
;                     f32x2 tlo = (f32x2){cur.k.x, cur.k.y} * vb, thi = (f32x2){cur.k.z, cur.k.w} * vb;
;                     tlo = __builtin_elementwise_fma(slo, (f32x2){cur.w.x, cur.w.y}, tlo); thi = __builtin_elementwise_fma(shi, (f32x2){cur.w.z, cur.w.w}, thi);
;                     psa = red16(psa);
;                     const f32x2 pb = {psa, psa};
;                     tlo = __builtin_elementwise_fma((f32x2){cur.b.x, cur.b.y}, pb, tlo); thi = __builtin_elementwise_fma((f32x2){cur.b.z, cur.b.w}, pb, thi);
;                     st = (f32x4){tlo.x, tlo.y, thi.x, thi.y};
;                     u[q] = psa * cur.vs.z + cur.vs.y;
;                 }
;                 const float qa = (odd1 ? pz[1] : pz[0]) + dppf<0xB1>(odd1 ? pz[0] : pz[1]);
;                 const float qb = (odd1 ? pz[3] : pz[2]) + dppf<0xB1>(odd1 ? pz[2] : pz[3]);
;                 float r = (odd2 ? qb : qa) + dppf<0x4E>(odd2 ? qa : qb);
;                 r += dppf<0x124>(r); r += dppf<0x128>(r);
;                 const float us = odd2 ? (odd1 ? u[3] : u[2]) : (odd1 ? u[1] : u[0]);
;                 if (j < 4) { const int t = blk * RW_TB + s4 + j; ((float*)(Ub + (size_t)t * (PWP * 2) + URR * 2))[h * 64 + row] = r + us; }
	v_pk_mul_f32 v[148:149], v[68:69], v[96:97]
	v_pk_fma_f32 v[148:149], v[70:71], v[98:99], v[148:149]
	v_add_f32_e32 v150, v148, v149
	v_pk_mul_f32 v[152:153], v[104:105], v[128:129] op_sel_hi:[1,0]
	v_pk_mul_f32 v[154:155], v[106:107], v[128:129] op_sel_hi:[1,0]
	v_add_f32_dpp v150, v150, v150 quad_perm:[1,0,3,2] row_mask:0xf bank_mask:0xf bound_ctrl:1
	v_pk_fma_f32 v[152:153], v[68:69], v[92:93], v[152:153]
	v_pk_fma_f32 v[154:155], v[70:71], v[94:95], v[154:155]
	v_add_f32_dpp v150, v150, v150 quad_perm:[2,3,0,1] row_mask:0xf bank_mask:0xf bound_ctrl:1
	v_pk_mul_f32 v[156:157], v[68:69], v[144:145]
	v_pk_fma_f32 v[156:157], v[70:71], v[146:147], v[156:157]
	v_add_f32_dpp v150, v150, v150 row_half_mirror row_mask:0xf bank_mask:0xf bound_ctrl:1
	v_add_f32_e32 v161, v156, v157
	v_add_f32_dpp v162, v158, v158 row_ror:8 row_mask:0xf bank_mask:0xf
	v_add_f32_dpp v150, v150, v150 row_mirror row_mask:0xf bank_mask:0xf bound_ctrl:1
	v_pk_fma_f32 v[72:73], v[100:101], v[150:151], v[152:153] op_sel_hi:[1,0,1]
	v_pk_fma_f32 v[74:75], v[102:103], v[150:151], v[154:155] op_sel_hi:[1,0,1]
	v_add_f32_dpp v163, v159, v159 row_ror:8 row_mask:0xf bank_mask:0xf
	v_add_f32_dpp v162, v160, v160 row_ror:8 row_mask:0xf bank_mask:0xc
	v_add_f32_dpp v163, v161, v161 row_ror:8 row_mask:0xf bank_mask:0xc
	ds_read_b128 v[80:83], v198 offset:46336
	ds_read_b128 v[88:91], v198 offset:46848
	v_add_f32_dpp v164, v162, v162 row_half_mirror row_mask:0xf bank_mask:0xf
	v_add_f32_dpp v164, v163, v163 row_half_mirror row_mask:0xf bank_mask:0xa
	ds_read_b128 v[76:79], v198 offset:46080
	ds_read_b128 v[84:87], v198 offset:46592
	v_add_f32_dpp v164, v164, v164 quad_perm:[1,0,3,2] row_mask:0xf bank_mask:0xf bound_ctrl:1
	ds_read_b128 v[140:143], v198 offset:47104
	s_nop 0
	v_add_f32_dpp v164, v164, v164 quad_perm:[2,3,0,1] row_mask:0xf bank_mask:0xf bound_ctrl:1
	global_store_dword v165, v164, s[34:35]
	v_add_u32_e32 v165, 0xb000, v165
	s_waitcnt lgkmcnt(5)
	v_pk_mul_f32 v[148:149], v[72:73], v[112:113]
	v_pk_fma_f32 v[148:149], v[74:75], v[114:115], v[148:149]
	v_add_f32_e32 v150, v148, v149
	v_pk_mul_f32 v[152:153], v[120:121], v[128:129] op_sel:[0,1] op_sel_hi:[1,1]
	v_pk_mul_f32 v[154:155], v[122:123], v[128:129] op_sel:[0,1] op_sel_hi:[1,1]
	v_add_f32_dpp v150, v150, v150 quad_perm:[1,0,3,2] row_mask:0xf bank_mask:0xf bound_ctrl:1
	v_pk_fma_f32 v[152:153], v[72:73], v[108:109], v[152:153]
	v_pk_fma_f32 v[154:155], v[74:75], v[110:111], v[154:155]
	v_add_f32_dpp v150, v150, v150 quad_perm:[2,3,0,1] row_mask:0xf bank_mask:0xf bound_ctrl:1
	v_pk_mul_f32 v[156:157], v[72:73], v[132:133]
	v_pk_fma_f32 v[156:157], v[74:75], v[134:135], v[156:157]
	v_add_f32_dpp v150, v150, v150 row_half_mirror row_mask:0xf bank_mask:0xf bound_ctrl:1
	v_add_f32_e32 v158, v156, v157
	ds_read_b128 v[96:99], v198 offset:47872
	v_add_f32_dpp v150, v150, v150 row_mirror row_mask:0xf bank_mask:0xf bound_ctrl:1
	v_pk_fma_f32 v[68:69], v[116:117], v[150:151], v[152:153] op_sel_hi:[1,0,1]
	v_pk_fma_f32 v[70:71], v[118:119], v[150:151], v[154:155] op_sel_hi:[1,0,1]
	ds_read_b128 v[104:107], v198 offset:48384
	ds_read_b128 v[92:95], v198 offset:47616
	ds_read_b128 v[100:103], v198 offset:48128
	ds_read_b128 v[144:147], v198 offset:48640
	s_waitcnt lgkmcnt(5)
	v_pk_mul_f32 v[148:149], v[68:69], v[80:81]
	v_pk_fma_f32 v[148:149], v[70:71], v[82:83], v[148:149]
	v_add_f32_e32 v150, v148, v149
	v_pk_mul_f32 v[152:153], v[88:89], v[130:131] op_sel_hi:[1,0]
	v_pk_mul_f32 v[154:155], v[90:91], v[130:131] op_sel_hi:[1,0]
	v_add_f32_dpp v150, v150, v150 quad_perm:[1,0,3,2] row_mask:0xf bank_mask:0xf bound_ctrl:1
	v_pk_fma_f32 v[152:153], v[68:69], v[76:77], v[152:153]
	v_pk_fma_f32 v[154:155], v[70:71], v[78:79], v[154:155]
	v_add_f32_dpp v150, v150, v150 quad_perm:[2,3,0,1] row_mask:0xf bank_mask:0xf bound_ctrl:1
	v_pk_mul_f32 v[156:157], v[68:69], v[136:137]
	v_pk_fma_f32 v[156:157], v[70:71], v[138:139], v[156:157]
	v_add_f32_dpp v150, v150, v150 row_half_mirror row_mask:0xf bank_mask:0xf bound_ctrl:1
	v_add_f32_e32 v159, v156, v157
	s_nop 0
	v_add_f32_dpp v150, v150, v150 row_mirror row_mask:0xf bank_mask:0xf bound_ctrl:1
	v_pk_fma_f32 v[72:73], v[84:85], v[150:151], v[152:153] op_sel_hi:[1,0,1]
	v_pk_fma_f32 v[74:75], v[86:87], v[150:151], v[154:155] op_sel_hi:[1,0,1]
	s_waitcnt lgkmcnt(0)
	v_pk_mul_f32 v[148:149], v[72:73], v[96:97]
	v_pk_fma_f32 v[148:149], v[74:75], v[98:99], v[148:149]
	v_add_f32_e32 v150, v148, v149
	v_pk_mul_f32 v[152:153], v[104:105], v[130:131] op_sel:[0,1] op_sel_hi:[1,1]
	v_pk_mul_f32 v[154:155], v[106:107], v[130:131] op_sel:[0,1] op_sel_hi:[1,1]
	v_add_f32_dpp v150, v150, v150 quad_perm:[1,0,3,2] row_mask:0xf bank_mask:0xf bound_ctrl:1
	v_pk_fma_f32 v[152:153], v[72:73], v[92:93], v[152:153]
	v_pk_fma_f32 v[154:155], v[74:75], v[94:95], v[154:155]
	v_add_f32_dpp v150, v150, v150 quad_perm:[2,3,0,1] row_mask:0xf bank_mask:0xf bound_ctrl:1
	v_pk_mul_f32 v[156:157], v[72:73], v[140:141]
	v_pk_fma_f32 v[156:157], v[74:75], v[142:143], v[156:157]
	v_add_f32_dpp v150, v150, v150 row_half_mirror row_mask:0xf bank_mask:0xf bound_ctrl:1
	v_add_f32_e32 v160, v156, v157
	s_nop 0
	v_add_f32_dpp v150, v150, v150 row_mirror row_mask:0xf bank_mask:0xf bound_ctrl:1
	v_pk_fma_f32 v[68:69], v[100:101], v[150:151], v[152:153] op_sel_hi:[1,0,1]
	v_pk_fma_f32 v[70:71], v[102:103], v[150:151], v[154:155] op_sel_hi:[1,0,1]
	v_pk_mul_f32 v[156:157], v[68:69], v[144:145]
	v_pk_fma_f32 v[156:157], v[70:71], v[146:147], v[156:157]
	v_add_f32_e32 v161, v156, v157
	v_add_f32_dpp v162, v158, v158 row_ror:8 row_mask:0xf bank_mask:0xf
	v_add_f32_dpp v163, v159, v159 row_ror:8 row_mask:0xf bank_mask:0xf
	v_add_f32_dpp v162, v160, v160 row_ror:8 row_mask:0xf bank_mask:0xc
	v_add_f32_dpp v163, v161, v161 row_ror:8 row_mask:0xf bank_mask:0xc
	s_nop 0
	s_nop 0
	v_add_f32_dpp v164, v162, v162 row_half_mirror row_mask:0xf bank_mask:0xf
	v_add_f32_dpp v164, v163, v163 row_half_mirror row_mask:0xf bank_mask:0xa
	s_nop 0
	s_nop 0
	v_add_f32_dpp v164, v164, v164 quad_perm:[1,0,3,2] row_mask:0xf bank_mask:0xf bound_ctrl:1
	s_nop 0
	s_nop 0
	v_add_f32_dpp v164, v164, v164 quad_perm:[2,3,0,1] row_mask:0xf bank_mask:0xf bound_ctrl:1
	global_store_dword v165, v164, s[34:35]
	v_add_u32_e32 v165, 0xb000, v165
	s_branch .LBB0_891

; __device__ __forceinline__ void rwkv_scan(Frame& F, int wg, unsigned* shw, unsigned wait_target, int wait_blk) {
;     ...
;     auto scan_block = [&](int blk) {
;             const LAS float* rb = buf + ((blk & 1) * RW_TB) * RW_REC + 4 * j;
;             const LAS float* rv_ = buf + ((blk & 1) * RW_TB) * RW_REC + 320 + (4 * F.wave + rg) * 4;
;     ...
;             RwOps R[4];
;             RW_LD(R[0], 0); RW_LD(R[1], 1); RW_LD(R[2], 2);
;             for (int s4 = 0; s4 < RW_TB; s4 += 4) {
;                 float pz[4], u[4];
; #pragma unroll
;                 for (int q = 0; q < 4; ++q) {
;                     RW_LD(R[(q + 3) & 3], s4 + q + 3);
;                     const RwOps& cur = R[q];
;                     const f32x2 slo = {st.x, st.y}, shi = {st.z, st.w};
;                     f32x2 ma = slo * (f32x2){cur.a.x, cur.a.y}; ma = __builtin_elementwise_fma(shi, (f32x2){cur.a.z, cur.a.w}, ma);
;                     f32x2 mz = slo * (f32x2){cur.wr.x, cur.wr.y}; mz = __builtin_elementwise_fma(shi, (f32x2){cur.wr.z, cur.wr.w}, mz);
;                     float psa = ma.x + ma.y; pz[q] = mz.x + mz.y;
;                     const f32x2 vb = {cur.vs.x, cur.vs.x};
;                     f32x2 tlo = (f32x2){cur.k.x, cur.k.y} * vb, thi = (f32x2){cur.k.z, cur.k.w} * vb;
;                     tlo = __builtin_elementwise_fma(slo, (f32x2){cur.w.x, cur.w.y}, tlo); thi = __builtin_elementwise_fma(shi, (f32x2){cur.w.z, cur.w.w}, thi);
;                     psa = red16(psa);
;                     const f32x2 pb = {psa, psa};
;                     tlo = __builtin_elementwise_fma((f32x2){cur.b.x, cur.b.y}, pb, tlo); thi = __builtin_elementwise_fma((f32x2){cur.b.z, cur.b.w}, pb, thi);
;                     st = (f32x4){tlo.x, tlo.y, thi.x, thi.y};
;                     u[q] = psa * cur.vs.z + cur.vs.y;
;                 }
;                 const float qa = (odd1 ? pz[1] : pz[0]) + dppf<0xB1>(odd1 ? pz[0] : pz[1]);
;                 const float qb = (odd1 ? pz[3] : pz[2]) + dppf<0xB1>(odd1 ? pz[2] : pz[3]);
;                 float r = (odd2 ? qb : qa) + dppf<0x4E>(odd2 ? qa : qb);
;                 r += dppf<0x124>(r); r += dppf<0x128>(r);
;                 const float us = odd2 ? (odd1 ? u[3] : u[2]) : (odd1 ? u[1] : u[0]);
;                 if (j < 4) { const int t = blk * RW_TB + s4 + j; ((float*)(Ub + (size_t)t * (PWP * 2) + URR * 2))[h * 64 + row] = r + us; }
.LBB0_891:
	s_mov_b64 s[50:51], -1
	s_and_b64 vcc, exec, s[26:27]
	s_waitcnt lgkmcnt(0)
	s_barrier
	s_cbranch_vccz .LBB0_909
	s_mul_i32 s50, s59, 0x58000
	s_add_i32 s50, s50, 0x58000
	ds_read_b128 v[80:83], v202 offset:256
	ds_read_b128 v[88:91], v202 offset:768
	ds_read_b128 v[124:127], v206 offset:0
	ds_read_b128 v[76:79], v202 offset:0
	ds_read_b128 v[84:87], v202 offset:512
	ds_read_b128 v[132:135], v202 offset:1024
	ds_read_b128 v[96:99], v202 offset:1792
	ds_read_b128 v[104:107], v202 offset:2304
	ds_read_b128 v[92:95], v202 offset:1536
	ds_read_b128 v[100:103], v202 offset:2048
	ds_read_b128 v[136:139], v202 offset:2560
	v_lshrrev_b32_e32 v165, 2, v194
	v_mul_u32_u24_e32 v165, 0x2c00, v165
	v_lshl_add_u32 v165, v186, 2, v165
	v_add_u32_e32 v165, s50, v165
	s_waitcnt lgkmcnt(5)
	v_pk_mul_f32 v[148:149], v[68:69], v[80:81]
	v_pk_fma_f32 v[148:149], v[70:71], v[82:83], v[148:149]
	v_add_f32_e32 v150, v148, v149
	v_pk_mul_f32 v[152:153], v[88:89], v[124:125] op_sel_hi:[1,0]
	v_pk_mul_f32 v[154:155], v[90:91], v[124:125] op_sel_hi:[1,0]
	v_add_f32_dpp v150, v150, v150 quad_perm:[1,0,3,2] row_mask:0xf bank_mask:0xf bound_ctrl:1
	v_pk_fma_f32 v[152:153], v[68:69], v[76:77], v[152:153]
	v_pk_fma_f32 v[154:155], v[70:71], v[78:79], v[154:155]
	v_add_f32_dpp v150, v150, v150 quad_perm:[2,3,0,1] row_mask:0xf bank_mask:0xf bound_ctrl:1
	ds_read_b128 v[112:115], v202 offset:3328
	ds_read_b128 v[120:123], v202 offset:3840
	v_add_f32_dpp v150, v150, v150 row_half_mirror row_mask:0xf bank_mask:0xf bound_ctrl:1
	ds_read_b128 v[108:111], v202 offset:3072
	ds_read_b128 v[116:119], v202 offset:3584
	v_add_f32_dpp v150, v150, v150 row_mirror row_mask:0xf bank_mask:0xf bound_ctrl:1
	v_pk_fma_f32 v[72:73], v[84:85], v[150:151], v[152:153] op_sel_hi:[1,0,1]
	v_pk_fma_f32 v[74:75], v[86:87], v[150:151], v[154:155] op_sel_hi:[1,0,1]
	ds_read_b128 v[140:143], v202 offset:4096
	s_waitcnt lgkmcnt(5)
	v_pk_mul_f32 v[148:149], v[72:73], v[96:97]
	v_pk_fma_f32 v[148:149], v[74:75], v[98:99], v[148:149]
	v_add_f32_e32 v150, v148, v149
	v_pk_mul_f32 v[152:153], v[104:105], v[124:125] op_sel:[0,1] op_sel_hi:[1,1]
	v_pk_mul_f32 v[154:155], v[106:107], v[124:125] op_sel:[0,1] op_sel_hi:[1,1]
	v_add_f32_dpp v150, v150, v150 quad_perm:[1,0,3,2] row_mask:0xf bank_mask:0xf bound_ctrl:1
	v_pk_fma_f32 v[152:153], v[72:73], v[92:93], v[152:153]
	v_pk_fma_f32 v[154:155], v[74:75], v[94:95], v[154:155]
	v_add_f32_dpp v150, v150, v150 quad_perm:[2,3,0,1] row_mask:0xf bank_mask:0xf bound_ctrl:1
	v_pk_mul_f32 v[156:157], v[72:73], v[132:133]
	v_pk_fma_f32 v[156:157], v[74:75], v[134:135], v[156:157]
	v_add_f32_dpp v150, v150, v150 row_half_mirror row_mask:0xf bank_mask:0xf bound_ctrl:1
	v_add_f32_e32 v158, v156, v157
	ds_read_b128 v[80:83], v202 offset:4864
	v_add_f32_dpp v150, v150, v150 row_mirror row_mask:0xf bank_mask:0xf bound_ctrl:1
	v_pk_fma_f32 v[68:69], v[100:101], v[150:151], v[152:153] op_sel_hi:[1,0,1]
	v_pk_fma_f32 v[70:71], v[102:103], v[150:151], v[154:155] op_sel_hi:[1,0,1]
	ds_read_b128 v[88:91], v202 offset:5376
	ds_read_b128 v[76:79], v202 offset:4608
	ds_read_b128 v[84:87], v202 offset:5120
	ds_read_b128 v[144:147], v202 offset:5632
	s_waitcnt lgkmcnt(5)
	v_pk_mul_f32 v[148:149], v[68:69], v[112:113]
	v_pk_fma_f32 v[148:149], v[70:71], v[114:115], v[148:149]
	v_add_f32_e32 v150, v148, v149
	v_pk_mul_f32 v[152:153], v[120:121], v[126:127] op_sel_hi:[1,0]
	v_pk_mul_f32 v[154:155], v[122:123], v[126:127] op_sel_hi:[1,0]
	v_add_f32_dpp v150, v150, v150 quad_perm:[1,0,3,2] row_mask:0xf bank_mask:0xf bound_ctrl:1
	v_pk_fma_f32 v[152:153], v[68:69], v[108:109], v[152:153]
	v_pk_fma_f32 v[154:155], v[70:71], v[110:111], v[154:155]
	v_add_f32_dpp v150, v150, v150 quad_perm:[2,3,0,1] row_mask:0xf bank_mask:0xf bound_ctrl:1
	v_pk_mul_f32 v[156:157], v[68:69], v[136:137]
	v_pk_fma_f32 v[156:157], v[70:71], v[138:139], v[156:157]
	v_add_f32_dpp v150, v150, v150 row_half_mirror row_mask:0xf bank_mask:0xf bound_ctrl:1
	v_add_f32_e32 v159, v156, v157
	ds_read_b128 v[96:99], v202 offset:6400
	v_add_f32_dpp v150, v150, v150 row_mirror row_mask:0xf bank_mask:0xf bound_ctrl:1
	v_pk_fma_f32 v[72:73], v[116:117], v[150:151], v[152:153] op_sel_hi:[1,0,1]
	v_pk_fma_f32 v[74:75], v[118:119], v[150:151], v[154:155] op_sel_hi:[1,0,1]
	ds_read_b128 v[104:107], v202 offset:6912
	ds_read_b128 v[128:131], v206 offset:6144
	ds_read_b128 v[92:95], v202 offset:6144
	ds_read_b128 v[100:103], v202 offset:6656
	ds_read_b128 v[132:135], v202 offset:7168
	s_waitcnt lgkmcnt(6)
	v_pk_mul_f32 v[148:149], v[72:73], v[80:81]
	v_pk_fma_f32 v[148:149], v[74:75], v[82:83], v[148:149]
	v_add_f32_e32 v150, v148, v149
	v_pk_mul_f32 v[152:153], v[88:89], v[126:127] op_sel:[0,1] op_sel_hi:[1,1]
	v_pk_mul_f32 v[154:155], v[90:91], v[126:127] op_sel:[0,1] op_sel_hi:[1,1]
	v_add_f32_dpp v150, v150, v150 quad_perm:[1,0,3,2] row_mask:0xf bank_mask:0xf bound_ctrl:1
	v_pk_fma_f32 v[152:153], v[72:73], v[76:77], v[152:153]
	v_pk_fma_f32 v[154:155], v[74:75], v[78:79], v[154:155]
	v_add_f32_dpp v150, v150, v150 quad_perm:[2,3,0,1] row_mask:0xf bank_mask:0xf bound_ctrl:1
	v_pk_mul_f32 v[156:157], v[72:73], v[140:141]
	v_pk_fma_f32 v[156:157], v[74:75], v[142:143], v[156:157]
	v_add_f32_dpp v150, v150, v150 row_half_mirror row_mask:0xf bank_mask:0xf bound_ctrl:1
	v_add_f32_e32 v160, v156, v157
	ds_read_b128 v[112:115], v202 offset:7936
	v_add_f32_dpp v150, v150, v150 row_mirror row_mask:0xf bank_mask:0xf bound_ctrl:1
	v_pk_fma_f32 v[68:69], v[84:85], v[150:151], v[152:153] op_sel_hi:[1,0,1]
	v_pk_fma_f32 v[70:71], v[86:87], v[150:151], v[154:155] op_sel_hi:[1,0,1]
	ds_read_b128 v[120:123], v202 offset:8448
	ds_read_b128 v[108:111], v202 offset:7680
	ds_read_b128 v[116:119], v202 offset:8192
	ds_read_b128 v[136:139], v202 offset:8704
	s_waitcnt lgkmcnt(5)
; __device__ __forceinline__ void rwkv_scan(Frame& F, int wg, unsigned* shw, unsigned wait_target, int wait_blk) {
;     ...
;             RwOps R[4];
;             RW_LD(R[0], 0); RW_LD(R[1], 1); RW_LD(R[2], 2);
;             for (int s4 = 0; s4 < RW_TB; s4 += 4) {
;                 float pz[4], u[4];
; #pragma unroll
;                 for (int q = 0; q < 4; ++q) {
;                     RW_LD(R[(q + 3) & 3], s4 + q + 3);
;                     const RwOps& cur = R[q];
;                     const f32x2 slo = {st.x, st.y}, shi = {st.z, st.w};
;                     f32x2 ma = slo * (f32x2){cur.a.x, cur.a.y}; ma = __builtin_elementwise_fma(shi, (f32x2){cur.a.z, cur.a.w}, ma);
;                     f32x2 mz = slo * (f32x2){cur.wr.x, cur.wr.y}; mz = __builtin_elementwise_fma(shi, (f32x2){cur.wr.z, cur.wr.w}, mz);
;                     float psa = ma.x + ma.y; pz[q] = mz.x + mz.y;
;                     const f32x2 vb = {cur.vs.x, cur.vs.x};
;                     f32x2 tlo = (f32x2){cur.k.x, cur.k.y} * vb, thi = (f32x2){cur.k.z, cur.k.w} * vb;
;                     tlo = __builtin_elementwise_fma(slo, (f32x2){cur.w.x, cur.w.y}, tlo); thi = __builtin_elementwise_fma(shi, (f32x2){cur.w.z, cur.w.w}, thi);
;                     psa = red16(psa);
;                     const f32x2 pb = {psa, psa};
;                     tlo = __builtin_elementwise_fma((f32x2){cur.b.x, cur.b.y}, pb, tlo); thi = __builtin_elementwise_fma((f32x2){cur.b.z, cur.b.w}, pb, thi);
;                     st = (f32x4){tlo.x, tlo.y, thi.x, thi.y};
;                     u[q] = psa * cur.vs.z + cur.vs.y;
;                 }
;                 const float qa = (odd1 ? pz[1] : pz[0]) + dppf<0xB1>(odd1 ? pz[0] : pz[1]);
;                 const float qb = (odd1 ? pz[3] : pz[2]) + dppf<0xB1>(odd1 ? pz[2] : pz[3]);
;                 float r = (odd2 ? qb : qa) + dppf<0x4E>(odd2 ? qa : qb);
;                 r += dppf<0x124>(r); r += dppf<0x128>(r);
;                 const float us = odd2 ? (odd1 ? u[3] : u[2]) : (odd1 ? u[1] : u[0]);
;                 if (j < 4) { const int t = blk * RW_TB + s4 + j; ((float*)(Ub + (size_t)t * (PWP * 2) + URR * 2))[h * 64 + row] = r + us; }
	v_pk_mul_f32 v[148:149], v[68:69], v[96:97]
	v_pk_fma_f32 v[148:149], v[70:71], v[98:99], v[148:149]
	v_add_f32_e32 v150, v148, v149
	v_pk_mul_f32 v[152:153], v[104:105], v[128:129] op_sel_hi:[1,0]
	v_pk_mul_f32 v[154:155], v[106:107], v[128:129] op_sel_hi:[1,0]
	v_add_f32_dpp v150, v150, v150 quad_perm:[1,0,3,2] row_mask:0xf bank_mask:0xf bound_ctrl:1
	v_pk_fma_f32 v[152:153], v[68:69], v[92:93], v[152:153]
	v_pk_fma_f32 v[154:155], v[70:71], v[94:95], v[154:155]
	v_add_f32_dpp v150, v150, v150 quad_perm:[2,3,0,1] row_mask:0xf bank_mask:0xf bound_ctrl:1
	v_pk_mul_f32 v[156:157], v[68:69], v[144:145]
	v_pk_fma_f32 v[156:157], v[70:71], v[146:147], v[156:157]
	v_add_f32_dpp v150, v150, v150 row_half_mirror row_mask:0xf bank_mask:0xf bound_ctrl:1
	v_add_f32_e32 v161, v156, v157
	v_add_f32_dpp v162, v158, v158 row_ror:8 row_mask:0xf bank_mask:0xf
	v_add_f32_dpp v150, v150, v150 row_mirror row_mask:0xf bank_mask:0xf bound_ctrl:1
	v_pk_fma_f32 v[72:73], v[100:101], v[150:151], v[152:153] op_sel_hi:[1,0,1]
	v_pk_fma_f32 v[74:75], v[102:103], v[150:151], v[154:155] op_sel_hi:[1,0,1]
	v_add_f32_dpp v163, v159, v159 row_ror:8 row_mask:0xf bank_mask:0xf
	v_add_f32_dpp v162, v160, v160 row_ror:8 row_mask:0xf bank_mask:0xc
	v_add_f32_dpp v163, v161, v161 row_ror:8 row_mask:0xf bank_mask:0xc
	ds_read_b128 v[80:83], v202 offset:9472
	ds_read_b128 v[88:91], v202 offset:9984
	v_add_f32_dpp v164, v162, v162 row_half_mirror row_mask:0xf bank_mask:0xf
	v_add_f32_dpp v164, v163, v163 row_half_mirror row_mask:0xf bank_mask:0xa
	ds_read_b128 v[76:79], v202 offset:9216
	ds_read_b128 v[84:87], v202 offset:9728
	v_add_f32_dpp v164, v164, v164 quad_perm:[1,0,3,2] row_mask:0xf bank_mask:0xf bound_ctrl:1
	ds_read_b128 v[140:143], v202 offset:10240
	s_nop 0
	v_add_f32_dpp v164, v164, v164 quad_perm:[2,3,0,1] row_mask:0xf bank_mask:0xf bound_ctrl:1
	global_store_dword v165, v164, s[34:35]
	v_add_u32_e32 v165, 0xb000, v165
	s_waitcnt lgkmcnt(5)
	v_pk_mul_f32 v[148:149], v[72:73], v[112:113]
	v_pk_fma_f32 v[148:149], v[74:75], v[114:115], v[148:149]
	v_add_f32_e32 v150, v148, v149
	v_pk_mul_f32 v[152:153], v[120:121], v[128:129] op_sel:[0,1] op_sel_hi:[1,1]
	v_pk_mul_f32 v[154:155], v[122:123], v[128:129] op_sel:[0,1] op_sel_hi:[1,1]
	v_add_f32_dpp v150, v150, v150 quad_perm:[1,0,3,2] row_mask:0xf bank_mask:0xf bound_ctrl:1
	v_pk_fma_f32 v[152:153], v[72:73], v[108:109], v[152:153]
	v_pk_fma_f32 v[154:155], v[74:75], v[110:111], v[154:155]
	v_add_f32_dpp v150, v150, v150 quad_perm:[2,3,0,1] row_mask:0xf bank_mask:0xf bound_ctrl:1
	v_pk_mul_f32 v[156:157], v[72:73], v[132:133]
	v_pk_fma_f32 v[156:157], v[74:75], v[134:135], v[156:157]
	v_add_f32_dpp v150, v150, v150 row_half_mirror row_mask:0xf bank_mask:0xf bound_ctrl:1
	v_add_f32_e32 v158, v156, v157
	ds_read_b128 v[96:99], v202 offset:11008
	v_add_f32_dpp v150, v150, v150 row_mirror row_mask:0xf bank_mask:0xf bound_ctrl:1
	v_pk_fma_f32 v[68:69], v[116:117], v[150:151], v[152:153] op_sel_hi:[1,0,1]
	v_pk_fma_f32 v[70:71], v[118:119], v[150:151], v[154:155] op_sel_hi:[1,0,1]
	ds_read_b128 v[104:107], v202 offset:11520
	ds_read_b128 v[92:95], v202 offset:10752
	ds_read_b128 v[100:103], v202 offset:11264
	ds_read_b128 v[144:147], v202 offset:11776
	s_waitcnt lgkmcnt(5)
	v_pk_mul_f32 v[148:149], v[68:69], v[80:81]
	v_pk_fma_f32 v[148:149], v[70:71], v[82:83], v[148:149]
	v_add_f32_e32 v150, v148, v149
	v_pk_mul_f32 v[152:153], v[88:89], v[130:131] op_sel_hi:[1,0]
	v_pk_mul_f32 v[154:155], v[90:91], v[130:131] op_sel_hi:[1,0]
	v_add_f32_dpp v150, v150, v150 quad_perm:[1,0,3,2] row_mask:0xf bank_mask:0xf bound_ctrl:1
	v_pk_fma_f32 v[152:153], v[68:69], v[76:77], v[152:153]
	v_pk_fma_f32 v[154:155], v[70:71], v[78:79], v[154:155]
	v_add_f32_dpp v150, v150, v150 quad_perm:[2,3,0,1] row_mask:0xf bank_mask:0xf bound_ctrl:1
	v_pk_mul_f32 v[156:157], v[68:69], v[136:137]
	v_pk_fma_f32 v[156:157], v[70:71], v[138:139], v[156:157]
	v_add_f32_dpp v150, v150, v150 row_half_mirror row_mask:0xf bank_mask:0xf bound_ctrl:1
	v_add_f32_e32 v159, v156, v157
	ds_read_b128 v[112:115], v202 offset:12544
	v_add_f32_dpp v150, v150, v150 row_mirror row_mask:0xf bank_mask:0xf bound_ctrl:1
	v_pk_fma_f32 v[72:73], v[84:85], v[150:151], v[152:153] op_sel_hi:[1,0,1]
	v_pk_fma_f32 v[74:75], v[86:87], v[150:151], v[154:155] op_sel_hi:[1,0,1]
	ds_read_b128 v[120:123], v202 offset:13056
	ds_read_b128 v[124:127], v206 offset:12288
	ds_read_b128 v[108:111], v202 offset:12288
	ds_read_b128 v[116:119], v202 offset:12800
	ds_read_b128 v[132:135], v202 offset:13312
	s_waitcnt lgkmcnt(6)
	v_pk_mul_f32 v[148:149], v[72:73], v[96:97]
	v_pk_fma_f32 v[148:149], v[74:75], v[98:99], v[148:149]
	v_add_f32_e32 v150, v148, v149
	v_pk_mul_f32 v[152:153], v[104:105], v[130:131] op_sel:[0,1] op_sel_hi:[1,1]
	v_pk_mul_f32 v[154:155], v[106:107], v[130:131] op_sel:[0,1] op_sel_hi:[1,1]
	v_add_f32_dpp v150, v150, v150 quad_perm:[1,0,3,2] row_mask:0xf bank_mask:0xf bound_ctrl:1
	v_pk_fma_f32 v[152:153], v[72:73], v[92:93], v[152:153]
	v_pk_fma_f32 v[154:155], v[74:75], v[94:95], v[154:155]
	v_add_f32_dpp v150, v150, v150 quad_perm:[2,3,0,1] row_mask:0xf bank_mask:0xf bound_ctrl:1
	v_pk_mul_f32 v[156:157], v[72:73], v[140:141]
	v_pk_fma_f32 v[156:157], v[74:75], v[142:143], v[156:157]
	v_add_f32_dpp v150, v150, v150 row_half_mirror row_mask:0xf bank_mask:0xf bound_ctrl:1
	v_add_f32_e32 v160, v156, v157
	ds_read_b128 v[80:83], v202 offset:14080
	v_add_f32_dpp v150, v150, v150 row_mirror row_mask:0xf bank_mask:0xf bound_ctrl:1
	v_pk_fma_f32 v[68:69], v[100:101], v[150:151], v[152:153] op_sel_hi:[1,0,1]
	v_pk_fma_f32 v[70:71], v[102:103], v[150:151], v[154:155] op_sel_hi:[1,0,1]
	ds_read_b128 v[88:91], v202 offset:14592
	ds_read_b128 v[76:79], v202 offset:13824
	ds_read_b128 v[84:87], v202 offset:14336
	ds_read_b128 v[136:139], v202 offset:14848
	s_waitcnt lgkmcnt(5)
; __device__ __forceinline__ void rwkv_scan(Frame& F, int wg, unsigned* shw, unsigned wait_target, int wait_blk) {
;     ...
;             RwOps R[4];
;             RW_LD(R[0], 0); RW_LD(R[1], 1); RW_LD(R[2], 2);
;             for (int s4 = 0; s4 < RW_TB; s4 += 4) {
;                 float pz[4], u[4];
; #pragma unroll
;                 for (int q = 0; q < 4; ++q) {
;                     RW_LD(R[(q + 3) & 3], s4 + q + 3);
;                     const RwOps& cur = R[q];
;                     const f32x2 slo = {st.x, st.y}, shi = {st.z, st.w};
;                     f32x2 ma = slo * (f32x2){cur.a.x, cur.a.y}; ma = __builtin_elementwise_fma(shi, (f32x2){cur.a.z, cur.a.w}, ma);
;                     f32x2 mz = slo * (f32x2){cur.wr.x, cur.wr.y}; mz = __builtin_elementwise_fma(shi, (f32x2){cur.wr.z, cur.wr.w}, mz);
;                     float psa = ma.x + ma.y; pz[q] = mz.x + mz.y;
;                     const f32x2 vb = {cur.vs.x, cur.vs.x};
;                     f32x2 tlo = (f32x2){cur.k.x, cur.k.y} * vb, thi = (f32x2){cur.k.z, cur.k.w} * vb;
;                     tlo = __builtin_elementwise_fma(slo, (f32x2){cur.w.x, cur.w.y}, tlo); thi = __builtin_elementwise_fma(shi, (f32x2){cur.w.z, cur.w.w}, thi);
;                     psa = red16(psa);
;                     const f32x2 pb = {psa, psa};
;                     tlo = __builtin_elementwise_fma((f32x2){cur.b.x, cur.b.y}, pb, tlo); thi = __builtin_elementwise_fma((f32x2){cur.b.z, cur.b.w}, pb, thi);
;                     st = (f32x4){tlo.x, tlo.y, thi.x, thi.y};
;                     u[q] = psa * cur.vs.z + cur.vs.y;
;                 }
;                 const float qa = (odd1 ? pz[1] : pz[0]) + dppf<0xB1>(odd1 ? pz[0] : pz[1]);
;                 const float qb = (odd1 ? pz[3] : pz[2]) + dppf<0xB1>(odd1 ? pz[2] : pz[3]);
;                 float r = (odd2 ? qb : qa) + dppf<0x4E>(odd2 ? qa : qb);
;                 r += dppf<0x124>(r); r += dppf<0x128>(r);
;                 const float us = odd2 ? (odd1 ? u[3] : u[2]) : (odd1 ? u[1] : u[0]);
;                 if (j < 4) { const int t = blk * RW_TB + s4 + j; ((float*)(Ub + (size_t)t * (PWP * 2) + URR * 2))[h * 64 + row] = r + us; }
	v_pk_mul_f32 v[148:149], v[68:69], v[112:113]
	v_pk_fma_f32 v[148:149], v[70:71], v[114:115], v[148:149]
	v_add_f32_e32 v150, v148, v149
	v_pk_mul_f32 v[152:153], v[120:121], v[124:125] op_sel_hi:[1,0]
	v_pk_mul_f32 v[154:155], v[122:123], v[124:125] op_sel_hi:[1,0]
	v_add_f32_dpp v150, v150, v150 quad_perm:[1,0,3,2] row_mask:0xf bank_mask:0xf bound_ctrl:1
	v_pk_fma_f32 v[152:153], v[68:69], v[108:109], v[152:153]
	v_pk_fma_f32 v[154:155], v[70:71], v[110:111], v[154:155]
	v_add_f32_dpp v150, v150, v150 quad_perm:[2,3,0,1] row_mask:0xf bank_mask:0xf bound_ctrl:1
	v_pk_mul_f32 v[156:157], v[68:69], v[144:145]
	v_pk_fma_f32 v[156:157], v[70:71], v[146:147], v[156:157]
	v_add_f32_dpp v150, v150, v150 row_half_mirror row_mask:0xf bank_mask:0xf bound_ctrl:1
	v_add_f32_e32 v161, v156, v157
	v_add_f32_dpp v162, v158, v158 row_ror:8 row_mask:0xf bank_mask:0xf
	v_add_f32_dpp v150, v150, v150 row_mirror row_mask:0xf bank_mask:0xf bound_ctrl:1
	v_pk_fma_f32 v[72:73], v[116:117], v[150:151], v[152:153] op_sel_hi:[1,0,1]
	v_pk_fma_f32 v[74:75], v[118:119], v[150:151], v[154:155] op_sel_hi:[1,0,1]
	v_add_f32_dpp v163, v159, v159 row_ror:8 row_mask:0xf bank_mask:0xf
	v_add_f32_dpp v162, v160, v160 row_ror:8 row_mask:0xf bank_mask:0xc
	v_add_f32_dpp v163, v161, v161 row_ror:8 row_mask:0xf bank_mask:0xc
	ds_read_b128 v[96:99], v202 offset:15616
	ds_read_b128 v[104:107], v202 offset:16128
	v_add_f32_dpp v164, v162, v162 row_half_mirror row_mask:0xf bank_mask:0xf
	v_add_f32_dpp v164, v163, v163 row_half_mirror row_mask:0xf bank_mask:0xa
	ds_read_b128 v[92:95], v202 offset:15360
	ds_read_b128 v[100:103], v202 offset:15872
	v_add_f32_dpp v164, v164, v164 quad_perm:[1,0,3,2] row_mask:0xf bank_mask:0xf bound_ctrl:1
	ds_read_b128 v[140:143], v202 offset:16384
	s_nop 0
	v_add_f32_dpp v164, v164, v164 quad_perm:[2,3,0,1] row_mask:0xf bank_mask:0xf bound_ctrl:1
	global_store_dword v165, v164, s[34:35]
	v_add_u32_e32 v165, 0xb000, v165
	s_waitcnt lgkmcnt(5)
	v_pk_mul_f32 v[148:149], v[72:73], v[80:81]
	v_pk_fma_f32 v[148:149], v[74:75], v[82:83], v[148:149]
	v_add_f32_e32 v150, v148, v149
	v_pk_mul_f32 v[152:153], v[88:89], v[124:125] op_sel:[0,1] op_sel_hi:[1,1]
	v_pk_mul_f32 v[154:155], v[90:91], v[124:125] op_sel:[0,1] op_sel_hi:[1,1]
	v_add_f32_dpp v150, v150, v150 quad_perm:[1,0,3,2] row_mask:0xf bank_mask:0xf bound_ctrl:1
	v_pk_fma_f32 v[152:153], v[72:73], v[76:77], v[152:153]
	v_pk_fma_f32 v[154:155], v[74:75], v[78:79], v[154:155]
	v_add_f32_dpp v150, v150, v150 quad_perm:[2,3,0,1] row_mask:0xf bank_mask:0xf bound_ctrl:1
	v_pk_mul_f32 v[156:157], v[72:73], v[132:133]
	v_pk_fma_f32 v[156:157], v[74:75], v[134:135], v[156:157]
	v_add_f32_dpp v150, v150, v150 row_half_mirror row_mask:0xf bank_mask:0xf bound_ctrl:1
	v_add_f32_e32 v158, v156, v157
	ds_read_b128 v[112:115], v202 offset:17152
	v_add_f32_dpp v150, v150, v150 row_mirror row_mask:0xf bank_mask:0xf bound_ctrl:1
	v_pk_fma_f32 v[68:69], v[84:85], v[150:151], v[152:153] op_sel_hi:[1,0,1]
	v_pk_fma_f32 v[70:71], v[86:87], v[150:151], v[154:155] op_sel_hi:[1,0,1]
	ds_read_b128 v[120:123], v202 offset:17664
	ds_read_b128 v[108:111], v202 offset:16896
	ds_read_b128 v[116:119], v202 offset:17408
	ds_read_b128 v[144:147], v202 offset:17920
	s_waitcnt lgkmcnt(5)
	v_pk_mul_f32 v[148:149], v[68:69], v[96:97]
	v_pk_fma_f32 v[148:149], v[70:71], v[98:99], v[148:149]
	v_add_f32_e32 v150, v148, v149
	v_pk_mul_f32 v[152:153], v[104:105], v[126:127] op_sel_hi:[1,0]
	v_pk_mul_f32 v[154:155], v[106:107], v[126:127] op_sel_hi:[1,0]
	v_add_f32_dpp v150, v150, v150 quad_perm:[1,0,3,2] row_mask:0xf bank_mask:0xf bound_ctrl:1
	v_pk_fma_f32 v[152:153], v[68:69], v[92:93], v[152:153]
	v_pk_fma_f32 v[154:155], v[70:71], v[94:95], v[154:155]
	v_add_f32_dpp v150, v150, v150 quad_perm:[2,3,0,1] row_mask:0xf bank_mask:0xf bound_ctrl:1
	v_pk_mul_f32 v[156:157], v[68:69], v[136:137]
	v_pk_fma_f32 v[156:157], v[70:71], v[138:139], v[156:157]
	v_add_f32_dpp v150, v150, v150 row_half_mirror row_mask:0xf bank_mask:0xf bound_ctrl:1
	v_add_f32_e32 v159, v156, v157
	ds_read_b128 v[80:83], v202 offset:18688
	v_add_f32_dpp v150, v150, v150 row_mirror row_mask:0xf bank_mask:0xf bound_ctrl:1
	v_pk_fma_f32 v[72:73], v[100:101], v[150:151], v[152:153] op_sel_hi:[1,0,1]
	v_pk_fma_f32 v[74:75], v[102:103], v[150:151], v[154:155] op_sel_hi:[1,0,1]
	ds_read_b128 v[88:91], v202 offset:19200
	ds_read_b128 v[128:131], v206 offset:18432
	ds_read_b128 v[76:79], v202 offset:18432
	ds_read_b128 v[84:87], v202 offset:18944
	ds_read_b128 v[132:135], v202 offset:19456
	s_waitcnt lgkmcnt(6)
	v_pk_mul_f32 v[148:149], v[72:73], v[112:113]
	v_pk_fma_f32 v[148:149], v[74:75], v[114:115], v[148:149]
	v_add_f32_e32 v150, v148, v149
	v_pk_mul_f32 v[152:153], v[120:121], v[126:127] op_sel:[0,1] op_sel_hi:[1,1]
	v_pk_mul_f32 v[154:155], v[122:123], v[126:127] op_sel:[0,1] op_sel_hi:[1,1]
	v_add_f32_dpp v150, v150, v150 quad_perm:[1,0,3,2] row_mask:0xf bank_mask:0xf bound_ctrl:1
	v_pk_fma_f32 v[152:153], v[72:73], v[108:109], v[152:153]
	v_pk_fma_f32 v[154:155], v[74:75], v[110:111], v[154:155]
	v_add_f32_dpp v150, v150, v150 quad_perm:[2,3,0,1] row_mask:0xf bank_mask:0xf bound_ctrl:1
	v_pk_mul_f32 v[156:157], v[72:73], v[140:141]
	v_pk_fma_f32 v[156:157], v[74:75], v[142:143], v[156:157]
	v_add_f32_dpp v150, v150, v150 row_half_mirror row_mask:0xf bank_mask:0xf bound_ctrl:1
	v_add_f32_e32 v160, v156, v157
	ds_read_b128 v[96:99], v202 offset:20224
	v_add_f32_dpp v150, v150, v150 row_mirror row_mask:0xf bank_mask:0xf bound_ctrl:1
	v_pk_fma_f32 v[68:69], v[116:117], v[150:151], v[152:153] op_sel_hi:[1,0,1]
	v_pk_fma_f32 v[70:71], v[118:119], v[150:151], v[154:155] op_sel_hi:[1,0,1]
	ds_read_b128 v[104:107], v202 offset:20736
	ds_read_b128 v[92:95], v202 offset:19968
	ds_read_b128 v[100:103], v202 offset:20480
	ds_read_b128 v[136:139], v202 offset:20992
	s_waitcnt lgkmcnt(5)
; __device__ __forceinline__ void rwkv_scan(Frame& F, int wg, unsigned* shw, unsigned wait_target, int wait_blk) {
;     ...
;             RwOps R[4];
;             RW_LD(R[0], 0); RW_LD(R[1], 1); RW_LD(R[2], 2);
;             for (int s4 = 0; s4 < RW_TB; s4 += 4) {
;                 float pz[4], u[4];
; #pragma unroll
;                 for (int q = 0; q < 4; ++q) {
;                     RW_LD(R[(q + 3) & 3], s4 + q + 3);
;                     const RwOps& cur = R[q];
;                     const f32x2 slo = {st.x, st.y}, shi = {st.z, st.w};
;                     f32x2 ma = slo * (f32x2){cur.a.x, cur.a.y}; ma = __builtin_elementwise_fma(shi, (f32x2){cur.a.z, cur.a.w}, ma);
;                     f32x2 mz = slo * (f32x2){cur.wr.x, cur.wr.y}; mz = __builtin_elementwise_fma(shi, (f32x2){cur.wr.z, cur.wr.w}, mz);
;                     float psa = ma.x + ma.y; pz[q] = mz.x + mz.y;
;                     const f32x2 vb = {cur.vs.x, cur.vs.x};
;                     f32x2 tlo = (f32x2){cur.k.x, cur.k.y} * vb, thi = (f32x2){cur.k.z, cur.k.w} * vb;
;                     tlo = __builtin_elementwise_fma(slo, (f32x2){cur.w.x, cur.w.y}, tlo); thi = __builtin_elementwise_fma(shi, (f32x2){cur.w.z, cur.w.w}, thi);
;                     psa = red16(psa);
;                     const f32x2 pb = {psa, psa};
;                     tlo = __builtin_elementwise_fma((f32x2){cur.b.x, cur.b.y}, pb, tlo); thi = __builtin_elementwise_fma((f32x2){cur.b.z, cur.b.w}, pb, thi);
;                     st = (f32x4){tlo.x, tlo.y, thi.x, thi.y};
;                     u[q] = psa * cur.vs.z + cur.vs.y;
;                 }
;                 const float qa = (odd1 ? pz[1] : pz[0]) + dppf<0xB1>(odd1 ? pz[0] : pz[1]);
;                 const float qb = (odd1 ? pz[3] : pz[2]) + dppf<0xB1>(odd1 ? pz[2] : pz[3]);
;                 float r = (odd2 ? qb : qa) + dppf<0x4E>(odd2 ? qa : qb);
;                 r += dppf<0x124>(r); r += dppf<0x128>(r);
;                 const float us = odd2 ? (odd1 ? u[3] : u[2]) : (odd1 ? u[1] : u[0]);
;                 if (j < 4) { const int t = blk * RW_TB + s4 + j; ((float*)(Ub + (size_t)t * (PWP * 2) + URR * 2))[h * 64 + row] = r + us; }
	v_pk_mul_f32 v[148:149], v[68:69], v[80:81]
	v_pk_fma_f32 v[148:149], v[70:71], v[82:83], v[148:149]
	v_add_f32_e32 v150, v148, v149
	v_pk_mul_f32 v[152:153], v[88:89], v[128:129] op_sel_hi:[1,0]
	v_pk_mul_f32 v[154:155], v[90:91], v[128:129] op_sel_hi:[1,0]
	v_add_f32_dpp v150, v150, v150 quad_perm:[1,0,3,2] row_mask:0xf bank_mask:0xf bound_ctrl:1
	v_pk_fma_f32 v[152:153], v[68:69], v[76:77], v[152:153]
	v_pk_fma_f32 v[154:155], v[70:71], v[78:79], v[154:155]
	v_add_f32_dpp v150, v150, v150 quad_perm:[2,3,0,1] row_mask:0xf bank_mask:0xf bound_ctrl:1
	v_pk_mul_f32 v[156:157], v[68:69], v[144:145]
	v_pk_fma_f32 v[156:157], v[70:71], v[146:147], v[156:157]
	v_add_f32_dpp v150, v150, v150 row_half_mirror row_mask:0xf bank_mask:0xf bound_ctrl:1
	v_add_f32_e32 v161, v156, v157
	v_add_f32_dpp v162, v158, v158 row_ror:8 row_mask:0xf bank_mask:0xf
	v_add_f32_dpp v150, v150, v150 row_mirror row_mask:0xf bank_mask:0xf bound_ctrl:1
	v_pk_fma_f32 v[72:73], v[84:85], v[150:151], v[152:153] op_sel_hi:[1,0,1]
	v_pk_fma_f32 v[74:75], v[86:87], v[150:151], v[154:155] op_sel_hi:[1,0,1]
	v_add_f32_dpp v163, v159, v159 row_ror:8 row_mask:0xf bank_mask:0xf
	v_add_f32_dpp v162, v160, v160 row_ror:8 row_mask:0xf bank_mask:0xc
	v_add_f32_dpp v163, v161, v161 row_ror:8 row_mask:0xf bank_mask:0xc
	ds_read_b128 v[112:115], v202 offset:21760
	ds_read_b128 v[120:123], v202 offset:22272
	v_add_f32_dpp v164, v162, v162 row_half_mirror row_mask:0xf bank_mask:0xf
	v_add_f32_dpp v164, v163, v163 row_half_mirror row_mask:0xf bank_mask:0xa
	ds_read_b128 v[108:111], v202 offset:21504
	ds_read_b128 v[116:119], v202 offset:22016
	v_add_f32_dpp v164, v164, v164 quad_perm:[1,0,3,2] row_mask:0xf bank_mask:0xf bound_ctrl:1
	ds_read_b128 v[140:143], v202 offset:22528
	s_nop 0
	v_add_f32_dpp v164, v164, v164 quad_perm:[2,3,0,1] row_mask:0xf bank_mask:0xf bound_ctrl:1
	global_store_dword v165, v164, s[34:35]
	v_add_u32_e32 v165, 0xb000, v165
	s_waitcnt lgkmcnt(5)
	v_pk_mul_f32 v[148:149], v[72:73], v[96:97]
	v_pk_fma_f32 v[148:149], v[74:75], v[98:99], v[148:149]
	v_add_f32_e32 v150, v148, v149
	v_pk_mul_f32 v[152:153], v[104:105], v[128:129] op_sel:[0,1] op_sel_hi:[1,1]
	v_pk_mul_f32 v[154:155], v[106:107], v[128:129] op_sel:[0,1] op_sel_hi:[1,1]
	v_add_f32_dpp v150, v150, v150 quad_perm:[1,0,3,2] row_mask:0xf bank_mask:0xf bound_ctrl:1
	v_pk_fma_f32 v[152:153], v[72:73], v[92:93], v[152:153]
	v_pk_fma_f32 v[154:155], v[74:75], v[94:95], v[154:155]
	v_add_f32_dpp v150, v150, v150 quad_perm:[2,3,0,1] row_mask:0xf bank_mask:0xf bound_ctrl:1
	v_pk_mul_f32 v[156:157], v[72:73], v[132:133]
	v_pk_fma_f32 v[156:157], v[74:75], v[134:135], v[156:157]
	v_add_f32_dpp v150, v150, v150 row_half_mirror row_mask:0xf bank_mask:0xf bound_ctrl:1
	v_add_f32_e32 v158, v156, v157
	ds_read_b128 v[80:83], v202 offset:23296
	v_add_f32_dpp v150, v150, v150 row_mirror row_mask:0xf bank_mask:0xf bound_ctrl:1
	v_pk_fma_f32 v[68:69], v[100:101], v[150:151], v[152:153] op_sel_hi:[1,0,1]
	v_pk_fma_f32 v[70:71], v[102:103], v[150:151], v[154:155] op_sel_hi:[1,0,1]
	ds_read_b128 v[88:91], v202 offset:23808
	ds_read_b128 v[76:79], v202 offset:23040
	ds_read_b128 v[84:87], v202 offset:23552
	ds_read_b128 v[144:147], v202 offset:24064
	s_waitcnt lgkmcnt(5)
	v_pk_mul_f32 v[148:149], v[68:69], v[112:113]
	v_pk_fma_f32 v[148:149], v[70:71], v[114:115], v[148:149]
	v_add_f32_e32 v150, v148, v149
	v_pk_mul_f32 v[152:153], v[120:121], v[130:131] op_sel_hi:[1,0]
	v_pk_mul_f32 v[154:155], v[122:123], v[130:131] op_sel_hi:[1,0]
	v_add_f32_dpp v150, v150, v150 quad_perm:[1,0,3,2] row_mask:0xf bank_mask:0xf bound_ctrl:1
	v_pk_fma_f32 v[152:153], v[68:69], v[108:109], v[152:153]
	v_pk_fma_f32 v[154:155], v[70:71], v[110:111], v[154:155]
	v_add_f32_dpp v150, v150, v150 quad_perm:[2,3,0,1] row_mask:0xf bank_mask:0xf bound_ctrl:1
	v_pk_mul_f32 v[156:157], v[68:69], v[136:137]
	v_pk_fma_f32 v[156:157], v[70:71], v[138:139], v[156:157]
	v_add_f32_dpp v150, v150, v150 row_half_mirror row_mask:0xf bank_mask:0xf bound_ctrl:1
	v_add_f32_e32 v159, v156, v157
	ds_read_b128 v[96:99], v202 offset:24832
	v_add_f32_dpp v150, v150, v150 row_mirror row_mask:0xf bank_mask:0xf bound_ctrl:1
	v_pk_fma_f32 v[72:73], v[116:117], v[150:151], v[152:153] op_sel_hi:[1,0,1]
	v_pk_fma_f32 v[74:75], v[118:119], v[150:151], v[154:155] op_sel_hi:[1,0,1]
	ds_read_b128 v[104:107], v202 offset:25344
	ds_read_b128 v[124:127], v206 offset:24576
	ds_read_b128 v[92:95], v202 offset:24576
	ds_read_b128 v[100:103], v202 offset:25088
	ds_read_b128 v[132:135], v202 offset:25600
	s_waitcnt lgkmcnt(6)
	v_pk_mul_f32 v[148:149], v[72:73], v[80:81]
	v_pk_fma_f32 v[148:149], v[74:75], v[82:83], v[148:149]
	v_add_f32_e32 v150, v148, v149
	v_pk_mul_f32 v[152:153], v[88:89], v[130:131] op_sel:[0,1] op_sel_hi:[1,1]
	v_pk_mul_f32 v[154:155], v[90:91], v[130:131] op_sel:[0,1] op_sel_hi:[1,1]
	v_add_f32_dpp v150, v150, v150 quad_perm:[1,0,3,2] row_mask:0xf bank_mask:0xf bound_ctrl:1
	v_pk_fma_f32 v[152:153], v[72:73], v[76:77], v[152:153]
	v_pk_fma_f32 v[154:155], v[74:75], v[78:79], v[154:155]
	v_add_f32_dpp v150, v150, v150 quad_perm:[2,3,0,1] row_mask:0xf bank_mask:0xf bound_ctrl:1
	v_pk_mul_f32 v[156:157], v[72:73], v[140:141]
	v_pk_fma_f32 v[156:157], v[74:75], v[142:143], v[156:157]
	v_add_f32_dpp v150, v150, v150 row_half_mirror row_mask:0xf bank_mask:0xf bound_ctrl:1
	v_add_f32_e32 v160, v156, v157
	ds_read_b128 v[112:115], v202 offset:26368
	v_add_f32_dpp v150, v150, v150 row_mirror row_mask:0xf bank_mask:0xf bound_ctrl:1
	v_pk_fma_f32 v[68:69], v[84:85], v[150:151], v[152:153] op_sel_hi:[1,0,1]
	v_pk_fma_f32 v[70:71], v[86:87], v[150:151], v[154:155] op_sel_hi:[1,0,1]
	ds_read_b128 v[120:123], v202 offset:26880
	ds_read_b128 v[108:111], v202 offset:26112
	ds_read_b128 v[116:119], v202 offset:26624
	ds_read_b128 v[136:139], v202 offset:27136
	s_waitcnt lgkmcnt(5)
; __device__ __forceinline__ void rwkv_scan(Frame& F, int wg, unsigned* shw, unsigned wait_target, int wait_blk) {
;     ...
;             RwOps R[4];
;             RW_LD(R[0], 0); RW_LD(R[1], 1); RW_LD(R[2], 2);
;             for (int s4 = 0; s4 < RW_TB; s4 += 4) {
;                 float pz[4], u[4];
; #pragma unroll
;                 for (int q = 0; q < 4; ++q) {
;                     RW_LD(R[(q + 3) & 3], s4 + q + 3);
;                     const RwOps& cur = R[q];
;                     const f32x2 slo = {st.x, st.y}, shi = {st.z, st.w};
;                     f32x2 ma = slo * (f32x2){cur.a.x, cur.a.y}; ma = __builtin_elementwise_fma(shi, (f32x2){cur.a.z, cur.a.w}, ma);
;                     f32x2 mz = slo * (f32x2){cur.wr.x, cur.wr.y}; mz = __builtin_elementwise_fma(shi, (f32x2){cur.wr.z, cur.wr.w}, mz);
;                     float psa = ma.x + ma.y; pz[q] = mz.x + mz.y;
;                     const f32x2 vb = {cur.vs.x, cur.vs.x};
;                     f32x2 tlo = (f32x2){cur.k.x, cur.k.y} * vb, thi = (f32x2){cur.k.z, cur.k.w} * vb;
;                     tlo = __builtin_elementwise_fma(slo, (f32x2){cur.w.x, cur.w.y}, tlo); thi = __builtin_elementwise_fma(shi, (f32x2){cur.w.z, cur.w.w}, thi);
;                     psa = red16(psa);
;                     const f32x2 pb = {psa, psa};
;                     tlo = __builtin_elementwise_fma((f32x2){cur.b.x, cur.b.y}, pb, tlo); thi = __builtin_elementwise_fma((f32x2){cur.b.z, cur.b.w}, pb, thi);
;                     st = (f32x4){tlo.x, tlo.y, thi.x, thi.y};
;                     u[q] = psa * cur.vs.z + cur.vs.y;
;                 }
;                 const float qa = (odd1 ? pz[1] : pz[0]) + dppf<0xB1>(odd1 ? pz[0] : pz[1]);
;                 const float qb = (odd1 ? pz[3] : pz[2]) + dppf<0xB1>(odd1 ? pz[2] : pz[3]);
;                 float r = (odd2 ? qb : qa) + dppf<0x4E>(odd2 ? qa : qb);
;                 r += dppf<0x124>(r); r += dppf<0x128>(r);
;                 const float us = odd2 ? (odd1 ? u[3] : u[2]) : (odd1 ? u[1] : u[0]);
;                 if (j < 4) { const int t = blk * RW_TB + s4 + j; ((float*)(Ub + (size_t)t * (PWP * 2) + URR * 2))[h * 64 + row] = r + us; }
	v_pk_mul_f32 v[148:149], v[68:69], v[96:97]
	v_pk_fma_f32 v[148:149], v[70:71], v[98:99], v[148:149]
	v_add_f32_e32 v150, v148, v149
	v_pk_mul_f32 v[152:153], v[104:105], v[124:125] op_sel_hi:[1,0]
	v_pk_mul_f32 v[154:155], v[106:107], v[124:125] op_sel_hi:[1,0]
	v_add_f32_dpp v150, v150, v150 quad_perm:[1,0,3,2] row_mask:0xf bank_mask:0xf bound_ctrl:1
	v_pk_fma_f32 v[152:153], v[68:69], v[92:93], v[152:153]
	v_pk_fma_f32 v[154:155], v[70:71], v[94:95], v[154:155]
	v_add_f32_dpp v150, v150, v150 quad_perm:[2,3,0,1] row_mask:0xf bank_mask:0xf bound_ctrl:1
	v_pk_mul_f32 v[156:157], v[68:69], v[144:145]
	v_pk_fma_f32 v[156:157], v[70:71], v[146:147], v[156:157]
	v_add_f32_dpp v150, v150, v150 row_half_mirror row_mask:0xf bank_mask:0xf bound_ctrl:1
	v_add_f32_e32 v161, v156, v157
	v_add_f32_dpp v162, v158, v158 row_ror:8 row_mask:0xf bank_mask:0xf
	v_add_f32_dpp v150, v150, v150 row_mirror row_mask:0xf bank_mask:0xf bound_ctrl:1
	v_pk_fma_f32 v[72:73], v[100:101], v[150:151], v[152:153] op_sel_hi:[1,0,1]
	v_pk_fma_f32 v[74:75], v[102:103], v[150:151], v[154:155] op_sel_hi:[1,0,1]
	v_add_f32_dpp v163, v159, v159 row_ror:8 row_mask:0xf bank_mask:0xf
	v_add_f32_dpp v162, v160, v160 row_ror:8 row_mask:0xf bank_mask:0xc
	v_add_f32_dpp v163, v161, v161 row_ror:8 row_mask:0xf bank_mask:0xc
	ds_read_b128 v[80:83], v202 offset:27904
	ds_read_b128 v[88:91], v202 offset:28416
	v_add_f32_dpp v164, v162, v162 row_half_mirror row_mask:0xf bank_mask:0xf
	v_add_f32_dpp v164, v163, v163 row_half_mirror row_mask:0xf bank_mask:0xa
	ds_read_b128 v[76:79], v202 offset:27648
	ds_read_b128 v[84:87], v202 offset:28160
	v_add_f32_dpp v164, v164, v164 quad_perm:[1,0,3,2] row_mask:0xf bank_mask:0xf bound_ctrl:1
	ds_read_b128 v[140:143], v202 offset:28672
	s_nop 0
	v_add_f32_dpp v164, v164, v164 quad_perm:[2,3,0,1] row_mask:0xf bank_mask:0xf bound_ctrl:1
	global_store_dword v165, v164, s[34:35]
	v_add_u32_e32 v165, 0xb000, v165
	s_waitcnt lgkmcnt(5)
	v_pk_mul_f32 v[148:149], v[72:73], v[112:113]
	v_pk_fma_f32 v[148:149], v[74:75], v[114:115], v[148:149]
	v_add_f32_e32 v150, v148, v149
	v_pk_mul_f32 v[152:153], v[120:121], v[124:125] op_sel:[0,1] op_sel_hi:[1,1]
	v_pk_mul_f32 v[154:155], v[122:123], v[124:125] op_sel:[0,1] op_sel_hi:[1,1]
	v_add_f32_dpp v150, v150, v150 quad_perm:[1,0,3,2] row_mask:0xf bank_mask:0xf bound_ctrl:1
	v_pk_fma_f32 v[152:153], v[72:73], v[108:109], v[152:153]
	v_pk_fma_f32 v[154:155], v[74:75], v[110:111], v[154:155]
	v_add_f32_dpp v150, v150, v150 quad_perm:[2,3,0,1] row_mask:0xf bank_mask:0xf bound_ctrl:1
	v_pk_mul_f32 v[156:157], v[72:73], v[132:133]
	v_pk_fma_f32 v[156:157], v[74:75], v[134:135], v[156:157]
	v_add_f32_dpp v150, v150, v150 row_half_mirror row_mask:0xf bank_mask:0xf bound_ctrl:1
	v_add_f32_e32 v158, v156, v157
	ds_read_b128 v[96:99], v202 offset:29440
	v_add_f32_dpp v150, v150, v150 row_mirror row_mask:0xf bank_mask:0xf bound_ctrl:1
	v_pk_fma_f32 v[68:69], v[116:117], v[150:151], v[152:153] op_sel_hi:[1,0,1]
	v_pk_fma_f32 v[70:71], v[118:119], v[150:151], v[154:155] op_sel_hi:[1,0,1]
	ds_read_b128 v[104:107], v202 offset:29952
	ds_read_b128 v[92:95], v202 offset:29184
	ds_read_b128 v[100:103], v202 offset:29696
	ds_read_b128 v[144:147], v202 offset:30208
	s_waitcnt lgkmcnt(5)
	v_pk_mul_f32 v[148:149], v[68:69], v[80:81]
	v_pk_fma_f32 v[148:149], v[70:71], v[82:83], v[148:149]
	v_add_f32_e32 v150, v148, v149
	v_pk_mul_f32 v[152:153], v[88:89], v[126:127] op_sel_hi:[1,0]
	v_pk_mul_f32 v[154:155], v[90:91], v[126:127] op_sel_hi:[1,0]
	v_add_f32_dpp v150, v150, v150 quad_perm:[1,0,3,2] row_mask:0xf bank_mask:0xf bound_ctrl:1
	v_pk_fma_f32 v[152:153], v[68:69], v[76:77], v[152:153]
	v_pk_fma_f32 v[154:155], v[70:71], v[78:79], v[154:155]
	v_add_f32_dpp v150, v150, v150 quad_perm:[2,3,0,1] row_mask:0xf bank_mask:0xf bound_ctrl:1
	v_pk_mul_f32 v[156:157], v[68:69], v[136:137]
	v_pk_fma_f32 v[156:157], v[70:71], v[138:139], v[156:157]
	v_add_f32_dpp v150, v150, v150 row_half_mirror row_mask:0xf bank_mask:0xf bound_ctrl:1
	v_add_f32_e32 v159, v156, v157
	ds_read_b128 v[112:115], v202 offset:30976
	v_add_f32_dpp v150, v150, v150 row_mirror row_mask:0xf bank_mask:0xf bound_ctrl:1
	v_pk_fma_f32 v[72:73], v[84:85], v[150:151], v[152:153] op_sel_hi:[1,0,1]
	v_pk_fma_f32 v[74:75], v[86:87], v[150:151], v[154:155] op_sel_hi:[1,0,1]
	ds_read_b128 v[120:123], v202 offset:31488
	ds_read_b128 v[128:131], v206 offset:30720
	ds_read_b128 v[108:111], v202 offset:30720
	ds_read_b128 v[116:119], v202 offset:31232
	ds_read_b128 v[132:135], v202 offset:31744
	s_waitcnt lgkmcnt(6)
	v_pk_mul_f32 v[148:149], v[72:73], v[96:97]
	v_pk_fma_f32 v[148:149], v[74:75], v[98:99], v[148:149]
	v_add_f32_e32 v150, v148, v149
	v_pk_mul_f32 v[152:153], v[104:105], v[126:127] op_sel:[0,1] op_sel_hi:[1,1]
	v_pk_mul_f32 v[154:155], v[106:107], v[126:127] op_sel:[0,1] op_sel_hi:[1,1]
	v_add_f32_dpp v150, v150, v150 quad_perm:[1,0,3,2] row_mask:0xf bank_mask:0xf bound_ctrl:1
	v_pk_fma_f32 v[152:153], v[72:73], v[92:93], v[152:153]
	v_pk_fma_f32 v[154:155], v[74:75], v[94:95], v[154:155]
	v_add_f32_dpp v150, v150, v150 quad_perm:[2,3,0,1] row_mask:0xf bank_mask:0xf bound_ctrl:1
	v_pk_mul_f32 v[156:157], v[72:73], v[140:141]
	v_pk_fma_f32 v[156:157], v[74:75], v[142:143], v[156:157]
	v_add_f32_dpp v150, v150, v150 row_half_mirror row_mask:0xf bank_mask:0xf bound_ctrl:1
	v_add_f32_e32 v160, v156, v157
	ds_read_b128 v[80:83], v202 offset:32512
	v_add_f32_dpp v150, v150, v150 row_mirror row_mask:0xf bank_mask:0xf bound_ctrl:1
	v_pk_fma_f32 v[68:69], v[100:101], v[150:151], v[152:153] op_sel_hi:[1,0,1]
	v_pk_fma_f32 v[70:71], v[102:103], v[150:151], v[154:155] op_sel_hi:[1,0,1]
	ds_read_b128 v[88:91], v202 offset:33024
	ds_read_b128 v[76:79], v202 offset:32256
	ds_read_b128 v[84:87], v202 offset:32768
	ds_read_b128 v[136:139], v202 offset:33280
	s_waitcnt lgkmcnt(5)
; __device__ __forceinline__ void rwkv_scan(Frame& F, int wg, unsigned* shw, unsigned wait_target, int wait_blk) {
;     ...
;             RwOps R[4];
;             RW_LD(R[0], 0); RW_LD(R[1], 1); RW_LD(R[2], 2);
;             for (int s4 = 0; s4 < RW_TB; s4 += 4) {
;                 float pz[4], u[4];
; #pragma unroll
;                 for (int q = 0; q < 4; ++q) {
;                     RW_LD(R[(q + 3) & 3], s4 + q + 3);
;                     const RwOps& cur = R[q];
;                     const f32x2 slo = {st.x, st.y}, shi = {st.z, st.w};
;                     f32x2 ma = slo * (f32x2){cur.a.x, cur.a.y}; ma = __builtin_elementwise_fma(shi, (f32x2){cur.a.z, cur.a.w}, ma);
;                     f32x2 mz = slo * (f32x2){cur.wr.x, cur.wr.y}; mz = __builtin_elementwise_fma(shi, (f32x2){cur.wr.z, cur.wr.w}, mz);
;                     float psa = ma.x + ma.y; pz[q] = mz.x + mz.y;
;                     const f32x2 vb = {cur.vs.x, cur.vs.x};
;                     f32x2 tlo = (f32x2){cur.k.x, cur.k.y} * vb, thi = (f32x2){cur.k.z, cur.k.w} * vb;
;                     tlo = __builtin_elementwise_fma(slo, (f32x2){cur.w.x, cur.w.y}, tlo); thi = __builtin_elementwise_fma(shi, (f32x2){cur.w.z, cur.w.w}, thi);
;                     psa = red16(psa);
;                     const f32x2 pb = {psa, psa};
;                     tlo = __builtin_elementwise_fma((f32x2){cur.b.x, cur.b.y}, pb, tlo); thi = __builtin_elementwise_fma((f32x2){cur.b.z, cur.b.w}, pb, thi);
;                     st = (f32x4){tlo.x, tlo.y, thi.x, thi.y};
;                     u[q] = psa * cur.vs.z + cur.vs.y;
;                 }
;                 const float qa = (odd1 ? pz[1] : pz[0]) + dppf<0xB1>(odd1 ? pz[0] : pz[1]);
;                 const float qb = (odd1 ? pz[3] : pz[2]) + dppf<0xB1>(odd1 ? pz[2] : pz[3]);
;                 float r = (odd2 ? qb : qa) + dppf<0x4E>(odd2 ? qa : qb);
;                 r += dppf<0x124>(r); r += dppf<0x128>(r);
;                 const float us = odd2 ? (odd1 ? u[3] : u[2]) : (odd1 ? u[1] : u[0]);
;                 if (j < 4) { const int t = blk * RW_TB + s4 + j; ((float*)(Ub + (size_t)t * (PWP * 2) + URR * 2))[h * 64 + row] = r + us; }
	v_pk_mul_f32 v[148:149], v[68:69], v[112:113]
	v_pk_fma_f32 v[148:149], v[70:71], v[114:115], v[148:149]
	v_add_f32_e32 v150, v148, v149
	v_pk_mul_f32 v[152:153], v[120:121], v[128:129] op_sel_hi:[1,0]
	v_pk_mul_f32 v[154:155], v[122:123], v[128:129] op_sel_hi:[1,0]
	v_add_f32_dpp v150, v150, v150 quad_perm:[1,0,3,2] row_mask:0xf bank_mask:0xf bound_ctrl:1
	v_pk_fma_f32 v[152:153], v[68:69], v[108:109], v[152:153]
	v_pk_fma_f32 v[154:155], v[70:71], v[110:111], v[154:155]
	v_add_f32_dpp v150, v150, v150 quad_perm:[2,3,0,1] row_mask:0xf bank_mask:0xf bound_ctrl:1
	v_pk_mul_f32 v[156:157], v[68:69], v[144:145]
	v_pk_fma_f32 v[156:157], v[70:71], v[146:147], v[156:157]
	v_add_f32_dpp v150, v150, v150 row_half_mirror row_mask:0xf bank_mask:0xf bound_ctrl:1
	v_add_f32_e32 v161, v156, v157
	v_add_f32_dpp v162, v158, v158 row_ror:8 row_mask:0xf bank_mask:0xf
	v_add_f32_dpp v150, v150, v150 row_mirror row_mask:0xf bank_mask:0xf bound_ctrl:1
	v_pk_fma_f32 v[72:73], v[116:117], v[150:151], v[152:153] op_sel_hi:[1,0,1]
	v_pk_fma_f32 v[74:75], v[118:119], v[150:151], v[154:155] op_sel_hi:[1,0,1]
	v_add_f32_dpp v163, v159, v159 row_ror:8 row_mask:0xf bank_mask:0xf
	v_add_f32_dpp v162, v160, v160 row_ror:8 row_mask:0xf bank_mask:0xc
	v_add_f32_dpp v163, v161, v161 row_ror:8 row_mask:0xf bank_mask:0xc
	ds_read_b128 v[96:99], v202 offset:34048
	ds_read_b128 v[104:107], v202 offset:34560
	v_add_f32_dpp v164, v162, v162 row_half_mirror row_mask:0xf bank_mask:0xf
	v_add_f32_dpp v164, v163, v163 row_half_mirror row_mask:0xf bank_mask:0xa
	ds_read_b128 v[92:95], v202 offset:33792
	ds_read_b128 v[100:103], v202 offset:34304
	v_add_f32_dpp v164, v164, v164 quad_perm:[1,0,3,2] row_mask:0xf bank_mask:0xf bound_ctrl:1
	ds_read_b128 v[140:143], v202 offset:34816
	s_nop 0
	v_add_f32_dpp v164, v164, v164 quad_perm:[2,3,0,1] row_mask:0xf bank_mask:0xf bound_ctrl:1
	global_store_dword v165, v164, s[34:35]
	v_add_u32_e32 v165, 0xb000, v165
	s_waitcnt lgkmcnt(5)
	v_pk_mul_f32 v[148:149], v[72:73], v[80:81]
	v_pk_fma_f32 v[148:149], v[74:75], v[82:83], v[148:149]
	v_add_f32_e32 v150, v148, v149
	v_pk_mul_f32 v[152:153], v[88:89], v[128:129] op_sel:[0,1] op_sel_hi:[1,1]
	v_pk_mul_f32 v[154:155], v[90:91], v[128:129] op_sel:[0,1] op_sel_hi:[1,1]
	v_add_f32_dpp v150, v150, v150 quad_perm:[1,0,3,2] row_mask:0xf bank_mask:0xf bound_ctrl:1
	v_pk_fma_f32 v[152:153], v[72:73], v[76:77], v[152:153]
	v_pk_fma_f32 v[154:155], v[74:75], v[78:79], v[154:155]
	v_add_f32_dpp v150, v150, v150 quad_perm:[2,3,0,1] row_mask:0xf bank_mask:0xf bound_ctrl:1
	v_pk_mul_f32 v[156:157], v[72:73], v[132:133]
	v_pk_fma_f32 v[156:157], v[74:75], v[134:135], v[156:157]
	v_add_f32_dpp v150, v150, v150 row_half_mirror row_mask:0xf bank_mask:0xf bound_ctrl:1
	v_add_f32_e32 v158, v156, v157
	ds_read_b128 v[112:115], v202 offset:35584
	v_add_f32_dpp v150, v150, v150 row_mirror row_mask:0xf bank_mask:0xf bound_ctrl:1
	v_pk_fma_f32 v[68:69], v[84:85], v[150:151], v[152:153] op_sel_hi:[1,0,1]
	v_pk_fma_f32 v[70:71], v[86:87], v[150:151], v[154:155] op_sel_hi:[1,0,1]
	ds_read_b128 v[120:123], v202 offset:36096
	ds_read_b128 v[108:111], v202 offset:35328
	ds_read_b128 v[116:119], v202 offset:35840
	ds_read_b128 v[144:147], v202 offset:36352
	s_waitcnt lgkmcnt(5)
	v_pk_mul_f32 v[148:149], v[68:69], v[96:97]
	v_pk_fma_f32 v[148:149], v[70:71], v[98:99], v[148:149]
	v_add_f32_e32 v150, v148, v149
	v_pk_mul_f32 v[152:153], v[104:105], v[130:131] op_sel_hi:[1,0]
	v_pk_mul_f32 v[154:155], v[106:107], v[130:131] op_sel_hi:[1,0]
	v_add_f32_dpp v150, v150, v150 quad_perm:[1,0,3,2] row_mask:0xf bank_mask:0xf bound_ctrl:1
	v_pk_fma_f32 v[152:153], v[68:69], v[92:93], v[152:153]
	v_pk_fma_f32 v[154:155], v[70:71], v[94:95], v[154:155]
	v_add_f32_dpp v150, v150, v150 quad_perm:[2,3,0,1] row_mask:0xf bank_mask:0xf bound_ctrl:1
	v_pk_mul_f32 v[156:157], v[68:69], v[136:137]
	v_pk_fma_f32 v[156:157], v[70:71], v[138:139], v[156:157]
	v_add_f32_dpp v150, v150, v150 row_half_mirror row_mask:0xf bank_mask:0xf bound_ctrl:1
	v_add_f32_e32 v159, v156, v157
	ds_read_b128 v[80:83], v202 offset:37120
	v_add_f32_dpp v150, v150, v150 row_mirror row_mask:0xf bank_mask:0xf bound_ctrl:1
	v_pk_fma_f32 v[72:73], v[100:101], v[150:151], v[152:153] op_sel_hi:[1,0,1]
	v_pk_fma_f32 v[74:75], v[102:103], v[150:151], v[154:155] op_sel_hi:[1,0,1]
	ds_read_b128 v[88:91], v202 offset:37632
	ds_read_b128 v[124:127], v206 offset:36864
	ds_read_b128 v[76:79], v202 offset:36864
	ds_read_b128 v[84:87], v202 offset:37376
	ds_read_b128 v[132:135], v202 offset:37888
	s_waitcnt lgkmcnt(6)
	v_pk_mul_f32 v[148:149], v[72:73], v[112:113]
	v_pk_fma_f32 v[148:149], v[74:75], v[114:115], v[148:149]
	v_add_f32_e32 v150, v148, v149
	v_pk_mul_f32 v[152:153], v[120:121], v[130:131] op_sel:[0,1] op_sel_hi:[1,1]
	v_pk_mul_f32 v[154:155], v[122:123], v[130:131] op_sel:[0,1] op_sel_hi:[1,1]
	v_add_f32_dpp v150, v150, v150 quad_perm:[1,0,3,2] row_mask:0xf bank_mask:0xf bound_ctrl:1
	v_pk_fma_f32 v[152:153], v[72:73], v[108:109], v[152:153]
	v_pk_fma_f32 v[154:155], v[74:75], v[110:111], v[154:155]
	v_add_f32_dpp v150, v150, v150 quad_perm:[2,3,0,1] row_mask:0xf bank_mask:0xf bound_ctrl:1
	v_pk_mul_f32 v[156:157], v[72:73], v[140:141]
	v_pk_fma_f32 v[156:157], v[74:75], v[142:143], v[156:157]
	v_add_f32_dpp v150, v150, v150 row_half_mirror row_mask:0xf bank_mask:0xf bound_ctrl:1
	v_add_f32_e32 v160, v156, v157
	ds_read_b128 v[96:99], v202 offset:38656
	v_add_f32_dpp v150, v150, v150 row_mirror row_mask:0xf bank_mask:0xf bound_ctrl:1
	v_pk_fma_f32 v[68:69], v[116:117], v[150:151], v[152:153] op_sel_hi:[1,0,1]
	v_pk_fma_f32 v[70:71], v[118:119], v[150:151], v[154:155] op_sel_hi:[1,0,1]
	ds_read_b128 v[104:107], v202 offset:39168
	ds_read_b128 v[92:95], v202 offset:38400
	ds_read_b128 v[100:103], v202 offset:38912
	ds_read_b128 v[136:139], v202 offset:39424
	s_waitcnt lgkmcnt(5)
; __device__ __forceinline__ void rwkv_scan(Frame& F, int wg, unsigned* shw, unsigned wait_target, int wait_blk) {
;     ...
;             for (int s4 = 0; s4 < RW_TB; s4 += 4) {
;                 float pz[4], u[4];
; #pragma unroll
;                 for (int q = 0; q < 4; ++q) {
;                     RW_LD(R[(q + 3) & 3], s4 + q + 3);
;                     const RwOps& cur = R[q];
;                     const f32x2 slo = {st.x, st.y}, shi = {st.z, st.w};
;                     f32x2 ma = slo * (f32x2){cur.a.x, cur.a.y}; ma = __builtin_elementwise_fma(shi, (f32x2){cur.a.z, cur.a.w}, ma);
;                     f32x2 mz = slo * (f32x2){cur.wr.x, cur.wr.y}; mz = __builtin_elementwise_fma(shi, (f32x2){cur.wr.z, cur.wr.w}, mz);
;                     float psa = ma.x + ma.y; pz[q] = mz.x + mz.y;
;                     const f32x2 vb = {cur.vs.x, cur.vs.x};
;                     f32x2 tlo = (f32x2){cur.k.x, cur.k.y} * vb, thi = (f32x2){cur.k.z, cur.k.w} * vb;
;                     tlo = __builtin_elementwise_fma(slo, (f32x2){cur.w.x, cur.w.y}, tlo); thi = __builtin_elementwise_fma(shi, (f32x2){cur.w.z, cur.w.w}, thi);
;                     psa = red16(psa);
;                     const f32x2 pb = {psa, psa};
;                     tlo = __builtin_elementwise_fma((f32x2){cur.b.x, cur.b.y}, pb, tlo); thi = __builtin_elementwise_fma((f32x2){cur.b.z, cur.b.w}, pb, thi);
;                     st = (f32x4){tlo.x, tlo.y, thi.x, thi.y};
;                     u[q] = psa * cur.vs.z + cur.vs.y;
;                 }
;                 const float qa = (odd1 ? pz[1] : pz[0]) + dppf<0xB1>(odd1 ? pz[0] : pz[1]);
;                 const float qb = (odd1 ? pz[3] : pz[2]) + dppf<0xB1>(odd1 ? pz[2] : pz[3]);
;                 float r = (odd2 ? qb : qa) + dppf<0x4E>(odd2 ? qa : qb);
;                 r += dppf<0x124>(r); r += dppf<0x128>(r);
;                 const float us = odd2 ? (odd1 ? u[3] : u[2]) : (odd1 ? u[1] : u[0]);
;                 if (j < 4) { const int t = blk * RW_TB + s4 + j; ((float*)(Ub + (size_t)t * (PWP * 2) + URR * 2))[h * 64 + row] = r + us; }
	v_pk_mul_f32 v[148:149], v[68:69], v[80:81]
	v_pk_fma_f32 v[148:149], v[70:71], v[82:83], v[148:149]
	v_add_f32_e32 v150, v148, v149
	v_pk_mul_f32 v[152:153], v[88:89], v[124:125] op_sel_hi:[1,0]
	v_pk_mul_f32 v[154:155], v[90:91], v[124:125] op_sel_hi:[1,0]
	v_add_f32_dpp v150, v150, v150 quad_perm:[1,0,3,2] row_mask:0xf bank_mask:0xf bound_ctrl:1
	v_pk_fma_f32 v[152:153], v[68:69], v[76:77], v[152:153]
	v_pk_fma_f32 v[154:155], v[70:71], v[78:79], v[154:155]
	v_add_f32_dpp v150, v150, v150 quad_perm:[2,3,0,1] row_mask:0xf bank_mask:0xf bound_ctrl:1
	v_pk_mul_f32 v[156:157], v[68:69], v[144:145]
	v_pk_fma_f32 v[156:157], v[70:71], v[146:147], v[156:157]
	v_add_f32_dpp v150, v150, v150 row_half_mirror row_mask:0xf bank_mask:0xf bound_ctrl:1
	v_add_f32_e32 v161, v156, v157
	v_add_f32_dpp v162, v158, v158 row_ror:8 row_mask:0xf bank_mask:0xf
	v_add_f32_dpp v150, v150, v150 row_mirror row_mask:0xf bank_mask:0xf bound_ctrl:1
	v_pk_fma_f32 v[72:73], v[84:85], v[150:151], v[152:153] op_sel_hi:[1,0,1]
	v_pk_fma_f32 v[74:75], v[86:87], v[150:151], v[154:155] op_sel_hi:[1,0,1]
	v_add_f32_dpp v163, v159, v159 row_ror:8 row_mask:0xf bank_mask:0xf
	v_add_f32_dpp v162, v160, v160 row_ror:8 row_mask:0xf bank_mask:0xc
	v_add_f32_dpp v163, v161, v161 row_ror:8 row_mask:0xf bank_mask:0xc
	ds_read_b128 v[112:115], v202 offset:40192
	ds_read_b128 v[120:123], v202 offset:40704
	v_add_f32_dpp v164, v162, v162 row_half_mirror row_mask:0xf bank_mask:0xf
	v_add_f32_dpp v164, v163, v163 row_half_mirror row_mask:0xf bank_mask:0xa
	ds_read_b128 v[108:111], v202 offset:39936
	ds_read_b128 v[116:119], v202 offset:40448
	v_add_f32_dpp v164, v164, v164 quad_perm:[1,0,3,2] row_mask:0xf bank_mask:0xf bound_ctrl:1
	ds_read_b128 v[140:143], v202 offset:40960
	s_nop 0
	v_add_f32_dpp v164, v164, v164 quad_perm:[2,3,0,1] row_mask:0xf bank_mask:0xf bound_ctrl:1
	global_store_dword v165, v164, s[34:35]
	v_add_u32_e32 v165, 0xb000, v165
	s_waitcnt lgkmcnt(5)
	v_pk_mul_f32 v[148:149], v[72:73], v[96:97]
	v_pk_fma_f32 v[148:149], v[74:75], v[98:99], v[148:149]
	v_add_f32_e32 v150, v148, v149
	v_pk_mul_f32 v[152:153], v[104:105], v[124:125] op_sel:[0,1] op_sel_hi:[1,1]
	v_pk_mul_f32 v[154:155], v[106:107], v[124:125] op_sel:[0,1] op_sel_hi:[1,1]
	v_add_f32_dpp v150, v150, v150 quad_perm:[1,0,3,2] row_mask:0xf bank_mask:0xf bound_ctrl:1
	v_pk_fma_f32 v[152:153], v[72:73], v[92:93], v[152:153]
	v_pk_fma_f32 v[154:155], v[74:75], v[94:95], v[154:155]
	v_add_f32_dpp v150, v150, v150 quad_perm:[2,3,0,1] row_mask:0xf bank_mask:0xf bound_ctrl:1
	v_pk_mul_f32 v[156:157], v[72:73], v[132:133]
	v_pk_fma_f32 v[156:157], v[74:75], v[134:135], v[156:157]
	v_add_f32_dpp v150, v150, v150 row_half_mirror row_mask:0xf bank_mask:0xf bound_ctrl:1
	v_add_f32_e32 v158, v156, v157
	ds_read_b128 v[80:83], v202 offset:41728
	v_add_f32_dpp v150, v150, v150 row_mirror row_mask:0xf bank_mask:0xf bound_ctrl:1
	v_pk_fma_f32 v[68:69], v[100:101], v[150:151], v[152:153] op_sel_hi:[1,0,1]
	v_pk_fma_f32 v[70:71], v[102:103], v[150:151], v[154:155] op_sel_hi:[1,0,1]
	ds_read_b128 v[88:91], v202 offset:42240
	ds_read_b128 v[76:79], v202 offset:41472
	ds_read_b128 v[84:87], v202 offset:41984
	ds_read_b128 v[144:147], v202 offset:42496
	s_waitcnt lgkmcnt(5)
	v_pk_mul_f32 v[148:149], v[68:69], v[112:113]
	v_pk_fma_f32 v[148:149], v[70:71], v[114:115], v[148:149]
	v_add_f32_e32 v150, v148, v149
	v_pk_mul_f32 v[152:153], v[120:121], v[126:127] op_sel_hi:[1,0]
	v_pk_mul_f32 v[154:155], v[122:123], v[126:127] op_sel_hi:[1,0]
	v_add_f32_dpp v150, v150, v150 quad_perm:[1,0,3,2] row_mask:0xf bank_mask:0xf bound_ctrl:1
	v_pk_fma_f32 v[152:153], v[68:69], v[108:109], v[152:153]
	v_pk_fma_f32 v[154:155], v[70:71], v[110:111], v[154:155]
	v_add_f32_dpp v150, v150, v150 quad_perm:[2,3,0,1] row_mask:0xf bank_mask:0xf bound_ctrl:1
	v_pk_mul_f32 v[156:157], v[68:69], v[136:137]
	v_pk_fma_f32 v[156:157], v[70:71], v[138:139], v[156:157]
	v_add_f32_dpp v150, v150, v150 row_half_mirror row_mask:0xf bank_mask:0xf bound_ctrl:1
	v_add_f32_e32 v159, v156, v157
	ds_read_b128 v[96:99], v202 offset:43264
	v_add_f32_dpp v150, v150, v150 row_mirror row_mask:0xf bank_mask:0xf bound_ctrl:1
	v_pk_fma_f32 v[72:73], v[116:117], v[150:151], v[152:153] op_sel_hi:[1,0,1]
	v_pk_fma_f32 v[74:75], v[118:119], v[150:151], v[154:155] op_sel_hi:[1,0,1]
	ds_read_b128 v[104:107], v202 offset:43776
	ds_read_b128 v[128:131], v206 offset:43008
	ds_read_b128 v[92:95], v202 offset:43008
	ds_read_b128 v[100:103], v202 offset:43520
	ds_read_b128 v[132:135], v202 offset:44032
	s_waitcnt lgkmcnt(6)
	v_pk_mul_f32 v[148:149], v[72:73], v[80:81]
	v_pk_fma_f32 v[148:149], v[74:75], v[82:83], v[148:149]
	v_add_f32_e32 v150, v148, v149
	v_pk_mul_f32 v[152:153], v[88:89], v[126:127] op_sel:[0,1] op_sel_hi:[1,1]
	v_pk_mul_f32 v[154:155], v[90:91], v[126:127] op_sel:[0,1] op_sel_hi:[1,1]
	v_add_f32_dpp v150, v150, v150 quad_perm:[1,0,3,2] row_mask:0xf bank_mask:0xf bound_ctrl:1
	v_pk_fma_f32 v[152:153], v[72:73], v[76:77], v[152:153]
	v_pk_fma_f32 v[154:155], v[74:75], v[78:79], v[154:155]
	v_add_f32_dpp v150, v150, v150 quad_perm:[2,3,0,1] row_mask:0xf bank_mask:0xf bound_ctrl:1
	v_pk_mul_f32 v[156:157], v[72:73], v[140:141]
	v_pk_fma_f32 v[156:157], v[74:75], v[142:143], v[156:157]
	v_add_f32_dpp v150, v150, v150 row_half_mirror row_mask:0xf bank_mask:0xf bound_ctrl:1
	v_add_f32_e32 v160, v156, v157
	ds_read_b128 v[112:115], v202 offset:44800
	v_add_f32_dpp v150, v150, v150 row_mirror row_mask:0xf bank_mask:0xf bound_ctrl:1
	v_pk_fma_f32 v[68:69], v[84:85], v[150:151], v[152:153] op_sel_hi:[1,0,1]
	v_pk_fma_f32 v[70:71], v[86:87], v[150:151], v[154:155] op_sel_hi:[1,0,1]
	ds_read_b128 v[120:123], v202 offset:45312
	ds_read_b128 v[108:111], v202 offset:44544
	ds_read_b128 v[116:119], v202 offset:45056
	ds_read_b128 v[136:139], v202 offset:45568
	s_waitcnt lgkmcnt(5)
; __device__ __forceinline__ void rwkv_scan(Frame& F, int wg, unsigned* shw, unsigned wait_target, int wait_blk) {
;     ...
;             for (int s4 = 0; s4 < RW_TB; s4 += 4) {
;                 float pz[4], u[4];
; #pragma unroll
;                 for (int q = 0; q < 4; ++q) {
;                     RW_LD(R[(q + 3) & 3], s4 + q + 3);
;                     const RwOps& cur = R[q];
;                     const f32x2 slo = {st.x, st.y}, shi = {st.z, st.w};
;                     f32x2 ma = slo * (f32x2){cur.a.x, cur.a.y}; ma = __builtin_elementwise_fma(shi, (f32x2){cur.a.z, cur.a.w}, ma);
;                     f32x2 mz = slo * (f32x2){cur.wr.x, cur.wr.y}; mz = __builtin_elementwise_fma(shi, (f32x2){cur.wr.z, cur.wr.w}, mz);
;                     float psa = ma.x + ma.y; pz[q] = mz.x + mz.y;
;                     const f32x2 vb = {cur.vs.x, cur.vs.x};
;                     f32x2 tlo = (f32x2){cur.k.x, cur.k.y} * vb, thi = (f32x2){cur.k.z, cur.k.w} * vb;
;                     tlo = __builtin_elementwise_fma(slo, (f32x2){cur.w.x, cur.w.y}, tlo); thi = __builtin_elementwise_fma(shi, (f32x2){cur.w.z, cur.w.w}, thi);
;                     psa = red16(psa);
;                     const f32x2 pb = {psa, psa};
;                     tlo = __builtin_elementwise_fma((f32x2){cur.b.x, cur.b.y}, pb, tlo); thi = __builtin_elementwise_fma((f32x2){cur.b.z, cur.b.w}, pb, thi);
;                     st = (f32x4){tlo.x, tlo.y, thi.x, thi.y};
;                     u[q] = psa * cur.vs.z + cur.vs.y;
;                 }
;                 const float qa = (odd1 ? pz[1] : pz[0]) + dppf<0xB1>(odd1 ? pz[0] : pz[1]);
;                 const float qb = (odd1 ? pz[3] : pz[2]) + dppf<0xB1>(odd1 ? pz[2] : pz[3]);
;                 float r = (odd2 ? qb : qa) + dppf<0x4E>(odd2 ? qa : qb);
;                 r += dppf<0x124>(r); r += dppf<0x128>(r);
;                 const float us = odd2 ? (odd1 ? u[3] : u[2]) : (odd1 ? u[1] : u[0]);
;                 if (j < 4) { const int t = blk * RW_TB + s4 + j; ((float*)(Ub + (size_t)t * (PWP * 2) + URR * 2))[h * 64 + row] = r + us; }
	v_pk_mul_f32 v[148:149], v[68:69], v[96:97]
	v_pk_fma_f32 v[148:149], v[70:71], v[98:99], v[148:149]
	v_add_f32_e32 v150, v148, v149
	v_pk_mul_f32 v[152:153], v[104:105], v[128:129] op_sel_hi:[1,0]
	v_pk_mul_f32 v[154:155], v[106:107], v[128:129] op_sel_hi:[1,0]
	v_add_f32_dpp v150, v150, v150 quad_perm:[1,0,3,2] row_mask:0xf bank_mask:0xf bound_ctrl:1
	v_pk_fma_f32 v[152:153], v[68:69], v[92:93], v[152:153]
	v_pk_fma_f32 v[154:155], v[70:71], v[94:95], v[154:155]
	v_add_f32_dpp v150, v150, v150 quad_perm:[2,3,0,1] row_mask:0xf bank_mask:0xf bound_ctrl:1
	v_pk_mul_f32 v[156:157], v[68:69], v[144:145]
	v_pk_fma_f32 v[156:157], v[70:71], v[146:147], v[156:157]
	v_add_f32_dpp v150, v150, v150 row_half_mirror row_mask:0xf bank_mask:0xf bound_ctrl:1
	v_add_f32_e32 v161, v156, v157
	v_add_f32_dpp v162, v158, v158 row_ror:8 row_mask:0xf bank_mask:0xf
	v_add_f32_dpp v150, v150, v150 row_mirror row_mask:0xf bank_mask:0xf bound_ctrl:1
	v_pk_fma_f32 v[72:73], v[100:101], v[150:151], v[152:153] op_sel_hi:[1,0,1]
	v_pk_fma_f32 v[74:75], v[102:103], v[150:151], v[154:155] op_sel_hi:[1,0,1]
	v_add_f32_dpp v163, v159, v159 row_ror:8 row_mask:0xf bank_mask:0xf
	v_add_f32_dpp v162, v160, v160 row_ror:8 row_mask:0xf bank_mask:0xc
	v_add_f32_dpp v163, v161, v161 row_ror:8 row_mask:0xf bank_mask:0xc
	ds_read_b128 v[80:83], v202 offset:46336
	ds_read_b128 v[88:91], v202 offset:46848
	v_add_f32_dpp v164, v162, v162 row_half_mirror row_mask:0xf bank_mask:0xf
	v_add_f32_dpp v164, v163, v163 row_half_mirror row_mask:0xf bank_mask:0xa
	ds_read_b128 v[76:79], v202 offset:46080
	ds_read_b128 v[84:87], v202 offset:46592
	v_add_f32_dpp v164, v164, v164 quad_perm:[1,0,3,2] row_mask:0xf bank_mask:0xf bound_ctrl:1
	ds_read_b128 v[140:143], v202 offset:47104
	s_nop 0
	v_add_f32_dpp v164, v164, v164 quad_perm:[2,3,0,1] row_mask:0xf bank_mask:0xf bound_ctrl:1
	global_store_dword v165, v164, s[34:35]
	v_add_u32_e32 v165, 0xb000, v165
	s_waitcnt lgkmcnt(5)
	v_pk_mul_f32 v[148:149], v[72:73], v[112:113]
	v_pk_fma_f32 v[148:149], v[74:75], v[114:115], v[148:149]
	v_add_f32_e32 v150, v148, v149
	v_pk_mul_f32 v[152:153], v[120:121], v[128:129] op_sel:[0,1] op_sel_hi:[1,1]
	v_pk_mul_f32 v[154:155], v[122:123], v[128:129] op_sel:[0,1] op_sel_hi:[1,1]
	v_add_f32_dpp v150, v150, v150 quad_perm:[1,0,3,2] row_mask:0xf bank_mask:0xf bound_ctrl:1
	v_pk_fma_f32 v[152:153], v[72:73], v[108:109], v[152:153]
	v_pk_fma_f32 v[154:155], v[74:75], v[110:111], v[154:155]
	v_add_f32_dpp v150, v150, v150 quad_perm:[2,3,0,1] row_mask:0xf bank_mask:0xf bound_ctrl:1
	v_pk_mul_f32 v[156:157], v[72:73], v[132:133]
	v_pk_fma_f32 v[156:157], v[74:75], v[134:135], v[156:157]
	v_add_f32_dpp v150, v150, v150 row_half_mirror row_mask:0xf bank_mask:0xf bound_ctrl:1
	v_add_f32_e32 v158, v156, v157
	ds_read_b128 v[96:99], v202 offset:47872
	v_add_f32_dpp v150, v150, v150 row_mirror row_mask:0xf bank_mask:0xf bound_ctrl:1
	v_pk_fma_f32 v[68:69], v[116:117], v[150:151], v[152:153] op_sel_hi:[1,0,1]
	v_pk_fma_f32 v[70:71], v[118:119], v[150:151], v[154:155] op_sel_hi:[1,0,1]
	ds_read_b128 v[104:107], v202 offset:48384
	ds_read_b128 v[92:95], v202 offset:47616
	ds_read_b128 v[100:103], v202 offset:48128
	ds_read_b128 v[144:147], v202 offset:48640
	s_waitcnt lgkmcnt(5)
	v_pk_mul_f32 v[148:149], v[68:69], v[80:81]
	v_pk_fma_f32 v[148:149], v[70:71], v[82:83], v[148:149]
	v_add_f32_e32 v150, v148, v149
	v_pk_mul_f32 v[152:153], v[88:89], v[130:131] op_sel_hi:[1,0]
	v_pk_mul_f32 v[154:155], v[90:91], v[130:131] op_sel_hi:[1,0]
	v_add_f32_dpp v150, v150, v150 quad_perm:[1,0,3,2] row_mask:0xf bank_mask:0xf bound_ctrl:1
	v_pk_fma_f32 v[152:153], v[68:69], v[76:77], v[152:153]
	v_pk_fma_f32 v[154:155], v[70:71], v[78:79], v[154:155]
	v_add_f32_dpp v150, v150, v150 quad_perm:[2,3,0,1] row_mask:0xf bank_mask:0xf bound_ctrl:1
	v_pk_mul_f32 v[156:157], v[68:69], v[136:137]
	v_pk_fma_f32 v[156:157], v[70:71], v[138:139], v[156:157]
	v_add_f32_dpp v150, v150, v150 row_half_mirror row_mask:0xf bank_mask:0xf bound_ctrl:1
	v_add_f32_e32 v159, v156, v157
	s_nop 0
	v_add_f32_dpp v150, v150, v150 row_mirror row_mask:0xf bank_mask:0xf bound_ctrl:1
	v_pk_fma_f32 v[72:73], v[84:85], v[150:151], v[152:153] op_sel_hi:[1,0,1]
	v_pk_fma_f32 v[74:75], v[86:87], v[150:151], v[154:155] op_sel_hi:[1,0,1]
	s_waitcnt lgkmcnt(0)
	v_pk_mul_f32 v[148:149], v[72:73], v[96:97]
	v_pk_fma_f32 v[148:149], v[74:75], v[98:99], v[148:149]
	v_add_f32_e32 v150, v148, v149
	v_pk_mul_f32 v[152:153], v[104:105], v[130:131] op_sel:[0,1] op_sel_hi:[1,1]
	v_pk_mul_f32 v[154:155], v[106:107], v[130:131] op_sel:[0,1] op_sel_hi:[1,1]
	v_add_f32_dpp v150, v150, v150 quad_perm:[1,0,3,2] row_mask:0xf bank_mask:0xf bound_ctrl:1
	v_pk_fma_f32 v[152:153], v[72:73], v[92:93], v[152:153]
	v_pk_fma_f32 v[154:155], v[74:75], v[94:95], v[154:155]
	v_add_f32_dpp v150, v150, v150 quad_perm:[2,3,0,1] row_mask:0xf bank_mask:0xf bound_ctrl:1
	v_pk_mul_f32 v[156:157], v[72:73], v[140:141]
	v_pk_fma_f32 v[156:157], v[74:75], v[142:143], v[156:157]
	v_add_f32_dpp v150, v150, v150 row_half_mirror row_mask:0xf bank_mask:0xf bound_ctrl:1
	v_add_f32_e32 v160, v156, v157
	s_nop 0
	v_add_f32_dpp v150, v150, v150 row_mirror row_mask:0xf bank_mask:0xf bound_ctrl:1
	v_pk_fma_f32 v[68:69], v[100:101], v[150:151], v[152:153] op_sel_hi:[1,0,1]
	v_pk_fma_f32 v[70:71], v[102:103], v[150:151], v[154:155] op_sel_hi:[1,0,1]
	v_pk_mul_f32 v[156:157], v[68:69], v[144:145]
	v_pk_fma_f32 v[156:157], v[70:71], v[146:147], v[156:157]
	v_add_f32_e32 v161, v156, v157
	v_add_f32_dpp v162, v158, v158 row_ror:8 row_mask:0xf bank_mask:0xf
	v_add_f32_dpp v163, v159, v159 row_ror:8 row_mask:0xf bank_mask:0xf
	v_add_f32_dpp v162, v160, v160 row_ror:8 row_mask:0xf bank_mask:0xc
	v_add_f32_dpp v163, v161, v161 row_ror:8 row_mask:0xf bank_mask:0xc
	s_nop 0
	s_nop 0
	v_add_f32_dpp v164, v162, v162 row_half_mirror row_mask:0xf bank_mask:0xf
	v_add_f32_dpp v164, v163, v163 row_half_mirror row_mask:0xf bank_mask:0xa
	s_nop 0
	s_nop 0
	v_add_f32_dpp v164, v164, v164 quad_perm:[1,0,3,2] row_mask:0xf bank_mask:0xf bound_ctrl:1
	s_nop 0
	s_nop 0
	v_add_f32_dpp v164, v164, v164 quad_perm:[2,3,0,1] row_mask:0xf bank_mask:0xf bound_ctrl:1
	global_store_dword v165, v164, s[34:35]
	v_add_u32_e32 v165, 0xb000, v165
	s_branch .LBB0_847
; #define LAS __attribute__((address_space(3)))
; __device__ __forceinline__ void rwkv_scan(Frame& F, int wg, unsigned* shw, unsigned wait_target, int wait_blk) {
;     ...
;     auto lstore = [&](const LdRegs& L, int b) {
;         LAS float* rec = buf + (b * RW_TB + lstep) * RW_REC;
;         const u32x4 av = L.a, bv = L.b, kv = L.k, rv = L.r;
;         f32x4 a_0 = {bflo(av.x), bfhi(av.x), bflo(av.y), bfhi(av.y)}, a_1 = {bflo(av.z), bfhi(av.z), bflo(av.w), bfhi(av.w)};
;         f32x4 b_0 = {bflo(bv.x), bfhi(bv.x), bflo(bv.y), bfhi(bv.y)}, b_1 = {bflo(bv.z), bfhi(bv.z), bflo(bv.w), bfhi(bv.w)};
;         f32x4 k_0 = {bflo(kv.x), bfhi(kv.x), bflo(kv.y), bfhi(kv.y)}, k_1 = {bflo(kv.z), bfhi(kv.z), bflo(kv.w), bfhi(kv.w)};
;         f32x4 r_0 = {bflo(rv.x), bfhi(rv.x), bflo(rv.y), bfhi(rv.y)}, r_1 = {bflo(rv.z), bfhi(rv.z), bflo(rv.w), bfhi(rv.w)};
;         *(LAS f32x4*)(rec + 8 * part) = L.w0; *(LAS f32x4*)(rec + 8 * part + 4) = L.w1;
;         *(LAS f32x4*)(rec + 64 + 8 * part) = a_0; *(LAS f32x4*)(rec + 64 + 8 * part + 4) = a_1;
;         *(LAS f32x4*)(rec + 128 + 8 * part) = b_0; *(LAS f32x4*)(rec + 128 + 8 * part + 4) = b_1;
;         *(LAS f32x4*)(rec + 192 + 8 * part) = k_0; *(LAS f32x4*)(rec + 192 + 8 * part + 4) = k_1;
;         *(LAS f32x4*)(rec + 256 + 8 * part) = L.w0 * r_0; *(LAS f32x4*)(rec + 256 + 8 * part + 4) = L.w1 * r_1;
;         if (part < 2) { const u32x4 vv = L.v;
;             const float v8[8] = {bflo(vv.x), bfhi(vv.x), bflo(vv.y), bfhi(vv.y), bflo(vv.z), bfhi(vv.z), bflo(vv.w), bfhi(vv.w)};
; #pragma unroll
;             for (int e = 0; e < 8; ++e) *(LAS f32x4*)(rec + 320 + (8 * part + e) * 4) = (f32x4){v8[e], v8[e] * L.kr, L.br, 0.f}; }
;     ...
;         if (loader) { lstore(L0, 1); if (blk + 3 < NBLK) gload(L0, blk + 3); }
.LBB0_909:
	s_and_b64 vcc, exec, s[50:51]
	s_cbranch_vccz .LBB0_846
	s_cmpk_gt_u32 s59, 0x1fd
	s_cbranch_scc1 .LBB0_847
	s_waitcnt vmcnt(3)
	v_lshlrev_b32_e32 v72, 16, v40
	v_and_b32_e32 v73, 0xffff0000, v40
	v_lshlrev_b32_e32 v74, 16, v41
	v_and_b32_e32 v75, 0xffff0000, v41
	s_waitcnt vmcnt(0)
	v_lshlrev_b32_e32 v4, 16, v52
	v_and_b32_e32 v5, 0xffff0000, v52
	v_lshlrev_b32_e32 v60, 16, v53
	v_and_b32_e32 v61, 0xffff0000, v53
	v_add_u32_e32 v7, v199, v195
	v_lshlrev_b32_e32 v76, 16, v42
	v_and_b32_e32 v77, 0xffff0000, v42
	v_lshlrev_b32_e32 v78, 16, v43
	v_and_b32_e32 v79, 0xffff0000, v43
	v_lshlrev_b32_e32 v80, 16, v44
	v_and_b32_e32 v81, 0xffff0000, v44
	v_lshlrev_b32_e32 v82, 16, v45
	v_and_b32_e32 v83, 0xffff0000, v45
	v_lshlrev_b32_e32 v84, 16, v46
	v_and_b32_e32 v85, 0xffff0000, v46
	v_lshlrev_b32_e32 v86, 16, v47
	v_and_b32_e32 v87, 0xffff0000, v47
	v_lshlrev_b32_e32 v88, 16, v48
	v_and_b32_e32 v89, 0xffff0000, v48
	v_lshlrev_b32_e32 v90, 16, v49
	v_and_b32_e32 v91, 0xffff0000, v49
	v_lshlrev_b32_e32 v92, 16, v50
	v_and_b32_e32 v93, 0xffff0000, v50
	v_lshlrev_b32_e32 v94, 16, v51
	v_and_b32_e32 v95, 0xffff0000, v51
	v_lshlrev_b32_e32 v64, 16, v54
	v_and_b32_e32 v65, 0xffff0000, v54
	v_lshlrev_b32_e32 v96, 16, v55
	v_and_b32_e32 v97, 0xffff0000, v55
	ds_write_b128 v7, v[36:39]
	ds_write_b128 v7, v[32:35] offset:16
	ds_write_b128 v7, v[72:75] offset:256
	ds_write_b128 v7, v[76:79] offset:272
	ds_write_b128 v7, v[80:83] offset:512
	ds_write_b128 v7, v[84:87] offset:528
	ds_write_b128 v7, v[88:91] offset:768
	ds_write_b128 v7, v[92:95] offset:784
	v_mov_b64_e32 v[74:75], v[60:61]
	v_mov_b64_e32 v[72:73], v[4:5]
	ds_write_b128 v7, v[72:75] offset:1024
	v_mov_b64_e32 v[74:75], v[96:97]
	v_mov_b64_e32 v[72:73], v[64:65]
	ds_write_b128 v7, v[72:75] offset:1040
	s_and_saveexec_b64 s[50:51], s[10:11]
	s_cbranch_execz .LBB0_913
	v_and_b32_e32 v100, 3, v201
	v_mul_u32_u24_e32 v100, 0x5fc, v100
	v_add_u32_e32 v101, v199, v200
	v_sub_u32_e32 v101, v101, v100
	v_lshlrev_b32_e32 v104, 16, v56
	v_and_b32_e32 v105, 0xffff0000, v56
	v_lshlrev_b32_e32 v106, 16, v57
	v_and_b32_e32 v107, 0xffff0000, v57
	v_lshlrev_b32_e32 v108, 16, v58
	v_and_b32_e32 v109, 0xffff0000, v58
	v_lshlrev_b32_e32 v110, 16, v59
	v_and_b32_e32 v111, 0xffff0000, v59
	ds_write_b32 v101, v104 offset:1280
	ds_write_b32 v101, v105 offset:1296
	ds_write_b32 v101, v106 offset:1312
	ds_write_b32 v101, v107 offset:1328
	ds_write_b32 v101, v108 offset:1344
	ds_write_b32 v101, v109 offset:1360
	ds_write_b32 v101, v110 offset:1376
	ds_write_b32 v101, v111 offset:1392
